# GEMM epilogue stores write-through (sc1)
# baseline (speedup 1.0000x reference)
; __device__ __forceinline__ unsigned cvt_pk_bf16(float lo, float hi) { unsigned r; asm volatile("v_cvt_pk_bf16_f32 %0, %1, %2" : "=v"(r) : "v"(lo), "v"(hi)); return r; }
; __device__ __forceinline__ float silu_f(float v) { return v * __builtin_amdgcn_rcpf(1.0f + __expf(-v)); }
;     __device__ __forceinline__ void operator()(const f32x4 (&acc)[2][2][4][2], const Unit& u, int wr, int wc, int fr, int fq) const {
;     ...
;                     if (wc == 0) { const f32x4 v0 = acc[ai][0][m][0] * rs, v1 = acc[ai][0][m][1] * rs; u32x4 w; w.x = cvt_pk_bf16(v0[0], v0[1]); w.y = cvt_pk_bf16(v0[2], v0[3]); w.z = cvt_pk_bf16(v1[0], v1[1]); w.w = cvt_pk_bf16(v1[2], v1[3]); *(u32x4*)(DEC + (size_t)r * 32 + 8 * fq) = w; }
;     ...
;                     bf16_t* rowp = Z + (size_t)r * ZW + pn * BM + wc * 32 + 8 * fq;
; #pragma unroll
;                     for (int bj = 0; bj < 2; ++bj) { f32x4 v0 = acc[ai][bj][m][0] * rs, v1 = acc[ai][bj][m][1] * rs;
;                         if (pn >= 4 && pn < 6) {
; #pragma unroll
;                             for (int j = 0; j < 4; ++j) { v0[j] = silu_f(v0[j]); v1[j] = silu_f(v1[j]); } }
;                         u32x4 w; w.x = cvt_pk_bf16(v0[0], v0[1]); w.y = cvt_pk_bf16(v0[2], v0[3]); w.z = cvt_pk_bf16(v1[0], v1[1]); w.w = cvt_pk_bf16(v1[2], v1[3]);
;                         *(u32x4*)(rowp + bj * HALF) = w; }
.LBB0_134:
	v_mov_b64_e32 v[130:131], s[60:61]
	v_mad_i64_i32 v[130:131], s[14:15], v180, s1, v[130:131]
	v_lshl_add_u64 v[130:131], s[96:97], 1, v[130:131]
	s_lshl_b32 s76, s7, 1
	v_mov_b32_e32 v142, v188
	v_mov_b32_e32 v143, v188
	v_lshl_add_u64 v[130:131], v[130:131], 0, s[76:77]
	v_lshlrev_b32_e32 v152, 1, v170
	v_cvt_pk_bf16_f32 v146, v134, v135
	v_cvt_pk_bf16_f32 v147, v132, v133
	v_mov_b32_e32 v132, v188
	v_mov_b32_e32 v133, v188
	v_lshl_add_u64 v[130:131], v[130:131], 0, v[152:153]
	v_pk_mul_f32 v[126:127], v[126:127], v[132:133]
	v_pk_mul_f32 v[124:125], v[124:125], v[142:143]
	v_pk_mul_f32 v[122:123], v[122:123], v[132:133]
	s_and_b64 vcc, exec, s[42:43]
	v_pk_mul_f32 v[120:121], v[120:121], v[142:143]
	v_cvt_pk_bf16_f32 v148, v138, v139
	v_cvt_pk_bf16_f32 v149, v140, v141
	global_store_dwordx4 v[130:131], v[146:149], off sc1
	s_cbranch_vccnz .LBB0_136
	v_mul_f32_e32 v133, 0xbfb8aa3b, v120
	v_exp_f32_e32 v133, v133
	v_mul_f32_e32 v132, 0xbfb8aa3b, v124
	v_exp_f32_e32 v132, v132
	v_mul_f32_e32 v139, 0xbfb8aa3b, v122
	v_add_f32_e32 v133, 1.0, v133
	v_rcp_f32_e32 v134, v133
	v_mul_f32_e32 v133, 0xbfb8aa3b, v125
	v_exp_f32_e32 v133, v133
	v_add_f32_e32 v132, 1.0, v132
	v_exp_f32_e32 v139, v139
	v_rcp_f32_e32 v132, v132
	v_add_f32_e32 v133, 1.0, v133
	v_rcp_f32_e32 v133, v133
	v_add_f32_e32 v139, 1.0, v139
	v_mul_f32_e32 v135, 0xbfb8aa3b, v121
	v_mul_f32_e32 v138, 0xbfb8aa3b, v126
	v_rcp_f32_e32 v140, v139
	v_mul_f32_e32 v139, 0xbfb8aa3b, v127
	v_pk_mul_f32 v[124:125], v[124:125], v[132:133]
	v_mul_f32_e32 v132, 0xbfb8aa3b, v123
	v_exp_f32_e32 v135, v135
	v_exp_f32_e32 v138, v138
	v_exp_f32_e32 v139, v139
	v_exp_f32_e32 v132, v132
	v_add_f32_e32 v135, 1.0, v135
	v_add_f32_e32 v138, 1.0, v138
	v_add_f32_e32 v139, 1.0, v139
	v_add_f32_e32 v132, 1.0, v132
	v_rcp_f32_e32 v135, v135
	v_rcp_f32_e32 v138, v138
	v_rcp_f32_e32 v139, v139
	v_rcp_f32_e32 v141, v132
	v_pk_mul_f32 v[120:121], v[120:121], v[134:135]
	v_pk_mul_f32 v[126:127], v[126:127], v[138:139]
	v_pk_mul_f32 v[122:123], v[122:123], v[140:141]
.LBB0_136:
	s_mov_b64 s[44:45], 0
	v_cvt_pk_bf16_f32 v124, v124, v125
	v_cvt_pk_bf16_f32 v125, v126, v127
	v_cvt_pk_bf16_f32 v126, v120, v121
	v_cvt_pk_bf16_f32 v127, v122, v123
	global_store_dwordx4 v[130:131], v[124:127], off offset:256 sc1
.LBB0_137:
	v_cndmask_b32_e64 v120, 0, 1, s[70:71]
	s_and_b64 vcc, exec, s[44:45]
	v_cmp_ne_u32_e64 s[44:45], 1, v120
	s_cbranch_vccz .LBB0_140
	s_and_b64 vcc, exec, s[44:45]
	s_cbranch_vccnz .LBB0_140
	s_waitcnt lgkmcnt(0)
	v_pk_mul_f32 v[116:117], v[116:117], v[188:189] op_sel_hi:[1,0]
	v_ashrrev_i32_e32 v181, 31, v180
	v_pk_mul_f32 v[120:121], v[114:115], v[188:189] op_sel_hi:[1,0]
	v_pk_mul_f32 v[114:115], v[112:113], v[188:189] op_sel_hi:[1,0]
	v_cvt_pk_bf16_f32 v112, v116, v117
	v_lshlrev_b64 v[116:117], 6, v[180:181]
	v_lshl_add_u64 v[116:117], v[172:173], 0, v[116:117]
	v_pk_mul_f32 v[118:119], v[118:119], v[188:189] op_sel_hi:[1,0]
	s_nop 0
	v_cvt_pk_bf16_f32 v113, v118, v119
	v_cvt_pk_bf16_f32 v114, v114, v115
	v_cvt_pk_bf16_f32 v115, v120, v121
	global_store_dwordx4 v[116:117], v[112:115], off sc1

; __device__ __forceinline__ unsigned cvt_pk_bf16(float lo, float hi) { unsigned r; asm volatile("v_cvt_pk_bf16_f32 %0, %1, %2" : "=v"(r) : "v"(lo), "v"(hi)); return r; }
; __device__ __forceinline__ float silu_f(float v) { return v * __builtin_amdgcn_rcpf(1.0f + __expf(-v)); }
;     __device__ __forceinline__ void operator()(const f32x4 (&acc)[2][2][4][2], const Unit& u, int wr, int wc, int fr, int fq) const {
;     ...
;                     bf16_t* rowp = Z + (size_t)r * ZW + pn * BM + wc * 32 + 8 * fq;
; #pragma unroll
;                     for (int bj = 0; bj < 2; ++bj) { f32x4 v0 = acc[ai][bj][m][0] * rs, v1 = acc[ai][bj][m][1] * rs;
;                         if (pn >= 4 && pn < 6) {
; #pragma unroll
;                             for (int j = 0; j < 4; ++j) { v0[j] = silu_f(v0[j]); v1[j] = silu_f(v1[j]); } }
;                         u32x4 w; w.x = cvt_pk_bf16(v0[0], v0[1]); w.y = cvt_pk_bf16(v0[2], v0[3]); w.z = cvt_pk_bf16(v1[0], v1[1]); w.w = cvt_pk_bf16(v1[2], v1[3]);
;                         *(u32x4*)(rowp + bj * HALF) = w; }
.LBB0_143:
	v_mov_b64_e32 v[112:113], s[60:61]
	v_mad_i64_i32 v[112:113], s[14:15], v186, s1, v[112:113]
	v_lshl_add_u64 v[112:113], s[96:97], 1, v[112:113]
	s_lshl_b32 s76, s7, 1
	v_mov_b32_e32 v122, v189
	v_mov_b32_e32 v123, v189
	v_lshl_add_u64 v[112:113], v[112:113], 0, s[76:77]
	v_lshlrev_b32_e32 v152, 1, v170
	v_cvt_pk_bf16_f32 v116, v116, v117
	v_cvt_pk_bf16_f32 v117, v114, v115
	v_mov_b32_e32 v114, v189
	v_mov_b32_e32 v115, v189
	v_lshl_add_u64 v[112:113], v[112:113], 0, v[152:153]
	v_pk_mul_f32 v[110:111], v[110:111], v[114:115]
	v_pk_mul_f32 v[108:109], v[108:109], v[122:123]
	v_pk_mul_f32 v[106:107], v[106:107], v[114:115]
	s_and_b64 vcc, exec, s[42:43]
	v_pk_mul_f32 v[104:105], v[104:105], v[122:123]
	v_cvt_pk_bf16_f32 v118, v118, v119
	v_cvt_pk_bf16_f32 v119, v120, v121
	global_store_dwordx4 v[112:113], v[116:119], off sc1
	s_cbranch_vccnz .LBB0_145
	v_mul_f32_e32 v115, 0xbfb8aa3b, v104
	v_exp_f32_e32 v115, v115
	v_mul_f32_e32 v114, 0xbfb8aa3b, v108
	v_exp_f32_e32 v114, v114
	v_mul_f32_e32 v119, 0xbfb8aa3b, v106
	v_add_f32_e32 v115, 1.0, v115
	v_rcp_f32_e32 v116, v115
	v_mul_f32_e32 v115, 0xbfb8aa3b, v109
	v_exp_f32_e32 v115, v115
	v_add_f32_e32 v114, 1.0, v114
	v_exp_f32_e32 v119, v119
	v_rcp_f32_e32 v114, v114
	v_add_f32_e32 v115, 1.0, v115
	v_rcp_f32_e32 v115, v115
	v_add_f32_e32 v119, 1.0, v119
	v_mul_f32_e32 v117, 0xbfb8aa3b, v105
	v_mul_f32_e32 v118, 0xbfb8aa3b, v110
	v_rcp_f32_e32 v120, v119
	v_mul_f32_e32 v119, 0xbfb8aa3b, v111
	v_pk_mul_f32 v[108:109], v[108:109], v[114:115]
	v_mul_f32_e32 v114, 0xbfb8aa3b, v107
	v_exp_f32_e32 v117, v117
	v_exp_f32_e32 v118, v118
	v_exp_f32_e32 v119, v119
	v_exp_f32_e32 v114, v114
	v_add_f32_e32 v117, 1.0, v117
	v_add_f32_e32 v118, 1.0, v118
	v_add_f32_e32 v119, 1.0, v119
	v_add_f32_e32 v114, 1.0, v114
	v_rcp_f32_e32 v117, v117
	v_rcp_f32_e32 v118, v118
	v_rcp_f32_e32 v119, v119
	v_rcp_f32_e32 v121, v114
	v_pk_mul_f32 v[104:105], v[104:105], v[116:117]
	v_pk_mul_f32 v[110:111], v[110:111], v[118:119]
	v_pk_mul_f32 v[106:107], v[106:107], v[120:121]
.LBB0_145:
	s_mov_b64 s[98:99], 0
	v_cvt_pk_bf16_f32 v108, v108, v109
	v_cvt_pk_bf16_f32 v109, v110, v111
	v_cvt_pk_bf16_f32 v110, v104, v105
	v_cvt_pk_bf16_f32 v111, v106, v107
	global_store_dwordx4 v[112:113], v[108:111], off offset:256 sc1

; __device__ __forceinline__ unsigned cvt_pk_bf16(float lo, float hi) { unsigned r; asm volatile("v_cvt_pk_bf16_f32 %0, %1, %2" : "=v"(r) : "v"(lo), "v"(hi)); return r; }
; __device__ __forceinline__ float silu_f(float v) { return v * __builtin_amdgcn_rcpf(1.0f + __expf(-v)); }
;     __device__ __forceinline__ void operator()(const f32x4 (&acc)[2][2][4][2], const Unit& u, int wr, int wc, int fr, int fq) const {
;     ...
;                     bf16_t* rowp = Z + (size_t)r * ZW + pn * BM + wc * 32 + 8 * fq;
; #pragma unroll
;                     for (int bj = 0; bj < 2; ++bj) { f32x4 v0 = acc[ai][bj][m][0] * rs, v1 = acc[ai][bj][m][1] * rs;
;                         if (pn >= 4 && pn < 6) {
; #pragma unroll
;                             for (int j = 0; j < 4; ++j) { v0[j] = silu_f(v0[j]); v1[j] = silu_f(v1[j]); } }
;                         u32x4 w; w.x = cvt_pk_bf16(v0[0], v0[1]); w.y = cvt_pk_bf16(v0[2], v0[3]); w.z = cvt_pk_bf16(v1[0], v1[1]); w.w = cvt_pk_bf16(v1[2], v1[3]);
;                         *(u32x4*)(rowp + bj * HALF) = w; }
.LBB0_151:
	v_mov_b64_e32 v[96:97], s[60:61]
	v_mad_i64_i32 v[96:97], s[14:15], v184, s1, v[96:97]
	v_lshl_add_u64 v[96:97], s[96:97], 1, v[96:97]
	s_lshl_b32 s76, s7, 1
	v_mov_b32_e32 v106, v144
	v_mov_b32_e32 v107, v144
	v_lshl_add_u64 v[96:97], v[96:97], 0, s[76:77]
	v_lshlrev_b32_e32 v152, 1, v170
	v_cvt_pk_bf16_f32 v100, v100, v101
	v_cvt_pk_bf16_f32 v101, v98, v99
	v_mov_b32_e32 v98, v144
	v_mov_b32_e32 v99, v144
	v_lshl_add_u64 v[96:97], v[96:97], 0, v[152:153]
	v_pk_mul_f32 v[94:95], v[94:95], v[98:99]
	v_pk_mul_f32 v[92:93], v[92:93], v[106:107]
	v_pk_mul_f32 v[90:91], v[90:91], v[98:99]
	s_and_b64 vcc, exec, s[42:43]
	v_pk_mul_f32 v[88:89], v[88:89], v[106:107]
	v_cvt_pk_bf16_f32 v102, v102, v103
	v_cvt_pk_bf16_f32 v103, v104, v105
	global_store_dwordx4 v[96:97], v[100:103], off sc1
	s_cbranch_vccnz .LBB0_153
	v_mul_f32_e32 v99, 0xbfb8aa3b, v88
	v_exp_f32_e32 v99, v99
	v_mul_f32_e32 v98, 0xbfb8aa3b, v92
	v_exp_f32_e32 v98, v98
	v_mul_f32_e32 v103, 0xbfb8aa3b, v90
	v_add_f32_e32 v99, 1.0, v99
	v_rcp_f32_e32 v100, v99
	v_mul_f32_e32 v99, 0xbfb8aa3b, v93
	v_exp_f32_e32 v99, v99
	v_add_f32_e32 v98, 1.0, v98
	v_exp_f32_e32 v103, v103
	v_rcp_f32_e32 v98, v98
	v_add_f32_e32 v99, 1.0, v99
	v_rcp_f32_e32 v99, v99
	v_add_f32_e32 v103, 1.0, v103
	v_mul_f32_e32 v101, 0xbfb8aa3b, v89
	v_mul_f32_e32 v102, 0xbfb8aa3b, v94
	v_rcp_f32_e32 v104, v103
	v_mul_f32_e32 v103, 0xbfb8aa3b, v95
	v_pk_mul_f32 v[92:93], v[92:93], v[98:99]
	v_mul_f32_e32 v98, 0xbfb8aa3b, v91
	v_exp_f32_e32 v101, v101
	v_exp_f32_e32 v102, v102
	v_exp_f32_e32 v103, v103
	v_exp_f32_e32 v98, v98
	v_add_f32_e32 v101, 1.0, v101
	v_add_f32_e32 v102, 1.0, v102
	v_add_f32_e32 v103, 1.0, v103
	v_add_f32_e32 v98, 1.0, v98
	v_rcp_f32_e32 v101, v101
	v_rcp_f32_e32 v102, v102
	v_rcp_f32_e32 v103, v103
	v_rcp_f32_e32 v105, v98
	v_pk_mul_f32 v[88:89], v[88:89], v[100:101]
	v_pk_mul_f32 v[94:95], v[94:95], v[102:103]
	v_pk_mul_f32 v[90:91], v[90:91], v[104:105]
.LBB0_153:
	s_mov_b64 s[98:99], 0
	v_cvt_pk_bf16_f32 v92, v92, v93
	v_cvt_pk_bf16_f32 v93, v94, v95
	v_cvt_pk_bf16_f32 v94, v88, v89
	v_cvt_pk_bf16_f32 v95, v90, v91
	global_store_dwordx4 v[96:97], v[92:95], off offset:256 sc1

; __device__ __forceinline__ unsigned cvt_pk_bf16(float lo, float hi) { unsigned r; asm volatile("v_cvt_pk_bf16_f32 %0, %1, %2" : "=v"(r) : "v"(lo), "v"(hi)); return r; }
; __device__ __forceinline__ float silu_f(float v) { return v * __builtin_amdgcn_rcpf(1.0f + __expf(-v)); }
;     __device__ __forceinline__ void operator()(const f32x4 (&acc)[2][2][4][2], const Unit& u, int wr, int wc, int fr, int fq) const {
;     ...
;                     bf16_t* rowp = Z + (size_t)r * ZW + pn * BM + wc * 32 + 8 * fq;
; #pragma unroll
;                     for (int bj = 0; bj < 2; ++bj) { f32x4 v0 = acc[ai][bj][m][0] * rs, v1 = acc[ai][bj][m][1] * rs;
;                         if (pn >= 4 && pn < 6) {
; #pragma unroll
;                             for (int j = 0; j < 4; ++j) { v0[j] = silu_f(v0[j]); v1[j] = silu_f(v1[j]); } }
;                         u32x4 w; w.x = cvt_pk_bf16(v0[0], v0[1]); w.y = cvt_pk_bf16(v0[2], v0[3]); w.z = cvt_pk_bf16(v1[0], v1[1]); w.w = cvt_pk_bf16(v1[2], v1[3]);
;                         *(u32x4*)(rowp + bj * HALF) = w; }
.LBB0_159:
	v_mov_b64_e32 v[80:81], s[60:61]
	v_mad_i64_i32 v[80:81], s[14:15], v182, s1, v[80:81]
	v_lshl_add_u64 v[80:81], s[96:97], 1, v[80:81]
	s_lshl_b32 s76, s7, 1
	v_mov_b32_e32 v90, v145
	v_mov_b32_e32 v91, v145
	v_lshl_add_u64 v[80:81], v[80:81], 0, s[76:77]
	v_lshlrev_b32_e32 v152, 1, v170
	v_cvt_pk_bf16_f32 v84, v84, v85
	v_cvt_pk_bf16_f32 v85, v82, v83
	v_mov_b32_e32 v82, v145
	v_mov_b32_e32 v83, v145
	v_lshl_add_u64 v[80:81], v[80:81], 0, v[152:153]
	v_pk_mul_f32 v[78:79], v[78:79], v[82:83]
	v_pk_mul_f32 v[76:77], v[76:77], v[90:91]
	v_pk_mul_f32 v[74:75], v[74:75], v[82:83]
	s_and_b64 vcc, exec, s[42:43]
	v_pk_mul_f32 v[72:73], v[72:73], v[90:91]
	v_cvt_pk_bf16_f32 v86, v86, v87
	v_cvt_pk_bf16_f32 v87, v88, v89
	global_store_dwordx4 v[80:81], v[84:87], off sc1
	s_cbranch_vccnz .LBB0_161
	v_mul_f32_e32 v83, 0xbfb8aa3b, v72
	v_exp_f32_e32 v83, v83
	v_mul_f32_e32 v82, 0xbfb8aa3b, v76
	v_exp_f32_e32 v82, v82
	v_mul_f32_e32 v87, 0xbfb8aa3b, v74
	v_add_f32_e32 v83, 1.0, v83
	v_rcp_f32_e32 v84, v83
	v_mul_f32_e32 v83, 0xbfb8aa3b, v77
	v_exp_f32_e32 v83, v83
	v_add_f32_e32 v82, 1.0, v82
	v_exp_f32_e32 v87, v87
	v_rcp_f32_e32 v82, v82
	v_add_f32_e32 v83, 1.0, v83
	v_rcp_f32_e32 v83, v83
	v_add_f32_e32 v87, 1.0, v87
	v_mul_f32_e32 v85, 0xbfb8aa3b, v73
	v_mul_f32_e32 v86, 0xbfb8aa3b, v78
	v_rcp_f32_e32 v88, v87
	v_mul_f32_e32 v87, 0xbfb8aa3b, v79
	v_pk_mul_f32 v[76:77], v[76:77], v[82:83]
	v_mul_f32_e32 v82, 0xbfb8aa3b, v75
	v_exp_f32_e32 v85, v85
	v_exp_f32_e32 v86, v86
	v_exp_f32_e32 v87, v87
	v_exp_f32_e32 v82, v82
	v_add_f32_e32 v85, 1.0, v85
	v_add_f32_e32 v86, 1.0, v86
	v_add_f32_e32 v87, 1.0, v87
	v_add_f32_e32 v82, 1.0, v82
	v_rcp_f32_e32 v85, v85
	v_rcp_f32_e32 v86, v86
	v_rcp_f32_e32 v87, v87
	v_rcp_f32_e32 v89, v82
	v_pk_mul_f32 v[72:73], v[72:73], v[84:85]
	v_pk_mul_f32 v[78:79], v[78:79], v[86:87]
	v_pk_mul_f32 v[74:75], v[74:75], v[88:89]
.LBB0_161:
	s_mov_b64 s[98:99], 0
	v_cvt_pk_bf16_f32 v76, v76, v77
	v_cvt_pk_bf16_f32 v77, v78, v79
	v_cvt_pk_bf16_f32 v78, v72, v73
	v_cvt_pk_bf16_f32 v79, v74, v75
	global_store_dwordx4 v[80:81], v[76:79], off offset:256 sc1

; __device__ __forceinline__ unsigned cvt_pk_bf16(float lo, float hi) { unsigned r; asm volatile("v_cvt_pk_bf16_f32 %0, %1, %2" : "=v"(r) : "v"(lo), "v"(hi)); return r; }
; __device__ __forceinline__ float silu_f(float v) { return v * __builtin_amdgcn_rcpf(1.0f + __expf(-v)); }
;     __device__ __forceinline__ void operator()(const f32x4 (&acc)[2][2][4][2], const Unit& u, int wr, int wc, int fr, int fq) const {
;     ...
;                     bf16_t* rowp = Z + (size_t)r * ZW + pn * BM + wc * 32 + 8 * fq;
; #pragma unroll
;                     for (int bj = 0; bj < 2; ++bj) { f32x4 v0 = acc[ai][bj][m][0] * rs, v1 = acc[ai][bj][m][1] * rs;
;                         if (pn >= 4 && pn < 6) {
; #pragma unroll
;                             for (int j = 0; j < 4; ++j) { v0[j] = silu_f(v0[j]); v1[j] = silu_f(v1[j]); } }
;                         u32x4 w; w.x = cvt_pk_bf16(v0[0], v0[1]); w.y = cvt_pk_bf16(v0[2], v0[3]); w.z = cvt_pk_bf16(v1[0], v1[1]); w.w = cvt_pk_bf16(v1[2], v1[3]);
;                         *(u32x4*)(rowp + bj * HALF) = w; }
.LBB0_167:
	v_mov_b64_e32 v[66:67], s[60:61]
	v_mad_i64_i32 v[66:67], s[14:15], v64, s1, v[66:67]
	v_lshl_add_u64 v[66:67], s[96:97], 1, v[66:67]
	s_lshl_b32 s76, s7, 1
	v_mov_b32_e32 v76, v136
	v_mov_b32_e32 v77, v136
	v_lshl_add_u64 v[66:67], v[66:67], 0, s[76:77]
	v_lshlrev_b32_e32 v152, 1, v170
	v_cvt_pk_bf16_f32 v70, v70, v71
	v_cvt_pk_bf16_f32 v71, v68, v69
	v_mov_b32_e32 v68, v136
	v_mov_b32_e32 v69, v136
	v_lshl_add_u64 v[66:67], v[66:67], 0, v[152:153]
	v_pk_mul_f32 v[62:63], v[62:63], v[68:69]
	v_pk_mul_f32 v[60:61], v[60:61], v[76:77]
	v_pk_mul_f32 v[58:59], v[58:59], v[68:69]
	s_and_b64 vcc, exec, s[42:43]
	v_pk_mul_f32 v[56:57], v[56:57], v[76:77]
	v_cvt_pk_bf16_f32 v72, v72, v73
	v_cvt_pk_bf16_f32 v73, v74, v75
	global_store_dwordx4 v[66:67], v[70:73], off sc1
	s_cbranch_vccnz .LBB0_169
	v_mul_f32_e32 v65, 0xbfb8aa3b, v60
	v_exp_f32_e32 v65, v65
	s_nop 0
	v_add_f32_e32 v65, 1.0, v65
	v_rcp_f32_e32 v68, v65
	v_mul_f32_e32 v65, 0xbfb8aa3b, v56
	v_exp_f32_e32 v65, v65
	s_nop 0
	v_add_f32_e32 v65, 1.0, v65
	v_rcp_f32_e32 v70, v65
	v_mul_f32_e32 v65, 0xbfb8aa3b, v61
	v_exp_f32_e32 v65, v65
	s_nop 0
	v_add_f32_e32 v65, 1.0, v65
	v_rcp_f32_e32 v69, v65
	v_mul_f32_e32 v65, 0xbfb8aa3b, v57
	v_exp_f32_e32 v65, v65
	v_pk_mul_f32 v[60:61], v[60:61], v[68:69]
	v_add_f32_e32 v65, 1.0, v65
	v_rcp_f32_e32 v71, v65
	v_mul_f32_e32 v65, 0xbfb8aa3b, v62
	v_exp_f32_e32 v65, v65
	v_pk_mul_f32 v[56:57], v[56:57], v[70:71]
	v_add_f32_e32 v65, 1.0, v65
	v_rcp_f32_e32 v72, v65
	v_mul_f32_e32 v65, 0xbfb8aa3b, v58
	v_exp_f32_e32 v65, v65
	s_nop 0
	v_add_f32_e32 v65, 1.0, v65
	v_rcp_f32_e32 v74, v65
	v_mul_f32_e32 v65, 0xbfb8aa3b, v63
	v_exp_f32_e32 v65, v65
	s_nop 0
	v_add_f32_e32 v65, 1.0, v65
	v_rcp_f32_e32 v73, v65
	v_mul_f32_e32 v65, 0xbfb8aa3b, v59
	v_exp_f32_e32 v65, v65
	v_pk_mul_f32 v[62:63], v[62:63], v[72:73]
	v_add_f32_e32 v65, 1.0, v65
	v_rcp_f32_e32 v75, v65
	s_nop 0
	v_pk_mul_f32 v[58:59], v[58:59], v[74:75]
.LBB0_169:
	s_mov_b64 s[98:99], 0
	v_cvt_pk_bf16_f32 v60, v60, v61
	v_cvt_pk_bf16_f32 v61, v62, v63
	v_cvt_pk_bf16_f32 v62, v56, v57
	v_cvt_pk_bf16_f32 v63, v58, v59
	global_store_dwordx4 v[66:67], v[60:63], off offset:256 sc1

; __device__ __forceinline__ unsigned cvt_pk_bf16(float lo, float hi) { unsigned r; asm volatile("v_cvt_pk_bf16_f32 %0, %1, %2" : "=v"(r) : "v"(lo), "v"(hi)); return r; }
; __device__ __forceinline__ float silu_f(float v) { return v * __builtin_amdgcn_rcpf(1.0f + __expf(-v)); }
;     __device__ __forceinline__ void operator()(const f32x4 (&acc)[2][2][4][2], const Unit& u, int wr, int wc, int fr, int fq) const {
;     ...
;                     bf16_t* rowp = Z + (size_t)r * ZW + pn * BM + wc * 32 + 8 * fq;
; #pragma unroll
;                     for (int bj = 0; bj < 2; ++bj) { f32x4 v0 = acc[ai][bj][m][0] * rs, v1 = acc[ai][bj][m][1] * rs;
;                         if (pn >= 4 && pn < 6) {
; #pragma unroll
;                             for (int j = 0; j < 4; ++j) { v0[j] = silu_f(v0[j]); v1[j] = silu_f(v1[j]); } }
;                         u32x4 w; w.x = cvt_pk_bf16(v0[0], v0[1]); w.y = cvt_pk_bf16(v0[2], v0[3]); w.z = cvt_pk_bf16(v1[0], v1[1]); w.w = cvt_pk_bf16(v1[2], v1[3]);
;                         *(u32x4*)(rowp + bj * HALF) = w; }
.LBB0_175:
	v_mov_b64_e32 v[50:51], s[60:61]
	v_mad_i64_i32 v[50:51], s[14:15], v48, s1, v[50:51]
	v_lshl_add_u64 v[50:51], s[96:97], 1, v[50:51]
	s_lshl_b32 s76, s7, 1
	v_mov_b32_e32 v60, v137
	v_mov_b32_e32 v61, v137
	v_lshl_add_u64 v[50:51], v[50:51], 0, s[76:77]
	v_lshlrev_b32_e32 v152, 1, v170
	v_cvt_pk_bf16_f32 v54, v54, v55
	v_cvt_pk_bf16_f32 v55, v52, v53
	v_mov_b32_e32 v52, v137
	v_mov_b32_e32 v53, v137
	v_lshl_add_u64 v[50:51], v[50:51], 0, v[152:153]
	v_pk_mul_f32 v[46:47], v[46:47], v[52:53]
	v_pk_mul_f32 v[44:45], v[44:45], v[60:61]
	v_pk_mul_f32 v[42:43], v[42:43], v[52:53]
	s_and_b64 vcc, exec, s[42:43]
	v_pk_mul_f32 v[40:41], v[40:41], v[60:61]
	v_cvt_pk_bf16_f32 v56, v56, v57
	v_cvt_pk_bf16_f32 v57, v58, v59
	global_store_dwordx4 v[50:51], v[54:57], off sc1
	s_cbranch_vccnz .LBB0_177
	v_mul_f32_e32 v49, 0xbfb8aa3b, v44
	v_exp_f32_e32 v49, v49
	s_nop 0
	v_add_f32_e32 v49, 1.0, v49
	v_rcp_f32_e32 v52, v49
	v_mul_f32_e32 v49, 0xbfb8aa3b, v40
	v_exp_f32_e32 v49, v49
	s_nop 0
	v_add_f32_e32 v49, 1.0, v49
	v_rcp_f32_e32 v54, v49
	v_mul_f32_e32 v49, 0xbfb8aa3b, v45
	v_exp_f32_e32 v49, v49
	s_nop 0
	v_add_f32_e32 v49, 1.0, v49
	v_rcp_f32_e32 v53, v49
	v_mul_f32_e32 v49, 0xbfb8aa3b, v41
	v_exp_f32_e32 v49, v49
	v_pk_mul_f32 v[44:45], v[44:45], v[52:53]
	v_add_f32_e32 v49, 1.0, v49
	v_rcp_f32_e32 v55, v49
	v_mul_f32_e32 v49, 0xbfb8aa3b, v46
	v_exp_f32_e32 v49, v49
	v_pk_mul_f32 v[40:41], v[40:41], v[54:55]
	v_add_f32_e32 v49, 1.0, v49
	v_rcp_f32_e32 v56, v49
	v_mul_f32_e32 v49, 0xbfb8aa3b, v42
	v_exp_f32_e32 v49, v49
	s_nop 0
	v_add_f32_e32 v49, 1.0, v49
	v_rcp_f32_e32 v58, v49
	v_mul_f32_e32 v49, 0xbfb8aa3b, v47
	v_exp_f32_e32 v49, v49
	s_nop 0
	v_add_f32_e32 v49, 1.0, v49
	v_rcp_f32_e32 v57, v49
	v_mul_f32_e32 v49, 0xbfb8aa3b, v43
	v_exp_f32_e32 v49, v49
	v_pk_mul_f32 v[46:47], v[46:47], v[56:57]
	v_add_f32_e32 v49, 1.0, v49
	v_rcp_f32_e32 v59, v49
	s_nop 0
	v_pk_mul_f32 v[42:43], v[42:43], v[58:59]
.LBB0_177:
	s_mov_b64 s[98:99], 0
	v_cvt_pk_bf16_f32 v44, v44, v45
	v_cvt_pk_bf16_f32 v45, v46, v47
	v_cvt_pk_bf16_f32 v46, v40, v41
	v_cvt_pk_bf16_f32 v47, v42, v43
	global_store_dwordx4 v[50:51], v[44:47], off offset:256 sc1

; __device__ __forceinline__ unsigned cvt_pk_bf16(float lo, float hi) { unsigned r; asm volatile("v_cvt_pk_bf16_f32 %0, %1, %2" : "=v"(r) : "v"(lo), "v"(hi)); return r; }
; __device__ __forceinline__ float silu_f(float v) { return v * __builtin_amdgcn_rcpf(1.0f + __expf(-v)); }
;     __device__ __forceinline__ void operator()(const f32x4 (&acc)[2][2][4][2], const Unit& u, int wr, int wc, int fr, int fq) const {
;     ...
;                     bf16_t* rowp = Z + (size_t)r * ZW + pn * BM + wc * 32 + 8 * fq;
; #pragma unroll
;                     for (int bj = 0; bj < 2; ++bj) { f32x4 v0 = acc[ai][bj][m][0] * rs, v1 = acc[ai][bj][m][1] * rs;
;                         if (pn >= 4 && pn < 6) {
; #pragma unroll
;                             for (int j = 0; j < 4; ++j) { v0[j] = silu_f(v0[j]); v1[j] = silu_f(v1[j]); } }
;                         u32x4 w; w.x = cvt_pk_bf16(v0[0], v0[1]); w.y = cvt_pk_bf16(v0[2], v0[3]); w.z = cvt_pk_bf16(v1[0], v1[1]); w.w = cvt_pk_bf16(v1[2], v1[3]);
;                         *(u32x4*)(rowp + bj * HALF) = w; }
.LBB0_183:
	v_mov_b64_e32 v[34:35], s[60:61]
	v_mad_i64_i32 v[34:35], s[14:15], v32, s1, v[34:35]
	v_lshl_add_u64 v[34:35], s[96:97], 1, v[34:35]
	s_lshl_b32 s76, s7, 1
	v_mov_b32_e32 v44, v128
	v_mov_b32_e32 v45, v128
	v_lshl_add_u64 v[34:35], v[34:35], 0, s[76:77]
	v_lshlrev_b32_e32 v152, 1, v170
	v_cvt_pk_bf16_f32 v38, v38, v39
	v_cvt_pk_bf16_f32 v39, v36, v37
	v_mov_b32_e32 v36, v128
	v_mov_b32_e32 v37, v128
	v_lshl_add_u64 v[34:35], v[34:35], 0, v[152:153]
	v_pk_mul_f32 v[30:31], v[30:31], v[36:37]
	v_pk_mul_f32 v[28:29], v[28:29], v[44:45]
	v_pk_mul_f32 v[26:27], v[26:27], v[36:37]
	s_and_b64 vcc, exec, s[42:43]
	v_pk_mul_f32 v[24:25], v[24:25], v[44:45]
	v_cvt_pk_bf16_f32 v40, v40, v41
	v_cvt_pk_bf16_f32 v41, v42, v43
	global_store_dwordx4 v[34:35], v[38:41], off sc1
	s_cbranch_vccnz .LBB0_185
	v_mul_f32_e32 v33, 0xbfb8aa3b, v28
	v_exp_f32_e32 v33, v33
	s_nop 0
	v_add_f32_e32 v33, 1.0, v33
	v_rcp_f32_e32 v36, v33
	v_mul_f32_e32 v33, 0xbfb8aa3b, v24
	v_exp_f32_e32 v33, v33
	s_nop 0
	v_add_f32_e32 v33, 1.0, v33
	v_rcp_f32_e32 v38, v33
	v_mul_f32_e32 v33, 0xbfb8aa3b, v29
	v_exp_f32_e32 v33, v33
	s_nop 0
	v_add_f32_e32 v33, 1.0, v33
	v_rcp_f32_e32 v37, v33
	v_mul_f32_e32 v33, 0xbfb8aa3b, v25
	v_exp_f32_e32 v33, v33
	v_pk_mul_f32 v[28:29], v[28:29], v[36:37]
	v_add_f32_e32 v33, 1.0, v33
	v_rcp_f32_e32 v39, v33
	v_mul_f32_e32 v33, 0xbfb8aa3b, v30
	v_exp_f32_e32 v33, v33
	v_pk_mul_f32 v[24:25], v[24:25], v[38:39]
	v_add_f32_e32 v33, 1.0, v33
	v_rcp_f32_e32 v40, v33
	v_mul_f32_e32 v33, 0xbfb8aa3b, v26
	v_exp_f32_e32 v33, v33
	s_nop 0
	v_add_f32_e32 v33, 1.0, v33
	v_rcp_f32_e32 v42, v33
	v_mul_f32_e32 v33, 0xbfb8aa3b, v31
	v_exp_f32_e32 v33, v33
	s_nop 0
	v_add_f32_e32 v33, 1.0, v33
	v_rcp_f32_e32 v41, v33
	v_mul_f32_e32 v33, 0xbfb8aa3b, v27
	v_exp_f32_e32 v33, v33
	v_pk_mul_f32 v[30:31], v[30:31], v[40:41]
	v_add_f32_e32 v33, 1.0, v33
	v_rcp_f32_e32 v43, v33
	s_nop 0
	v_pk_mul_f32 v[26:27], v[26:27], v[42:43]
.LBB0_185:
	s_mov_b64 s[98:99], 0
	v_cvt_pk_bf16_f32 v28, v28, v29
	v_cvt_pk_bf16_f32 v29, v30, v31
	v_cvt_pk_bf16_f32 v30, v24, v25
	v_cvt_pk_bf16_f32 v31, v26, v27
	global_store_dwordx4 v[34:35], v[28:31], off offset:256 sc1

; __device__ __forceinline__ unsigned cvt_pk_bf16(float lo, float hi) { unsigned r; asm volatile("v_cvt_pk_bf16_f32 %0, %1, %2" : "=v"(r) : "v"(lo), "v"(hi)); return r; }
; __device__ __forceinline__ float silu_f(float v) { return v * __builtin_amdgcn_rcpf(1.0f + __expf(-v)); }
;     __device__ __forceinline__ void operator()(const f32x4 (&acc)[2][2][4][2], const Unit& u, int wr, int wc, int fr, int fq) const {
;     ...
;                     bf16_t* rowp = Z + (size_t)r * ZW + pn * BM + wc * 32 + 8 * fq;
; #pragma unroll
;                     for (int bj = 0; bj < 2; ++bj) { f32x4 v0 = acc[ai][bj][m][0] * rs, v1 = acc[ai][bj][m][1] * rs;
;                         if (pn >= 4 && pn < 6) {
; #pragma unroll
;                             for (int j = 0; j < 4; ++j) { v0[j] = silu_f(v0[j]); v1[j] = silu_f(v1[j]); } }
;                         u32x4 w; w.x = cvt_pk_bf16(v0[0], v0[1]); w.y = cvt_pk_bf16(v0[2], v0[3]); w.z = cvt_pk_bf16(v1[0], v1[1]); w.w = cvt_pk_bf16(v1[2], v1[3]);
;                         *(u32x4*)(rowp + bj * HALF) = w; }
.LBB0_191:
	v_mov_b64_e32 v[18:19], s[60:61]
	v_mad_i64_i32 v[18:19], s[14:15], v16, s1, v[18:19]
	v_lshl_add_u64 v[18:19], s[96:97], 1, v[18:19]
	s_lshl_b32 s76, s7, 1
	v_mov_b32_e32 v28, v129
	v_mov_b32_e32 v29, v129
	v_lshl_add_u64 v[18:19], v[18:19], 0, s[76:77]
	v_lshlrev_b32_e32 v152, 1, v170
	v_cvt_pk_bf16_f32 v22, v22, v23
	v_cvt_pk_bf16_f32 v23, v20, v21
	v_mov_b32_e32 v20, v129
	v_mov_b32_e32 v21, v129
	v_lshl_add_u64 v[18:19], v[18:19], 0, v[152:153]
	v_pk_mul_f32 v[14:15], v[14:15], v[20:21]
	v_pk_mul_f32 v[12:13], v[12:13], v[28:29]
	v_pk_mul_f32 v[10:11], v[10:11], v[20:21]
	s_and_b64 vcc, exec, s[42:43]
	v_pk_mul_f32 v[8:9], v[8:9], v[28:29]
	v_cvt_pk_bf16_f32 v24, v24, v25
	v_cvt_pk_bf16_f32 v25, v26, v27
	global_store_dwordx4 v[18:19], v[22:25], off sc1
	s_cbranch_vccnz .LBB0_193
	v_mul_f32_e32 v17, 0xbfb8aa3b, v12
	v_exp_f32_e32 v17, v17
	s_nop 0
	v_add_f32_e32 v17, 1.0, v17
	v_rcp_f32_e32 v20, v17
	v_mul_f32_e32 v17, 0xbfb8aa3b, v8
	v_exp_f32_e32 v17, v17
	s_nop 0
	v_add_f32_e32 v17, 1.0, v17
	v_rcp_f32_e32 v22, v17
	v_mul_f32_e32 v17, 0xbfb8aa3b, v13
	v_exp_f32_e32 v17, v17
	s_nop 0
	v_add_f32_e32 v17, 1.0, v17
	v_rcp_f32_e32 v21, v17
	v_mul_f32_e32 v17, 0xbfb8aa3b, v9
	v_exp_f32_e32 v17, v17
	v_pk_mul_f32 v[12:13], v[12:13], v[20:21]
	v_add_f32_e32 v17, 1.0, v17
	v_rcp_f32_e32 v23, v17
	v_mul_f32_e32 v17, 0xbfb8aa3b, v14
	v_exp_f32_e32 v17, v17
	v_pk_mul_f32 v[8:9], v[8:9], v[22:23]
	v_add_f32_e32 v17, 1.0, v17
	v_rcp_f32_e32 v24, v17
	v_mul_f32_e32 v17, 0xbfb8aa3b, v10
	v_exp_f32_e32 v17, v17
	s_nop 0
	v_add_f32_e32 v17, 1.0, v17
	v_rcp_f32_e32 v26, v17
	v_mul_f32_e32 v17, 0xbfb8aa3b, v15
	v_exp_f32_e32 v17, v17
	s_nop 0
	v_add_f32_e32 v17, 1.0, v17
	v_rcp_f32_e32 v25, v17
	v_mul_f32_e32 v17, 0xbfb8aa3b, v11
	v_exp_f32_e32 v17, v17
	v_pk_mul_f32 v[14:15], v[14:15], v[24:25]
	v_add_f32_e32 v17, 1.0, v17
	v_rcp_f32_e32 v27, v17
	s_nop 0
	v_pk_mul_f32 v[10:11], v[10:11], v[26:27]
.LBB0_193:
	s_mov_b64 s[46:47], 0
	v_cvt_pk_bf16_f32 v12, v12, v13
	v_cvt_pk_bf16_f32 v13, v14, v15
	v_cvt_pk_bf16_f32 v14, v8, v9
	v_cvt_pk_bf16_f32 v15, v10, v11
	global_store_dwordx4 v[18:19], v[12:15], off offset:256 sc1

; __device__ __forceinline__ unsigned cvt_pk_bf16(float lo, float hi) { unsigned r; asm volatile("v_cvt_pk_bf16_f32 %0, %1, %2" : "=v"(r) : "v"(lo), "v"(hi)); return r; }
;     __device__ __forceinline__ void operator()(const f32x4 (&acc)[2][2][4][2], const Unit& u, int wr, int wc, int fr, int fq) const {
;         const int row0 = u.pm * BM + wr * 64 + fr; const int pn = u.pn;
;         float rsv[2][4]; rows_rstd_cached(ssq, row0, fq, rsv, u.pm == cached_pm, rsc, wr * 64 + fr, wc == 0 && fq == 0); cached_pm = u.pm;
; #pragma unroll
;         for (int ai = 0; ai < 2; ++ai)
; #pragma unroll
;             for (int m = 0; m < 4; ++m) {
;                 const int r = row0 + ai * HALF + m * 16; const float rs = rsv[ai][m];
;                 if (pn == 8) {
;                     if (wc == 0) { const f32x4 v0 = acc[ai][0][m][0] * rs, v1 = acc[ai][0][m][1] * rs; u32x4 w; w.x = cvt_pk_bf16(v0[0], v0[1]); w.y = cvt_pk_bf16(v0[2], v0[3]); w.z = cvt_pk_bf16(v1[0], v1[1]); w.w = cvt_pk_bf16(v1[2], v1[3]); *(u32x4*)(DEC + (size_t)r * 32 + 8 * fq) = w; }
.LBB0_199:
	s_waitcnt lgkmcnt(0)
	v_pk_mul_f32 v[100:101], v[100:101], v[188:189] op_sel:[0,1]
	v_ashrrev_i32_e32 v187, 31, v186
	v_pk_mul_f32 v[104:105], v[98:99], v[188:189] op_sel:[0,1]
	v_pk_mul_f32 v[98:99], v[96:97], v[188:189] op_sel:[0,1]
	v_cvt_pk_bf16_f32 v96, v100, v101
	v_lshlrev_b64 v[100:101], 6, v[186:187]
	v_lshl_add_u64 v[100:101], v[172:173], 0, v[100:101]
	v_pk_mul_f32 v[102:103], v[102:103], v[188:189] op_sel:[0,1]
	s_nop 0
	v_cvt_pk_bf16_f32 v97, v102, v103
	v_cvt_pk_bf16_f32 v98, v98, v99
	v_cvt_pk_bf16_f32 v99, v104, v105
	global_store_dwordx4 v[100:101], v[96:99], off sc1
	s_and_b64 vcc, exec, s[46:47]
	s_mov_b64 s[98:99], -1
	s_cbranch_vccz .LBB0_149
	s_branch .LBB0_154
.LBB0_200:
	s_waitcnt lgkmcnt(0)
	v_pk_mul_f32 v[84:85], v[84:85], v[144:145] op_sel_hi:[1,0]
	v_ashrrev_i32_e32 v185, 31, v184
	v_pk_mul_f32 v[88:89], v[82:83], v[144:145] op_sel_hi:[1,0]
	v_pk_mul_f32 v[82:83], v[80:81], v[144:145] op_sel_hi:[1,0]
	v_cvt_pk_bf16_f32 v80, v84, v85
	v_lshlrev_b64 v[84:85], 6, v[184:185]
	v_lshl_add_u64 v[84:85], v[172:173], 0, v[84:85]
	v_pk_mul_f32 v[86:87], v[86:87], v[144:145] op_sel_hi:[1,0]
	s_nop 0
	v_cvt_pk_bf16_f32 v81, v86, v87
	v_cvt_pk_bf16_f32 v82, v82, v83
	v_cvt_pk_bf16_f32 v83, v88, v89
	global_store_dwordx4 v[84:85], v[80:83], off sc1
	s_and_b64 vcc, exec, s[46:47]
	s_mov_b64 s[98:99], -1
	s_cbranch_vccz .LBB0_157
	s_branch .LBB0_162
.LBB0_201:
	s_waitcnt lgkmcnt(0)
	v_pk_mul_f32 v[68:69], v[68:69], v[144:145] op_sel:[0,1]
	v_ashrrev_i32_e32 v183, 31, v182
	v_pk_mul_f32 v[72:73], v[66:67], v[144:145] op_sel:[0,1]
	v_pk_mul_f32 v[66:67], v[64:65], v[144:145] op_sel:[0,1]
	v_cvt_pk_bf16_f32 v64, v68, v69
	v_lshlrev_b64 v[68:69], 6, v[182:183]
	v_lshl_add_u64 v[68:69], v[172:173], 0, v[68:69]
	v_pk_mul_f32 v[70:71], v[70:71], v[144:145] op_sel:[0,1]
	s_nop 0
	v_cvt_pk_bf16_f32 v65, v70, v71
	v_cvt_pk_bf16_f32 v66, v66, v67
	v_cvt_pk_bf16_f32 v67, v72, v73
	global_store_dwordx4 v[68:69], v[64:67], off sc1
	s_nop 1
	v_add_u32_e32 v64, 0x80, v180
	s_and_b64 vcc, exec, s[46:47]
	s_mov_b64 s[98:99], -1
	s_cbranch_vccz .LBB0_165
	s_branch .LBB0_170
.LBB0_202:
	s_waitcnt lgkmcnt(0)
	v_pk_mul_f32 v[52:53], v[52:53], v[136:137] op_sel_hi:[1,0]
	v_ashrrev_i32_e32 v65, 31, v64
	v_pk_mul_f32 v[56:57], v[50:51], v[136:137] op_sel_hi:[1,0]
	v_pk_mul_f32 v[50:51], v[48:49], v[136:137] op_sel_hi:[1,0]
	v_cvt_pk_bf16_f32 v48, v52, v53
	v_lshlrev_b64 v[52:53], 6, v[64:65]
	v_lshl_add_u64 v[52:53], v[172:173], 0, v[52:53]
	v_pk_mul_f32 v[54:55], v[54:55], v[136:137] op_sel_hi:[1,0]
	s_nop 0
	v_cvt_pk_bf16_f32 v49, v54, v55
	v_cvt_pk_bf16_f32 v50, v50, v51
	v_cvt_pk_bf16_f32 v51, v56, v57
	global_store_dwordx4 v[52:53], v[48:51], off sc1
	s_nop 1
	v_add_u32_e32 v48, 0x90, v180
	s_and_b64 vcc, exec, s[46:47]
	s_mov_b64 s[98:99], -1
	s_cbranch_vccz .LBB0_173
	s_branch .LBB0_178
.LBB0_203:
	s_waitcnt lgkmcnt(0)
	v_pk_mul_f32 v[36:37], v[36:37], v[136:137] op_sel:[0,1]
	v_ashrrev_i32_e32 v49, 31, v48
	v_pk_mul_f32 v[40:41], v[34:35], v[136:137] op_sel:[0,1]
	v_pk_mul_f32 v[34:35], v[32:33], v[136:137] op_sel:[0,1]
	v_cvt_pk_bf16_f32 v32, v36, v37
	v_lshlrev_b64 v[36:37], 6, v[48:49]
	v_lshl_add_u64 v[36:37], v[172:173], 0, v[36:37]
	v_pk_mul_f32 v[38:39], v[38:39], v[136:137] op_sel:[0,1]
	s_nop 0
	v_cvt_pk_bf16_f32 v33, v38, v39
	v_cvt_pk_bf16_f32 v34, v34, v35
	v_cvt_pk_bf16_f32 v35, v40, v41
	global_store_dwordx4 v[36:37], v[32:35], off sc1
	s_nop 1
	v_add_u32_e32 v32, 0xa0, v180
	s_and_b64 vcc, exec, s[46:47]
	s_mov_b64 s[98:99], -1
	s_cbranch_vccz .LBB0_181
	s_branch .LBB0_186
.LBB0_204:
	s_waitcnt lgkmcnt(0)
	v_pk_mul_f32 v[20:21], v[20:21], v[128:129] op_sel_hi:[1,0]
	v_ashrrev_i32_e32 v33, 31, v32
	v_pk_mul_f32 v[24:25], v[18:19], v[128:129] op_sel_hi:[1,0]
	v_pk_mul_f32 v[18:19], v[16:17], v[128:129] op_sel_hi:[1,0]
	v_cvt_pk_bf16_f32 v16, v20, v21
	v_lshlrev_b64 v[20:21], 6, v[32:33]
	v_lshl_add_u64 v[20:21], v[172:173], 0, v[20:21]
	v_pk_mul_f32 v[22:23], v[22:23], v[128:129] op_sel_hi:[1,0]
	s_nop 0
	v_cvt_pk_bf16_f32 v17, v22, v23
	v_cvt_pk_bf16_f32 v18, v18, v19
	v_cvt_pk_bf16_f32 v19, v24, v25
	global_store_dwordx4 v[20:21], v[16:19], off sc1
	s_nop 1
	v_add_u32_e32 v16, 0xb0, v180
	s_and_b64 vcc, exec, s[46:47]
	s_mov_b64 s[46:47], -1
	s_cbranch_vccz .LBB0_189
	s_branch .LBB0_194
.LBB0_205:
	s_waitcnt lgkmcnt(0)
	v_pk_mul_f32 v[4:5], v[4:5], v[128:129] op_sel:[0,1]
	v_ashrrev_i32_e32 v17, 31, v16
	v_pk_mul_f32 v[8:9], v[2:3], v[128:129] op_sel:[0,1]
	v_pk_mul_f32 v[2:3], v[0:1], v[128:129] op_sel:[0,1]
	v_cvt_pk_bf16_f32 v0, v4, v5
	v_lshlrev_b64 v[4:5], 6, v[16:17]
	v_lshl_add_u64 v[4:5], v[172:173], 0, v[4:5]
	v_pk_mul_f32 v[6:7], v[6:7], v[128:129] op_sel:[0,1]
	s_nop 0
	v_cvt_pk_bf16_f32 v1, v6, v7
	v_cvt_pk_bf16_f32 v2, v2, v3
	v_cvt_pk_bf16_f32 v3, v8, v9
	global_store_dwordx4 v[4:5], v[0:3], off sc1
	s_andn2_b64 vcc, exec, s[54:55]
	s_mov_b64 s[42:43], -1
	s_cbranch_vccnz .LBB0_113
	s_branch .LBB0_197

; __device__ __forceinline__ unsigned cvt_pk_bf16(float lo, float hi) { unsigned r; asm volatile("v_cvt_pk_bf16_f32 %0, %1, %2" : "=v"(r) : "v"(lo), "v"(hi)); return r; }
; __device__ __forceinline__ float bflo(unsigned w) { return __uint_as_float(w << 16); }
; __device__ __forceinline__ float bfhi(unsigned w) { return __uint_as_float(w & 0xffff0000u); }
; template <bool RD32>
; __device__ __forceinline__ void res_rows(const float* __restrict__ xold32, const bf16_t* __restrict__ xoldb, bf16_t* __restrict__ xb, float* __restrict__ ssq, const f32x4 (&acc)[2][2][4][2], int row0, int col0, int slot) {
;     f32x4 xo[2][2][2];
;     float ssv[8];
;     auto ld = [&](size_t o, f32x4& a, f32x4& b) { if (RD32) { a = *(const f32x4*)(xold32 + o); b = *(const f32x4*)(xold32 + o + 4); }
;         else { const u32x4 w = *(const u32x4*)(xoldb + o); a = (f32x4){bflo(w.x), bfhi(w.x), bflo(w.y), bfhi(w.y)}; b = (f32x4){bflo(w.z), bfhi(w.z), bflo(w.w), bfhi(w.w)}; } };
; #pragma unroll
;     for (int bj = 0; bj < 2; ++bj) ld((size_t)row0 * D + col0 + bj * HALF, xo[0][bj][0], xo[0][bj][1]);
; #pragma unroll
;     for (int idx = 0; idx < 8; ++idx) {
;         const int ai = idx >> 2, m = idx & 3; const int r = row0 + ai * HALF + m * 16; const size_t off = (size_t)r * D + col0;
;         if (idx < 7) { const int ai2 = (idx + 1) >> 2, m2 = (idx + 1) & 3; const size_t off2 = (size_t)(row0 + ai2 * HALF + m2 * 16) * D + col0;
; #pragma unroll
;             for (int bj = 0; bj < 2; ++bj) ld(off2 + bj * HALF, xo[(idx + 1) & 1][bj][0], xo[(idx + 1) & 1][bj][1]); }
;         float ss = 0.f;
; #pragma unroll
;         for (int bj = 0; bj < 2; ++bj) { const f32x4 x0 = xo[idx & 1][bj][0] + acc[ai][bj][m][0], x1 = xo[idx & 1][bj][1] + acc[ai][bj][m][1];
;             u32x4 w; w.x = cvt_pk_bf16(x0[0], x0[1]); w.y = cvt_pk_bf16(x0[2], x0[3]); w.z = cvt_pk_bf16(x1[0], x1[1]); w.w = cvt_pk_bf16(x1[2], x1[3]);
;             *(u32x4*)(xb + off + bj * HALF) = w;
;             ss += ((x0[0] * x0[0] + x0[1] * x0[1]) + (x0[2] * x0[2] + x0[3] * x0[3])) + ((x1[0] * x1[0] + x1[1] * x1[1]) + (x1[2] * x1[2] + x1[3] * x1[3])); }
;         ss += __shfl_xor(ss, 16); ss += __shfl_xor(ss, 32);
;         ssv[idx] = ss;
;     }
.LBB0_421:
	v_lshl_add_u32 v166, s5, 8, v217
	v_lshl_or_b32 v132, s4, 8, v219
	v_lshl_or_b32 v222, s4, 2, v220
	v_ashrrev_i32_e32 v167, 31, v166
	v_or_b32_e32 v223, s95, v222
	v_ashrrev_i32_e32 v133, 31, v132
	s_andn2_b64 vcc, exec, s[48:49]
	v_lshlrev_b64 v[174:175], 11, v[166:167]
	v_or_b32_e32 v172, 16, v166
	v_or_b32_e32 v170, 32, v166
	v_or_b32_e32 v168, 48, v166
	s_cbranch_vccnz .LBB0_436
	v_lshl_add_u64 v[128:129], s[58:59], 0, v[174:175]
	v_lshlrev_b64 v[134:135], 1, v[132:133]
	v_lshl_add_u64 v[136:137], v[128:129], 0, v[134:135]
	global_load_dwordx4 v[128:131], v[136:137], off
	v_ashrrev_i32_e32 v173, 31, v172
	v_ashrrev_i32_e32 v171, 31, v170
	s_mov_b64 s[4:5], 0x40000
	s_waitcnt vmcnt(0)
	v_lshlrev_b32_e32 v138, 16, v128
	v_and_b32_e32 v139, 0xffff0000, v128
	v_lshlrev_b32_e32 v140, 16, v129
	v_and_b32_e32 v141, 0xffff0000, v129
	v_lshlrev_b32_e32 v142, 16, v130
	v_and_b32_e32 v143, 0xffff0000, v130
	v_lshlrev_b32_e32 v176, 16, v131
	v_and_b32_e32 v177, 0xffff0000, v131
	global_load_dwordx4 v[128:131], v[136:137], off offset:256
	v_pk_add_f32 v[140:141], v[126:127], v[140:141]
	v_pk_add_f32 v[138:139], v[124:125], v[138:139]
	v_pk_add_f32 v[176:177], v[122:123], v[176:177]
	v_pk_add_f32 v[142:143], v[120:121], v[142:143]
	s_waitcnt vmcnt(0)
	v_lshlrev_b32_e32 v178, 16, v128
	v_and_b32_e32 v179, 0xffff0000, v128
	v_lshlrev_b32_e32 v180, 16, v129
	v_and_b32_e32 v181, 0xffff0000, v129
	v_lshlrev_b32_e32 v182, 16, v130
	v_and_b32_e32 v183, 0xffff0000, v130
	v_lshlrev_b32_e32 v202, 16, v131
	v_and_b32_e32 v203, 0xffff0000, v131
	v_lshl_add_u64 v[130:131], s[58:59], 0, v[134:135]
	v_lshlrev_b64 v[128:129], 11, v[172:173]
	v_lshl_add_u64 v[184:185], v[130:131], 0, v[128:129]
	global_load_dwordx4 v[134:137], v[184:185], off
	v_lshl_add_u64 v[128:129], v[130:131], 0, v[174:175]
	s_waitcnt vmcnt(0)
	v_lshlrev_b32_e32 v186, 16, v134
	v_and_b32_e32 v187, 0xffff0000, v134
	v_lshlrev_b32_e32 v190, 16, v135
	v_and_b32_e32 v191, 0xffff0000, v135
	v_lshlrev_b32_e32 v188, 16, v136
	v_and_b32_e32 v189, 0xffff0000, v136
	v_lshlrev_b32_e32 v192, 16, v137
	v_and_b32_e32 v193, 0xffff0000, v137
	global_load_dwordx4 v[134:137], v[184:185], off offset:256
	v_pk_add_f32 v[190:191], v[110:111], v[190:191]
	v_pk_add_f32 v[192:193], v[106:107], v[192:193]
	s_waitcnt vmcnt(0)
	v_lshlrev_b32_e32 v194, 16, v134
	v_and_b32_e32 v195, 0xffff0000, v134
	v_lshlrev_b32_e32 v198, 16, v135
	v_and_b32_e32 v199, 0xffff0000, v135
	v_cvt_pk_bf16_f32 v134, v138, v139
	v_cvt_pk_bf16_f32 v135, v140, v141
	v_lshlrev_b32_e32 v196, 16, v136
	v_and_b32_e32 v197, 0xffff0000, v136
	v_lshlrev_b32_e32 v200, 16, v137
	v_and_b32_e32 v201, 0xffff0000, v137
	v_cvt_pk_bf16_f32 v136, v142, v143
	v_cvt_pk_bf16_f32 v137, v176, v177
	global_store_dwordx4 v[128:129], v[134:137], off sc1
	v_pk_add_f32 v[196:197], v[96:97], v[196:197]
	s_nop 0
	v_mul_f32_e32 v134, v139, v139
	v_mul_f32_e32 v135, v141, v141
	v_fmac_f32_e32 v134, v138, v138
	v_fmac_f32_e32 v135, v140, v140
	v_add_f32_e32 v134, v134, v135
	v_mul_f32_e32 v135, v143, v143
	v_mul_f32_e32 v136, v177, v177
	v_fmac_f32_e32 v135, v142, v142
	v_fmac_f32_e32 v136, v176, v176
	v_add_f32_e32 v135, v135, v136
	v_add_f32_e32 v152, v134, v135
	v_pk_add_f32 v[138:139], v[118:119], v[180:181]
	v_pk_add_f32 v[140:141], v[116:117], v[178:179]
	v_pk_add_f32 v[142:143], v[114:115], v[202:203]
	v_cvt_pk_bf16_f32 v134, v140, v141
	v_cvt_pk_bf16_f32 v135, v138, v139
	v_pk_add_f32 v[176:177], v[112:113], v[182:183]
	s_nop 0
	v_cvt_pk_bf16_f32 v136, v176, v177
	v_cvt_pk_bf16_f32 v137, v142, v143
	global_store_dwordx4 v[128:129], v[134:137], off offset:256 sc1
	s_nop 1
	v_mul_f32_e32 v134, v141, v141
	v_mul_f32_e32 v135, v139, v139
	v_fmac_f32_e32 v134, v140, v140
	v_fmac_f32_e32 v135, v138, v138
	v_add_f32_e32 v134, v134, v135
	v_mul_f32_e32 v135, v177, v177
	v_mul_f32_e32 v136, v143, v143
	v_fmac_f32_e32 v135, v176, v176
	v_fmac_f32_e32 v136, v142, v142
	v_add_f32_e32 v135, v135, v136
	v_and_b32_e32 v136, 64, v209
	v_add_f32_e32 v134, v134, v135
	v_xor_b32_e32 v135, 16, v209
	v_add_u32_e32 v136, 64, v136
	v_cmp_lt_i32_e32 vcc, v135, v136
	v_add_f32_e32 v134, v152, v134
	s_nop 0
	v_cndmask_b32_e32 v135, v209, v135, vcc
	v_lshlrev_b32_e32 v152, 2, v135
	ds_bpermute_b32 v135, v152, v134
	s_waitcnt lgkmcnt(0)
	v_add_f32_e32 v173, v134, v135
	v_xor_b32_e32 v134, 32, v209
	v_cmp_lt_i32_e32 vcc, v134, v136
	s_nop 1
	v_cndmask_b32_e32 v134, v209, v134, vcc
	v_lshlrev_b32_e32 v225, 2, v134
	v_lshlrev_b64 v[134:135], 11, v[170:171]
	v_lshl_add_u64 v[134:135], v[130:131], 0, v[134:135]
	global_load_dwordx4 v[136:139], v[134:135], off
	global_load_dwordx4 v[202:205], v[134:135], off offset:256
	v_mul_f32_e32 v171, v191, v191
	v_fmac_f32_e32 v171, v190, v190
	ds_bpermute_b32 v224, v225, v173
	s_waitcnt vmcnt(1)
	v_lshlrev_b32_e32 v176, 16, v138
	v_and_b32_e32 v177, 0xffff0000, v138
	v_lshlrev_b32_e32 v180, 16, v139
	v_and_b32_e32 v181, 0xffff0000, v139
	s_waitcnt vmcnt(0)
; __device__ __forceinline__ unsigned cvt_pk_bf16(float lo, float hi) { unsigned r; asm volatile("v_cvt_pk_bf16_f32 %0, %1, %2" : "=v"(r) : "v"(lo), "v"(hi)); return r; }
; template <bool RD32>
; __device__ __forceinline__ void res_rows(const float* __restrict__ xold32, const bf16_t* __restrict__ xoldb, bf16_t* __restrict__ xb, float* __restrict__ ssq, const f32x4 (&acc)[2][2][4][2], int row0, int col0, int slot) {
;     ...
;     for (int bj = 0; bj < 2; ++bj) ld((size_t)row0 * D + col0 + bj * HALF, xo[0][bj][0], xo[0][bj][1]);
; #pragma unroll
;     for (int idx = 0; idx < 8; ++idx) {
;         const int ai = idx >> 2, m = idx & 3; const int r = row0 + ai * HALF + m * 16; const size_t off = (size_t)r * D + col0;
;         if (idx < 7) { const int ai2 = (idx + 1) >> 2, m2 = (idx + 1) & 3; const size_t off2 = (size_t)(row0 + ai2 * HALF + m2 * 16) * D + col0;
; #pragma unroll
;             for (int bj = 0; bj < 2; ++bj) ld(off2 + bj * HALF, xo[(idx + 1) & 1][bj][0], xo[(idx + 1) & 1][bj][1]); }
;         float ss = 0.f;
; #pragma unroll
;         for (int bj = 0; bj < 2; ++bj) { const f32x4 x0 = xo[idx & 1][bj][0] + acc[ai][bj][m][0], x1 = xo[idx & 1][bj][1] + acc[ai][bj][m][1];
;             u32x4 w; w.x = cvt_pk_bf16(x0[0], x0[1]); w.y = cvt_pk_bf16(x0[2], x0[3]); w.z = cvt_pk_bf16(x1[0], x1[1]); w.w = cvt_pk_bf16(x1[2], x1[3]);
;             *(u32x4*)(xb + off + bj * HALF) = w;
;             ss += ((x0[0] * x0[0] + x0[1] * x0[1]) + (x0[2] * x0[2] + x0[3] * x0[3])) + ((x1[0] * x1[0] + x1[1] * x1[1]) + (x1[2] * x1[2] + x1[3] * x1[3])); }
;         ss += __shfl_xor(ss, 16); ss += __shfl_xor(ss, 32);
;         ssv[idx] = ss;
;     }
	v_lshlrev_b32_e32 v138, 16, v202
	v_and_b32_e32 v139, 0xffff0000, v202
	v_lshlrev_b32_e32 v142, 16, v203
	v_and_b32_e32 v143, 0xffff0000, v203
	v_pk_add_f32 v[202:203], v[108:109], v[186:187]
	v_lshlrev_b32_e32 v178, 16, v136
	v_mul_f32_e32 v169, v203, v203
	v_and_b32_e32 v179, 0xffff0000, v136
	v_lshlrev_b32_e32 v182, 16, v137
	v_and_b32_e32 v183, 0xffff0000, v137
	v_lshlrev_b32_e32 v136, 16, v204
	v_and_b32_e32 v137, 0xffff0000, v204
	v_lshlrev_b32_e32 v140, 16, v205
	v_and_b32_e32 v141, 0xffff0000, v205
	v_pk_add_f32 v[204:205], v[104:105], v[188:189]
	v_cvt_pk_bf16_f32 v186, v202, v203
	v_fmac_f32_e32 v169, v202, v202
	v_cvt_pk_bf16_f32 v187, v190, v191
	v_cvt_pk_bf16_f32 v188, v204, v205
	v_cvt_pk_bf16_f32 v189, v192, v193
	global_store_dwordx4 v[184:185], v[186:189], off sc1
	v_add_f32_e32 v169, v169, v171
	v_mul_f32_e32 v171, v205, v205
	v_mul_f32_e32 v186, v193, v193
	v_fmac_f32_e32 v171, v204, v204
	v_fmac_f32_e32 v186, v192, v192
	v_add_f32_e32 v171, v171, v186
	v_pk_add_f32 v[190:191], v[102:103], v[198:199]
	v_pk_add_f32 v[192:193], v[100:101], v[194:195]
	v_add_f32_e32 v169, v169, v171
	v_pk_add_f32 v[194:195], v[98:99], v[200:201]
	v_cvt_pk_bf16_f32 v186, v192, v193
	v_cvt_pk_bf16_f32 v187, v190, v191
	v_cvt_pk_bf16_f32 v188, v196, v197
	v_mul_f32_e32 v171, v193, v193
	v_cvt_pk_bf16_f32 v189, v194, v195
	global_store_dwordx4 v[184:185], v[186:189], off offset:256 sc1
	v_mul_f32_e32 v184, v191, v191
	v_fmac_f32_e32 v171, v192, v192
	v_fmac_f32_e32 v184, v190, v190
	v_add_f32_e32 v171, v171, v184
	v_mul_f32_e32 v184, v197, v197
	v_mul_f32_e32 v185, v195, v195
	v_fmac_f32_e32 v184, v196, v196
	v_fmac_f32_e32 v185, v194, v194
	v_add_f32_e32 v184, v184, v185
	v_add_f32_e32 v171, v171, v184
	v_add_f32_e32 v169, v169, v171
	ds_bpermute_b32 v171, v152, v169
	v_pk_add_f32 v[182:183], v[94:95], v[182:183]
	v_pk_add_f32 v[194:195], v[92:93], v[178:179]
	v_pk_add_f32 v[180:181], v[90:91], v[180:181]
	v_pk_add_f32 v[142:143], v[86:87], v[142:143]
	s_waitcnt lgkmcnt(0)
	v_add_f32_e32 v171, v169, v171
	v_ashrrev_i32_e32 v169, 31, v168
	v_lshlrev_b64 v[184:185], 11, v[168:169]
	v_lshl_add_u64 v[130:131], v[130:131], 0, v[184:185]
	global_load_dwordx4 v[184:187], v[130:131], off
	global_load_dwordx4 v[202:205], v[130:131], off offset:256
	v_mul_f32_e32 v169, v195, v195
	v_fmac_f32_e32 v169, v194, v194
	v_pk_add_f32 v[140:141], v[82:83], v[140:141]
	ds_bpermute_b32 v226, v225, v171
	s_waitcnt vmcnt(1)
	v_lshlrev_b32_e32 v192, 16, v186
	v_and_b32_e32 v193, 0xffff0000, v186
	v_lshlrev_b32_e32 v198, 16, v187
	v_and_b32_e32 v199, 0xffff0000, v187
	s_waitcnt vmcnt(0)
	v_lshlrev_b32_e32 v186, 16, v202
	v_and_b32_e32 v187, 0xffff0000, v202
	v_lshlrev_b32_e32 v190, 16, v203
	v_and_b32_e32 v191, 0xffff0000, v203
	v_pk_add_f32 v[202:203], v[88:89], v[176:177]
	v_cvt_pk_bf16_f32 v176, v194, v195
	v_cvt_pk_bf16_f32 v177, v182, v183
	v_lshlrev_b32_e32 v196, 16, v184
	v_cvt_pk_bf16_f32 v178, v202, v203
	v_cvt_pk_bf16_f32 v179, v180, v181
	global_store_dwordx4 v[134:135], v[176:179], off sc1
	v_and_b32_e32 v197, 0xffff0000, v184
	v_lshlrev_b32_e32 v200, 16, v185
	v_mul_f32_e32 v176, v183, v183
	v_fmac_f32_e32 v176, v182, v182
	v_add_f32_e32 v169, v169, v176
	v_mul_f32_e32 v176, v203, v203
	v_mul_f32_e32 v177, v181, v181
	v_fmac_f32_e32 v176, v202, v202
	v_fmac_f32_e32 v177, v180, v180
	v_add_f32_e32 v176, v176, v177
	v_add_f32_e32 v169, v169, v176
	v_pk_add_f32 v[176:177], v[84:85], v[138:139]
	v_pk_add_f32 v[178:179], v[80:81], v[136:137]
	v_cvt_pk_bf16_f32 v136, v176, v177
	v_cvt_pk_bf16_f32 v137, v142, v143
	v_and_b32_e32 v201, 0xffff0000, v185
	v_cvt_pk_bf16_f32 v138, v178, v179
	v_cvt_pk_bf16_f32 v139, v140, v141
	global_store_dwordx4 v[134:135], v[136:139], off offset:256 sc1
	v_mul_f32_e32 v134, v177, v177
	v_mul_f32_e32 v135, v143, v143
	v_fmac_f32_e32 v134, v176, v176
	v_fmac_f32_e32 v135, v142, v142
	v_add_f32_e32 v134, v134, v135
	v_mul_f32_e32 v135, v179, v179
	v_mul_f32_e32 v136, v141, v141
	v_fmac_f32_e32 v135, v178, v178
	v_fmac_f32_e32 v136, v140, v140
	v_add_f32_e32 v135, v135, v136
	v_add_f32_e32 v134, v134, v135
	v_add_f32_e32 v134, v169, v134
	ds_bpermute_b32 v135, v152, v134
	v_lshlrev_b32_e32 v184, 16, v204
	v_and_b32_e32 v185, 0xffff0000, v204
	v_lshlrev_b32_e32 v188, 16, v205
	v_and_b32_e32 v189, 0xffff0000, v205
	s_waitcnt lgkmcnt(0)
	v_add_f32_e32 v169, v134, v135
	v_lshl_add_u64 v[134:135], v[128:129], 0, s[4:5]
	s_mov_b32 s4, 0x40000
	v_add_co_u32_e32 v136, vcc, s4, v128
	global_load_dwordx4 v[202:205], v[134:135], off offset:256
	s_nop 0
	v_addc_co_u32_e32 v137, vcc, 0, v129, vcc
	global_load_dwordx4 v[138:141], v[136:137], off
	v_pk_add_f32 v[192:193], v[72:73], v[192:193]
	v_pk_add_f32 v[200:201], v[78:79], v[200:201]
	v_pk_add_f32 v[190:191], v[70:71], v[190:191]
	v_pk_add_f32 v[188:189], v[66:67], v[188:189]
	s_mov_b64 s[4:5], 0x48000
	ds_bpermute_b32 v227, v225, v169
	s_waitcnt vmcnt(1)
	v_lshlrev_b32_e32 v176, 16, v203
	v_and_b32_e32 v177, 0xffff0000, v203
	v_lshlrev_b32_e32 v142, 16, v205
	s_waitcnt vmcnt(0)
; __device__ __forceinline__ unsigned cvt_pk_bf16(float lo, float hi) { unsigned r; asm volatile("v_cvt_pk_bf16_f32 %0, %1, %2" : "=v"(r) : "v"(lo), "v"(hi)); return r; }
; template <bool RD32>
; __device__ __forceinline__ void res_rows(const float* __restrict__ xold32, const bf16_t* __restrict__ xoldb, bf16_t* __restrict__ xb, float* __restrict__ ssq, const f32x4 (&acc)[2][2][4][2], int row0, int col0, int slot) {
;     ...
;     for (int bj = 0; bj < 2; ++bj) ld((size_t)row0 * D + col0 + bj * HALF, xo[0][bj][0], xo[0][bj][1]);
; #pragma unroll
;     for (int idx = 0; idx < 8; ++idx) {
;         const int ai = idx >> 2, m = idx & 3; const int r = row0 + ai * HALF + m * 16; const size_t off = (size_t)r * D + col0;
;         if (idx < 7) { const int ai2 = (idx + 1) >> 2, m2 = (idx + 1) & 3; const size_t off2 = (size_t)(row0 + ai2 * HALF + m2 * 16) * D + col0;
; #pragma unroll
;             for (int bj = 0; bj < 2; ++bj) ld(off2 + bj * HALF, xo[(idx + 1) & 1][bj][0], xo[(idx + 1) & 1][bj][1]); }
;         float ss = 0.f;
; #pragma unroll
;         for (int bj = 0; bj < 2; ++bj) { const f32x4 x0 = xo[idx & 1][bj][0] + acc[ai][bj][m][0], x1 = xo[idx & 1][bj][1] + acc[ai][bj][m][1];
;             u32x4 w; w.x = cvt_pk_bf16(x0[0], x0[1]); w.y = cvt_pk_bf16(x0[2], x0[3]); w.z = cvt_pk_bf16(x1[0], x1[1]); w.w = cvt_pk_bf16(x1[2], x1[3]);
;             *(u32x4*)(xb + off + bj * HALF) = w;
;             ss += ((x0[0] * x0[0] + x0[1] * x0[1]) + (x0[2] * x0[2] + x0[3] * x0[3])) + ((x1[0] * x1[0] + x1[1] * x1[1]) + (x1[2] * x1[2] + x1[3] * x1[3])); }
;         ss += __shfl_xor(ss, 16); ss += __shfl_xor(ss, 32);
;         ssv[idx] = ss;
;     }
	v_lshlrev_b32_e32 v180, 16, v138
	v_and_b32_e32 v181, 0xffff0000, v138
	v_lshlrev_b32_e32 v194, 16, v139
	v_and_b32_e32 v195, 0xffff0000, v139
	v_lshlrev_b32_e32 v178, 16, v140
	v_and_b32_e32 v179, 0xffff0000, v140
	v_lshlrev_b32_e32 v182, 16, v141
	v_and_b32_e32 v183, 0xffff0000, v141
	v_lshlrev_b32_e32 v140, 16, v202
	v_and_b32_e32 v141, 0xffff0000, v202
	v_lshlrev_b32_e32 v138, 16, v204
	v_and_b32_e32 v139, 0xffff0000, v204
	v_and_b32_e32 v143, 0xffff0000, v205
	v_pk_add_f32 v[202:203], v[76:77], v[196:197]
	v_pk_add_f32 v[204:205], v[74:75], v[198:199]
	v_cvt_pk_bf16_f32 v196, v202, v203
	v_cvt_pk_bf16_f32 v197, v200, v201
	v_cvt_pk_bf16_f32 v198, v192, v193
	v_mul_f32_e32 v193, v193, v193
	v_cvt_pk_bf16_f32 v199, v204, v205
	global_store_dwordx4 v[130:131], v[196:199], off sc1
	v_fmac_f32_e32 v193, v192, v192
	v_mul_f32_e32 v192, v205, v205
	v_mul_f32_e32 v196, v203, v203
	v_mul_f32_e32 v197, v201, v201
	v_fmac_f32_e32 v196, v202, v202
	v_fmac_f32_e32 v197, v200, v200
	v_fmac_f32_e32 v192, v204, v204
	v_add_f32_e32 v196, v196, v197
	v_add_f32_e32 v192, v193, v192
	v_add_f32_e32 v198, v196, v192
	v_pk_add_f32 v[192:193], v[68:69], v[186:187]
	v_pk_add_f32 v[196:197], v[64:65], v[184:185]
	v_cvt_pk_bf16_f32 v184, v192, v193
	v_cvt_pk_bf16_f32 v185, v190, v191
	v_pk_add_f32 v[182:183], v[58:59], v[182:183]
	v_cvt_pk_bf16_f32 v186, v196, v197
	v_cvt_pk_bf16_f32 v187, v188, v189
	global_store_dwordx4 v[130:131], v[184:187], off offset:256 sc1
	v_mul_f32_e32 v130, v193, v193
	v_mul_f32_e32 v131, v191, v191
	v_fmac_f32_e32 v130, v192, v192
	v_fmac_f32_e32 v131, v190, v190
	v_add_f32_e32 v130, v130, v131
	v_mul_f32_e32 v131, v197, v197
	v_mul_f32_e32 v184, v189, v189
	v_fmac_f32_e32 v131, v196, v196
	v_fmac_f32_e32 v184, v188, v188
	v_add_f32_e32 v131, v131, v184
	v_add_f32_e32 v130, v130, v131
	v_add_f32_e32 v130, v198, v130
	ds_bpermute_b32 v131, v152, v130
	v_pk_add_f32 v[184:185], v[62:63], v[194:195]
	v_pk_add_f32 v[194:195], v[60:61], v[180:181]
	v_pk_add_f32 v[176:177], v[54:55], v[176:177]
	v_pk_add_f32 v[140:141], v[52:53], v[140:141]
	s_waitcnt lgkmcnt(0)
	v_add_f32_e32 v228, v130, v131
	v_lshl_add_u64 v[130:131], v[128:129], 0, s[4:5]
	s_mov_b32 s4, 0x48000
	v_add_co_u32_e32 v186, vcc, s4, v128
	global_load_dwordx4 v[230:233], v[130:131], off offset:256
	s_nop 0
	v_addc_co_u32_e32 v187, vcc, 0, v129, vcc
	global_load_dwordx4 v[188:191], v[186:187], off
	v_pk_add_f32 v[142:143], v[50:51], v[142:143]
	s_mov_b64 s[4:5], 0x50000
	ds_bpermute_b32 v229, v225, v228
	s_waitcnt vmcnt(1)
	v_lshlrev_b32_e32 v196, 16, v231
	v_and_b32_e32 v197, 0xffff0000, v231
	v_lshlrev_b32_e32 v192, 16, v233
	s_waitcnt vmcnt(0)
	v_lshlrev_b32_e32 v198, 16, v190
	v_and_b32_e32 v199, 0xffff0000, v190
	v_lshlrev_b32_e32 v202, 16, v191
	v_and_b32_e32 v203, 0xffff0000, v191
	v_lshlrev_b32_e32 v190, 16, v230
	v_and_b32_e32 v191, 0xffff0000, v230
	v_pk_add_f32 v[230:231], v[56:57], v[178:179]
	v_cvt_pk_bf16_f32 v178, v194, v195
	v_cvt_pk_bf16_f32 v179, v184, v185
	v_lshlrev_b32_e32 v200, 16, v188
	v_cvt_pk_bf16_f32 v180, v230, v231
	v_cvt_pk_bf16_f32 v181, v182, v183
	global_store_dwordx4 v[136:137], v[178:181], off sc1
	v_mul_f32_e32 v136, v195, v195
	v_mul_f32_e32 v137, v185, v185
	v_fmac_f32_e32 v136, v194, v194
	v_fmac_f32_e32 v137, v184, v184
	v_add_f32_e32 v136, v136, v137
	v_mul_f32_e32 v137, v231, v231
	v_mul_f32_e32 v178, v183, v183
	v_fmac_f32_e32 v137, v230, v230
	v_fmac_f32_e32 v178, v182, v182
	v_add_f32_e32 v137, v137, v178
	v_add_f32_e32 v180, v136, v137
	v_pk_add_f32 v[178:179], v[48:49], v[138:139]
	v_cvt_pk_bf16_f32 v136, v140, v141
	v_cvt_pk_bf16_f32 v137, v176, v177
	v_and_b32_e32 v201, 0xffff0000, v188
	v_cvt_pk_bf16_f32 v138, v178, v179
	v_cvt_pk_bf16_f32 v139, v142, v143
	global_store_dwordx4 v[134:135], v[136:139], off offset:256 sc1
	v_mul_f32_e32 v134, v141, v141
	v_mul_f32_e32 v135, v177, v177
	v_fmac_f32_e32 v134, v140, v140
	v_fmac_f32_e32 v135, v176, v176
	v_add_f32_e32 v134, v134, v135
	v_mul_f32_e32 v135, v179, v179
	v_mul_f32_e32 v136, v143, v143
	v_fmac_f32_e32 v135, v178, v178
	v_fmac_f32_e32 v136, v142, v142
	v_add_f32_e32 v135, v135, v136
	v_add_f32_e32 v134, v134, v135
	v_add_f32_e32 v134, v180, v134
	ds_bpermute_b32 v135, v152, v134
	v_lshlrev_b32_e32 v204, 16, v189
	v_and_b32_e32 v205, 0xffff0000, v189
	v_lshlrev_b32_e32 v188, 16, v232
	v_and_b32_e32 v189, 0xffff0000, v232
	s_waitcnt lgkmcnt(0)
	v_add_f32_e32 v230, v134, v135
	v_lshl_add_u64 v[134:135], v[128:129], 0, s[4:5]
	s_mov_b32 s4, 0x50000
	v_add_co_u32_e32 v136, vcc, s4, v128
	v_and_b32_e32 v193, 0xffff0000, v233
	s_nop 0
	v_addc_co_u32_e32 v137, vcc, 0, v129, vcc
	global_load_dwordx4 v[176:179], v[136:137], off
	global_load_dwordx4 v[232:235], v[134:135], off offset:256
	v_pk_add_f32 v[194:195], v[46:47], v[204:205]
	v_pk_add_f32 v[204:205], v[44:45], v[200:201]
	v_pk_add_f32 v[202:203], v[42:43], v[202:203]
	v_pk_add_f32 v[190:191], v[36:37], v[190:191]
	v_pk_add_f32 v[192:193], v[34:35], v[192:193]
	s_mov_b64 s[4:5], 0x58000
	ds_bpermute_b32 v231, v225, v230
	s_waitcnt vmcnt(1)
	v_lshlrev_b32_e32 v140, 16, v176
	s_waitcnt vmcnt(0)
; __device__ __forceinline__ unsigned cvt_pk_bf16(float lo, float hi) { unsigned r; asm volatile("v_cvt_pk_bf16_f32 %0, %1, %2" : "=v"(r) : "v"(lo), "v"(hi)); return r; }
; template <bool RD32>
; __device__ __forceinline__ void res_rows(const float* __restrict__ xold32, const bf16_t* __restrict__ xoldb, bf16_t* __restrict__ xb, float* __restrict__ ssq, const f32x4 (&acc)[2][2][4][2], int row0, int col0, int slot) {
;     ...
;     for (int bj = 0; bj < 2; ++bj) ld((size_t)row0 * D + col0 + bj * HALF, xo[0][bj][0], xo[0][bj][1]);
; #pragma unroll
;     for (int idx = 0; idx < 8; ++idx) {
;         const int ai = idx >> 2, m = idx & 3; const int r = row0 + ai * HALF + m * 16; const size_t off = (size_t)r * D + col0;
;         if (idx < 7) { const int ai2 = (idx + 1) >> 2, m2 = (idx + 1) & 3; const size_t off2 = (size_t)(row0 + ai2 * HALF + m2 * 16) * D + col0;
; #pragma unroll
;             for (int bj = 0; bj < 2; ++bj) ld(off2 + bj * HALF, xo[(idx + 1) & 1][bj][0], xo[(idx + 1) & 1][bj][1]); }
;         float ss = 0.f;
; #pragma unroll
;         for (int bj = 0; bj < 2; ++bj) { const f32x4 x0 = xo[idx & 1][bj][0] + acc[ai][bj][m][0], x1 = xo[idx & 1][bj][1] + acc[ai][bj][m][1];
;             u32x4 w; w.x = cvt_pk_bf16(x0[0], x0[1]); w.y = cvt_pk_bf16(x0[2], x0[3]); w.z = cvt_pk_bf16(x1[0], x1[1]); w.w = cvt_pk_bf16(x1[2], x1[3]);
;             *(u32x4*)(xb + off + bj * HALF) = w;
;             ss += ((x0[0] * x0[0] + x0[1] * x0[1]) + (x0[2] * x0[2] + x0[3] * x0[3])) + ((x1[0] * x1[0] + x1[1] * x1[1]) + (x1[2] * x1[2] + x1[3] * x1[3])); }
;         ss += __shfl_xor(ss, 16); ss += __shfl_xor(ss, 32);
;         ssv[idx] = ss;
;     }
;     const int fq = slot >> 6;
; #pragma unroll
;     for (int j = 0; j < 2; ++j) { const float v = fq == 0 ? ssv[j] : fq == 1 ? ssv[2 + j] : fq == 2 ? ssv[4 + j] : ssv[6 + j]; const int idx = 2 * fq + j;
;         ssq[(size_t)(row0 + (idx >> 2) * HALF + (idx & 3) * 16) * 16 + (slot & 15)] = v; }
	v_lshlrev_b32_e32 v180, 16, v232
	v_and_b32_e32 v181, 0xffff0000, v232
	v_lshlrev_b32_e32 v184, 16, v233
	v_and_b32_e32 v185, 0xffff0000, v233
	v_pk_add_f32 v[232:233], v[40:41], v[198:199]
	v_cvt_pk_bf16_f32 v198, v204, v205
	v_cvt_pk_bf16_f32 v199, v194, v195
	v_and_b32_e32 v141, 0xffff0000, v176
	v_cvt_pk_bf16_f32 v200, v232, v233
	v_cvt_pk_bf16_f32 v201, v202, v203
	global_store_dwordx4 v[186:187], v[198:201], off sc1
	v_mul_f32_e32 v186, v205, v205
	v_mul_f32_e32 v187, v195, v195
	v_fmac_f32_e32 v186, v204, v204
	v_fmac_f32_e32 v187, v194, v194
	v_add_f32_e32 v186, v186, v187
	v_mul_f32_e32 v187, v233, v233
	v_mul_f32_e32 v194, v203, v203
	v_fmac_f32_e32 v187, v232, v232
	v_fmac_f32_e32 v194, v202, v202
	v_add_f32_e32 v187, v187, v194
	v_pk_add_f32 v[194:195], v[38:39], v[196:197]
	v_add_f32_e32 v198, v186, v187
	v_pk_add_f32 v[196:197], v[32:33], v[188:189]
	v_cvt_pk_bf16_f32 v186, v190, v191
	v_cvt_pk_bf16_f32 v187, v194, v195
	v_lshlrev_b32_e32 v176, 16, v177
	v_cvt_pk_bf16_f32 v188, v196, v197
	v_cvt_pk_bf16_f32 v189, v192, v193
	global_store_dwordx4 v[130:131], v[186:189], off offset:256 sc1
	v_mul_f32_e32 v130, v191, v191
	v_mul_f32_e32 v131, v195, v195
	v_fmac_f32_e32 v130, v190, v190
	v_fmac_f32_e32 v131, v194, v194
	v_add_f32_e32 v130, v130, v131
	v_mul_f32_e32 v131, v197, v197
	v_mul_f32_e32 v186, v193, v193
	v_fmac_f32_e32 v131, v196, v196
	v_fmac_f32_e32 v186, v192, v192
	v_add_f32_e32 v131, v131, v186
	v_add_f32_e32 v130, v130, v131
	v_add_f32_e32 v130, v198, v130
	ds_bpermute_b32 v131, v152, v130
	v_lshl_add_u64 v[186:187], v[128:129], 0, s[4:5]
	s_mov_b32 s4, 0x58000
	v_add_co_u32_e32 v188, vcc, s4, v128
	s_waitcnt lgkmcnt(0)
	v_add_f32_e32 v198, v130, v131
	v_addc_co_u32_e32 v189, vcc, 0, v129, vcc
	global_load_dwordx4 v[128:131], v[188:189], off
	v_and_b32_e32 v177, 0xffff0000, v177
	v_lshlrev_b32_e32 v138, 16, v178
	v_and_b32_e32 v139, 0xffff0000, v178
	v_lshlrev_b32_e32 v142, 16, v179
	v_and_b32_e32 v143, 0xffff0000, v179
	v_pk_add_f32 v[176:177], v[30:31], v[176:177]
	v_pk_add_f32 v[140:141], v[28:29], v[140:141]
	v_pk_add_f32 v[142:143], v[26:27], v[142:143]
	v_pk_add_f32 v[138:139], v[24:25], v[138:139]
	v_lshlrev_b32_e32 v178, 16, v234
	v_and_b32_e32 v179, 0xffff0000, v234
	v_lshlrev_b32_e32 v182, 16, v235
	v_and_b32_e32 v183, 0xffff0000, v235
	ds_bpermute_b32 v199, v225, v198
	v_cmp_lt_u32_e32 vcc, 63, v222
	s_waitcnt vmcnt(0)
	v_lshlrev_b32_e32 v192, 16, v128
	v_and_b32_e32 v193, 0xffff0000, v128
	v_lshlrev_b32_e32 v196, 16, v129
	v_and_b32_e32 v197, 0xffff0000, v129
	v_lshlrev_b32_e32 v190, 16, v130
	v_and_b32_e32 v191, 0xffff0000, v130
	v_lshlrev_b32_e32 v194, 16, v131
	v_and_b32_e32 v195, 0xffff0000, v131
	global_load_dwordx4 v[128:131], v[186:187], off offset:256
	s_waitcnt vmcnt(0)
	v_lshlrev_b32_e32 v200, 16, v128
	v_and_b32_e32 v201, 0xffff0000, v128
	v_lshlrev_b32_e32 v202, 16, v129
	v_and_b32_e32 v203, 0xffff0000, v129
	v_cvt_pk_bf16_f32 v128, v140, v141
	v_cvt_pk_bf16_f32 v129, v176, v177
	v_lshlrev_b32_e32 v204, 16, v130
	v_and_b32_e32 v205, 0xffff0000, v130
	v_lshlrev_b32_e32 v232, 16, v131
	v_and_b32_e32 v233, 0xffff0000, v131
	v_cvt_pk_bf16_f32 v130, v138, v139
	v_cvt_pk_bf16_f32 v131, v142, v143
	global_store_dwordx4 v[136:137], v[128:131], off sc1
	v_pk_add_f32 v[136:137], v[22:23], v[184:185]
	s_nop 0
	v_mul_f32_e32 v128, v141, v141
	v_mul_f32_e32 v129, v177, v177
	v_fmac_f32_e32 v128, v140, v140
	v_fmac_f32_e32 v129, v176, v176
	v_add_f32_e32 v128, v128, v129
	v_mul_f32_e32 v129, v139, v139
	v_mul_f32_e32 v130, v143, v143
	v_fmac_f32_e32 v129, v138, v138
	v_fmac_f32_e32 v130, v142, v142
	v_add_f32_e32 v129, v129, v130
	v_add_f32_e32 v176, v128, v129
	v_pk_add_f32 v[138:139], v[20:21], v[180:181]
	v_pk_add_f32 v[140:141], v[18:19], v[182:183]
	v_cvt_pk_bf16_f32 v128, v138, v139
	v_cvt_pk_bf16_f32 v129, v136, v137
	v_pk_add_f32 v[142:143], v[16:17], v[178:179]
	s_nop 0
	v_cvt_pk_bf16_f32 v130, v142, v143
	v_cvt_pk_bf16_f32 v131, v140, v141
	global_store_dwordx4 v[134:135], v[128:131], off offset:256 sc1
	s_nop 1
	v_mul_f32_e32 v128, v139, v139
	v_mul_f32_e32 v129, v137, v137
	v_fmac_f32_e32 v128, v138, v138
	v_fmac_f32_e32 v129, v136, v136
	v_add_f32_e32 v128, v128, v129
	v_mul_f32_e32 v129, v143, v143
	v_mul_f32_e32 v130, v141, v141
	v_fmac_f32_e32 v129, v142, v142
	v_fmac_f32_e32 v130, v140, v140
	v_add_f32_e32 v129, v129, v130
	v_add_f32_e32 v128, v128, v129
	v_add_f32_e32 v128, v176, v128
	ds_bpermute_b32 v129, v152, v128
	v_pk_add_f32 v[130:131], v[14:15], v[196:197]
	v_pk_add_f32 v[140:141], v[12:13], v[192:193]
	v_pk_add_f32 v[142:143], v[10:11], v[194:195]
	v_cvt_pk_bf16_f32 v136, v140, v141
	s_waitcnt lgkmcnt(0)
	v_add_f32_e32 v129, v128, v129
	v_cvt_pk_bf16_f32 v137, v130, v131
	v_mul_f32_e32 v128, v141, v141
	v_mul_f32_e32 v131, v131, v131
	v_pk_add_f32 v[176:177], v[8:9], v[190:191]
	v_fmac_f32_e32 v128, v140, v140
	v_fmac_f32_e32 v131, v130, v130
	v_add_f32_e32 v128, v128, v131
	v_mul_f32_e32 v130, v177, v177
	v_mul_f32_e32 v131, v143, v143
	v_fmac_f32_e32 v130, v176, v176
	v_fmac_f32_e32 v131, v142, v142
	v_add_f32_e32 v130, v130, v131
	v_add_f32_e32 v128, v128, v130
	v_pk_add_f32 v[130:131], v[6:7], v[202:203]
	v_pk_add_f32 v[140:141], v[4:5], v[200:201]
	v_cvt_pk_bf16_f32 v138, v176, v177
	v_cvt_pk_bf16_f32 v139, v142, v143
	global_store_dwordx4 v[188:189], v[136:139], off sc1
	v_mul_f32_e32 v134, v141, v141
	v_pk_add_f32 v[142:143], v[2:3], v[232:233]
	v_cvt_pk_bf16_f32 v136, v140, v141
	v_cvt_pk_bf16_f32 v137, v130, v131
	v_mul_f32_e32 v131, v131, v131
	v_pk_add_f32 v[176:177], v[0:1], v[204:205]
	v_fmac_f32_e32 v134, v140, v140
	v_fmac_f32_e32 v131, v130, v130
	v_add_f32_e32 v130, v134, v131
	v_mul_f32_e32 v131, v177, v177
	v_mul_f32_e32 v134, v143, v143
	v_fmac_f32_e32 v131, v176, v176
	v_fmac_f32_e32 v134, v142, v142
	v_add_f32_e32 v131, v131, v134
	v_add_f32_e32 v130, v130, v131
	v_add_f32_e32 v128, v128, v130
	ds_bpermute_b32 v130, v152, v128
	v_cvt_pk_bf16_f32 v138, v176, v177
	v_cvt_pk_bf16_f32 v139, v142, v143
	global_store_dwordx4 v[186:187], v[136:139], off offset:256 sc1
	ds_bpermute_b32 v135, v225, v129
	s_waitcnt lgkmcnt(1)
	v_add_f32_e32 v136, v128, v130
	ds_bpermute_b32 v137, v225, v136
	v_and_b32_e32 v130, 15, v223
	v_and_b32_e32 v128, 0xffffff80, v222
	v_lshlrev_b32_e32 v152, 2, v130
	v_add_u32_e32 v128, v166, v128
	v_lshl_add_u64 v[130:131], s[18:19], 0, v[152:153]
	s_and_saveexec_b64 s[4:5], vcc
	s_xor_b64 s[24:25], exec, s[4:5]
	s_cbranch_execz .LBB0_433
	v_ashrrev_i32_e32 v138, 6, v222
	v_cmp_lt_i32_e32 vcc, 1, v138
	s_mov_b64 s[36:37], 0
	s_and_saveexec_b64 s[4:5], vcc
	s_xor_b64 s[38:39], exec, s[4:5]
	s_cbranch_execnz .LBB0_454
	s_or_saveexec_b64 s[38:39], s[38:39]
	v_cmp_ne_u32_e32 vcc, 1, v138
	s_xor_b64 exec, exec, s[38:39]
	s_cbranch_execnz .LBB0_457

; __device__ __forceinline__ unsigned cvt_pk_bf16(float lo, float hi) { unsigned r; asm volatile("v_cvt_pk_bf16_f32 %0, %1, %2" : "=v"(r) : "v"(lo), "v"(hi)); return r; }
; __device__ __forceinline__ float bflo(unsigned w) { return __uint_as_float(w << 16); }
; __device__ __forceinline__ float bfhi(unsigned w) { return __uint_as_float(w & 0xffff0000u); }
; template <bool RD32>
; __device__ __forceinline__ void res_rows(const float* __restrict__ xold32, const bf16_t* __restrict__ xoldb, bf16_t* __restrict__ xb, float* __restrict__ ssq, const f32x4 (&acc)[2][2][4][2], int row0, int col0, int slot) {
;     f32x4 xo[2][2][2];
;     float ssv[8];
;     auto ld = [&](size_t o, f32x4& a, f32x4& b) { if (RD32) { a = *(const f32x4*)(xold32 + o); b = *(const f32x4*)(xold32 + o + 4); }
;         else { const u32x4 w = *(const u32x4*)(xoldb + o); a = (f32x4){bflo(w.x), bfhi(w.x), bflo(w.y), bfhi(w.y)}; b = (f32x4){bflo(w.z), bfhi(w.z), bflo(w.w), bfhi(w.w)}; } };
; #pragma unroll
;     for (int bj = 0; bj < 2; ++bj) ld((size_t)row0 * D + col0 + bj * HALF, xo[0][bj][0], xo[0][bj][1]);
; #pragma unroll
;     for (int idx = 0; idx < 8; ++idx) {
;         const int ai = idx >> 2, m = idx & 3; const int r = row0 + ai * HALF + m * 16; const size_t off = (size_t)r * D + col0;
;         if (idx < 7) { const int ai2 = (idx + 1) >> 2, m2 = (idx + 1) & 3; const size_t off2 = (size_t)(row0 + ai2 * HALF + m2 * 16) * D + col0;
; #pragma unroll
;             for (int bj = 0; bj < 2; ++bj) ld(off2 + bj * HALF, xo[(idx + 1) & 1][bj][0], xo[(idx + 1) & 1][bj][1]); }
;         float ss = 0.f;
; #pragma unroll
;         for (int bj = 0; bj < 2; ++bj) { const f32x4 x0 = xo[idx & 1][bj][0] + acc[ai][bj][m][0], x1 = xo[idx & 1][bj][1] + acc[ai][bj][m][1];
;             u32x4 w; w.x = cvt_pk_bf16(x0[0], x0[1]); w.y = cvt_pk_bf16(x0[2], x0[3]); w.z = cvt_pk_bf16(x1[0], x1[1]); w.w = cvt_pk_bf16(x1[2], x1[3]);
;             *(u32x4*)(xb + off + bj * HALF) = w;
;             ss += ((x0[0] * x0[0] + x0[1] * x0[1]) + (x0[2] * x0[2] + x0[3] * x0[3])) + ((x1[0] * x1[0] + x1[1] * x1[1]) + (x1[2] * x1[2] + x1[3] * x1[3])); }
;         ss += __shfl_xor(ss, 16); ss += __shfl_xor(ss, 32);
;         ssv[idx] = ss;
;     }
.LBB0_436:
.LBB0_437:
	v_readlane_b32 s4, v248, 0
	v_lshlrev_b64 v[128:129], 12, v[166:167]
	v_readlane_b32 s5, v248, 1
	v_lshlrev_b64 v[130:131], 2, v[132:133]
	v_ashrrev_i32_e32 v173, 31, v172
	v_lshl_add_u64 v[128:129], s[4:5], 0, v[128:129]
	v_lshl_add_u64 v[128:129], v[128:129], 0, v[130:131]
	global_load_dwordx4 v[180:183], v[128:129], off offset:16
	global_load_dwordx4 v[184:187], v[128:129], off
	global_load_dwordx4 v[188:191], v[128:129], off offset:528
	global_load_dwordx4 v[192:195], v[128:129], off offset:512
	v_lshl_add_u64 v[178:179], s[4:5], 0, v[130:131]
	v_lshlrev_b64 v[128:129], 12, v[172:173]
	v_lshl_add_u64 v[176:177], v[132:133], 1, s[58:59]
	v_lshl_add_u64 v[132:133], v[178:179], 0, v[128:129]
	s_waitcnt lgkmcnt(0)
	global_load_dwordx4 v[136:139], v[132:133], off offset:16
	global_load_dwordx4 v[140:143], v[132:133], off
	global_load_dwordx4 v[128:131], v[132:133], off offset:528
	s_nop 0
	global_load_dwordx4 v[132:135], v[132:133], off offset:512
	v_lshl_add_u64 v[174:175], v[176:177], 0, v[174:175]
	v_ashrrev_i32_e32 v171, 31, v170
	v_lshlrev_b64 v[172:173], 11, v[172:173]
	v_lshl_add_u64 v[172:173], v[176:177], 0, v[172:173]
	v_ashrrev_i32_e32 v169, 31, v168
	v_readlane_b32 s18, v248, 14
	v_readlane_b32 s19, v248, 15
	v_readlane_b32 s18, v246, 41
	v_readlane_b32 s19, v246, 42
	v_readlane_b32 s6, v248, 2
	v_readlane_b32 s7, v248, 3
	v_readlane_b32 s8, v248, 4
	v_readlane_b32 s9, v248, 5
	v_readlane_b32 s10, v248, 6
	v_readlane_b32 s11, v248, 7
	v_readlane_b32 s12, v248, 8
	v_readlane_b32 s13, v248, 9
	v_readlane_b32 s14, v248, 10
	v_readlane_b32 s15, v248, 11
	v_readlane_b32 s16, v248, 12
	v_readlane_b32 s17, v248, 13
	s_waitcnt vmcnt(0)
	v_pk_add_f32 v[180:181], v[120:121], v[180:181]
	v_pk_add_f32 v[126:127], v[126:127], v[186:187]
	v_pk_add_f32 v[124:125], v[124:125], v[184:185]
	v_pk_add_f32 v[182:183], v[122:123], v[182:183]
	v_cvt_pk_bf16_f32 v120, v124, v125
	v_cvt_pk_bf16_f32 v121, v126, v127
	v_cvt_pk_bf16_f32 v122, v180, v181
	v_pk_add_f32 v[118:119], v[118:119], v[194:195]
	v_cvt_pk_bf16_f32 v123, v182, v183
	global_store_dwordx4 v[174:175], v[120:123], off sc1
	v_pk_add_f32 v[116:117], v[116:117], v[192:193]
	v_pk_add_f32 v[110:111], v[110:111], v[142:143]
	v_mul_f32_e32 v120, v125, v125
	v_mul_f32_e32 v121, v127, v127
	v_fmac_f32_e32 v120, v124, v124
	v_fmac_f32_e32 v121, v126, v126
	v_add_f32_e32 v120, v120, v121
	v_mul_f32_e32 v121, v181, v181
	v_mul_f32_e32 v122, v183, v183
	v_fmac_f32_e32 v121, v180, v180
	v_fmac_f32_e32 v122, v182, v182
	v_add_f32_e32 v121, v121, v122
	v_pk_add_f32 v[122:123], v[112:113], v[188:189]
	v_cvt_pk_bf16_f32 v112, v116, v117
	v_cvt_pk_bf16_f32 v113, v118, v119
	v_add_f32_e32 v124, v120, v121
	v_pk_add_f32 v[120:121], v[114:115], v[190:191]
	v_cvt_pk_bf16_f32 v114, v122, v123
	v_pk_add_f32 v[108:109], v[108:109], v[140:141]
	v_cvt_pk_bf16_f32 v115, v120, v121
	global_store_dwordx4 v[174:175], v[112:115], off offset:256 sc1
	v_pk_add_f32 v[136:137], v[104:105], v[136:137]
	v_pk_add_f32 v[138:139], v[106:107], v[138:139]
	v_mul_f32_e32 v112, v117, v117
	v_mul_f32_e32 v113, v119, v119
	v_fmac_f32_e32 v112, v116, v116
	v_fmac_f32_e32 v113, v118, v118
	v_add_f32_e32 v112, v112, v113
	v_mul_f32_e32 v113, v123, v123
	v_mul_f32_e32 v114, v121, v121
	v_fmac_f32_e32 v113, v122, v122
	v_fmac_f32_e32 v114, v120, v120
	v_add_f32_e32 v113, v113, v114
	v_and_b32_e32 v114, 64, v209
	v_add_f32_e32 v112, v112, v113
	v_xor_b32_e32 v113, 16, v209
	v_add_u32_e32 v114, 64, v114
	v_cmp_lt_i32_e32 vcc, v113, v114
	v_add_f32_e32 v112, v124, v112
	v_pk_add_f32 v[102:103], v[102:103], v[134:135]
	v_cndmask_b32_e32 v113, v209, v113, vcc
	v_lshlrev_b32_e32 v152, 2, v113
	ds_bpermute_b32 v113, v152, v112
	v_pk_add_f32 v[100:101], v[100:101], v[132:133]
	s_waitcnt lgkmcnt(0)
	v_add_f32_e32 v174, v112, v113
	v_xor_b32_e32 v112, 32, v209
	v_cmp_lt_i32_e32 vcc, v112, v114
	s_nop 1
	v_cndmask_b32_e32 v112, v209, v112, vcc
	v_lshlrev_b32_e32 v180, 2, v112
	v_lshlrev_b64 v[112:113], 12, v[170:171]
	v_lshl_add_u64 v[116:117], v[178:179], 0, v[112:113]
	global_load_dwordx4 v[120:123], v[116:117], off offset:16
	global_load_dwordx4 v[124:127], v[116:117], off
	global_load_dwordx4 v[112:115], v[116:117], off offset:528
	s_nop 0
	global_load_dwordx4 v[116:119], v[116:117], off offset:512
	v_cvt_pk_bf16_f32 v104, v108, v109
	v_cvt_pk_bf16_f32 v105, v110, v111
	v_cvt_pk_bf16_f32 v106, v136, v137
	v_cvt_pk_bf16_f32 v107, v138, v139
	global_store_dwordx4 v[172:173], v[104:107], off sc1
	ds_bpermute_b32 v175, v180, v174
	v_cmp_lt_u32_e32 vcc, 63, v222
	v_mul_f32_e32 v104, v109, v109
	v_mul_f32_e32 v105, v111, v111
	v_fmac_f32_e32 v104, v108, v108
	v_fmac_f32_e32 v105, v110, v110
	v_add_f32_e32 v104, v104, v105
	v_mul_f32_e32 v105, v137, v137
	v_mul_f32_e32 v106, v139, v139
	v_fmac_f32_e32 v105, v136, v136
	v_fmac_f32_e32 v106, v138, v138
	v_add_f32_e32 v105, v105, v106
	v_pk_add_f32 v[106:107], v[96:97], v[128:129]
	v_cvt_pk_bf16_f32 v96, v100, v101
	v_cvt_pk_bf16_f32 v97, v102, v103
	v_add_f32_e32 v108, v104, v105
	v_pk_add_f32 v[104:105], v[98:99], v[130:131]
	v_cvt_pk_bf16_f32 v98, v106, v107
	v_lshlrev_b64 v[130:131], 11, v[170:171]
	v_cvt_pk_bf16_f32 v99, v104, v105
	global_store_dwordx4 v[172:173], v[96:99], off offset:256 sc1
	v_lshl_add_u64 v[130:131], v[176:177], 0, v[130:131]
	s_waitcnt vmcnt(5)
	v_pk_add_f32 v[120:121], v[88:89], v[120:121]
	v_mul_f32_e32 v96, v101, v101
	v_mul_f32_e32 v97, v103, v103
	v_fmac_f32_e32 v96, v100, v100
	v_fmac_f32_e32 v97, v102, v102
	v_add_f32_e32 v96, v96, v97
	v_mul_f32_e32 v97, v107, v107
	v_mul_f32_e32 v98, v105, v105
	v_fmac_f32_e32 v97, v106, v106
	v_fmac_f32_e32 v98, v104, v104
	v_add_f32_e32 v97, v97, v98
	v_add_f32_e32 v96, v96, v97
	v_add_f32_e32 v96, v108, v96
	ds_bpermute_b32 v97, v152, v96
	s_waitcnt vmcnt(4)
; __device__ __forceinline__ unsigned cvt_pk_bf16(float lo, float hi) { unsigned r; asm volatile("v_cvt_pk_bf16_f32 %0, %1, %2" : "=v"(r) : "v"(lo), "v"(hi)); return r; }
; template <bool RD32>
; __device__ __forceinline__ void res_rows(const float* __restrict__ xold32, const bf16_t* __restrict__ xoldb, bf16_t* __restrict__ xb, float* __restrict__ ssq, const f32x4 (&acc)[2][2][4][2], int row0, int col0, int slot) {
;     ...
;     for (int bj = 0; bj < 2; ++bj) ld((size_t)row0 * D + col0 + bj * HALF, xo[0][bj][0], xo[0][bj][1]);
; #pragma unroll
;     for (int idx = 0; idx < 8; ++idx) {
;         const int ai = idx >> 2, m = idx & 3; const int r = row0 + ai * HALF + m * 16; const size_t off = (size_t)r * D + col0;
;         if (idx < 7) { const int ai2 = (idx + 1) >> 2, m2 = (idx + 1) & 3; const size_t off2 = (size_t)(row0 + ai2 * HALF + m2 * 16) * D + col0;
; #pragma unroll
;             for (int bj = 0; bj < 2; ++bj) ld(off2 + bj * HALF, xo[(idx + 1) & 1][bj][0], xo[(idx + 1) & 1][bj][1]); }
;         float ss = 0.f;
; #pragma unroll
;         for (int bj = 0; bj < 2; ++bj) { const f32x4 x0 = xo[idx & 1][bj][0] + acc[ai][bj][m][0], x1 = xo[idx & 1][bj][1] + acc[ai][bj][m][1];
;             u32x4 w; w.x = cvt_pk_bf16(x0[0], x0[1]); w.y = cvt_pk_bf16(x0[2], x0[3]); w.z = cvt_pk_bf16(x1[0], x1[1]); w.w = cvt_pk_bf16(x1[2], x1[3]);
;             *(u32x4*)(xb + off + bj * HALF) = w;
;             ss += ((x0[0] * x0[0] + x0[1] * x0[1]) + (x0[2] * x0[2] + x0[3] * x0[3])) + ((x1[0] * x1[0] + x1[1] * x1[1]) + (x1[2] * x1[2] + x1[3] * x1[3])); }
;         ss += __shfl_xor(ss, 16); ss += __shfl_xor(ss, 32);
;         ssv[idx] = ss;
;     }
	v_pk_add_f32 v[94:95], v[94:95], v[126:127]
	v_pk_add_f32 v[92:93], v[92:93], v[124:125]
	v_pk_add_f32 v[122:123], v[90:91], v[122:123]
	s_waitcnt vmcnt(2)
	v_pk_add_f32 v[86:87], v[86:87], v[118:119]
	s_waitcnt lgkmcnt(0)
	v_add_f32_e32 v129, v96, v97
	v_lshlrev_b64 v[96:97], 12, v[168:169]
	v_lshl_add_u64 v[100:101], v[178:179], 0, v[96:97]
	global_load_dwordx4 v[104:107], v[100:101], off offset:16
	global_load_dwordx4 v[108:111], v[100:101], off
	global_load_dwordx4 v[96:99], v[100:101], off offset:528
	s_nop 0
	global_load_dwordx4 v[100:103], v[100:101], off offset:512
	v_cvt_pk_bf16_f32 v88, v92, v93
	v_cvt_pk_bf16_f32 v89, v94, v95
	v_cvt_pk_bf16_f32 v90, v120, v121
	v_cvt_pk_bf16_f32 v91, v122, v123
	global_store_dwordx4 v[130:131], v[88:91], off sc1
	v_pk_add_f32 v[84:85], v[84:85], v[116:117]
	v_lshlrev_b64 v[116:117], 11, v[168:169]
	v_mul_f32_e32 v88, v93, v93
	v_mul_f32_e32 v89, v95, v95
	v_fmac_f32_e32 v88, v92, v92
	v_fmac_f32_e32 v89, v94, v94
	v_add_f32_e32 v88, v88, v89
	v_mul_f32_e32 v89, v121, v121
	v_mul_f32_e32 v90, v123, v123
	v_fmac_f32_e32 v89, v120, v120
	v_fmac_f32_e32 v90, v122, v122
	v_add_f32_e32 v89, v89, v90
	v_pk_add_f32 v[90:91], v[80:81], v[112:113]
	v_cvt_pk_bf16_f32 v80, v84, v85
	v_cvt_pk_bf16_f32 v81, v86, v87
	v_add_f32_e32 v92, v88, v89
	v_pk_add_f32 v[88:89], v[82:83], v[114:115]
	v_cvt_pk_bf16_f32 v82, v90, v91
	v_add_u32_e32 v112, 0x80, v166
	v_cvt_pk_bf16_f32 v83, v88, v89
	global_store_dwordx4 v[130:131], v[80:83], off offset:256 sc1
	v_ashrrev_i32_e32 v113, 31, v112
	v_lshl_add_u64 v[116:117], v[176:177], 0, v[116:117]
	v_mul_f32_e32 v80, v85, v85
	v_mul_f32_e32 v81, v87, v87
	v_fmac_f32_e32 v80, v84, v84
	v_fmac_f32_e32 v81, v86, v86
	v_add_f32_e32 v80, v80, v81
	v_mul_f32_e32 v81, v91, v91
	v_mul_f32_e32 v82, v89, v89
	v_fmac_f32_e32 v81, v90, v90
	v_fmac_f32_e32 v82, v88, v88
	v_add_f32_e32 v81, v81, v82
	v_add_f32_e32 v80, v80, v81
	v_add_f32_e32 v80, v92, v80
	ds_bpermute_b32 v81, v152, v80
	ds_bpermute_b32 v132, v180, v129
	s_waitcnt lgkmcnt(1)
	v_add_f32_e32 v114, v80, v81
	v_lshlrev_b64 v[80:81], 12, v[112:113]
	v_lshl_add_u64 v[84:85], v[178:179], 0, v[80:81]
	global_load_dwordx4 v[88:91], v[84:85], off offset:16
	global_load_dwordx4 v[92:95], v[84:85], off
	global_load_dwordx4 v[80:83], v[84:85], off offset:528
	s_nop 0
	global_load_dwordx4 v[84:87], v[84:85], off offset:512
	ds_bpermute_b32 v115, v180, v114
	s_waitcnt vmcnt(9)
	v_pk_add_f32 v[104:105], v[72:73], v[104:105]
	s_waitcnt vmcnt(8)
	v_pk_add_f32 v[78:79], v[78:79], v[110:111]
	v_pk_add_f32 v[76:77], v[76:77], v[108:109]
	v_pk_add_f32 v[106:107], v[74:75], v[106:107]
	v_cvt_pk_bf16_f32 v72, v76, v77
	v_cvt_pk_bf16_f32 v73, v78, v79
	v_cvt_pk_bf16_f32 v74, v104, v105
	s_waitcnt vmcnt(6)
	v_pk_add_f32 v[70:71], v[70:71], v[102:103]
	v_cvt_pk_bf16_f32 v75, v106, v107
	global_store_dwordx4 v[116:117], v[72:75], off sc1
	v_pk_add_f32 v[68:69], v[68:69], v[100:101]
	s_waitcnt vmcnt(4)
	v_pk_add_f32 v[88:89], v[56:57], v[88:89]
	v_mul_f32_e32 v72, v77, v77
	v_mul_f32_e32 v73, v79, v79
	v_fmac_f32_e32 v72, v76, v76
	v_fmac_f32_e32 v73, v78, v78
	v_add_f32_e32 v72, v72, v73
	v_mul_f32_e32 v73, v105, v105
	v_mul_f32_e32 v74, v107, v107
	v_fmac_f32_e32 v73, v104, v104
	v_fmac_f32_e32 v74, v106, v106
	v_add_f32_e32 v73, v73, v74
	v_pk_add_f32 v[74:75], v[64:65], v[96:97]
	v_cvt_pk_bf16_f32 v64, v68, v69
	v_cvt_pk_bf16_f32 v65, v70, v71
	v_add_f32_e32 v76, v72, v73
	v_pk_add_f32 v[72:73], v[66:67], v[98:99]
	v_cvt_pk_bf16_f32 v66, v74, v75
	v_add_u32_e32 v96, 0x90, v166
	v_cvt_pk_bf16_f32 v67, v72, v73
	global_store_dwordx4 v[116:117], v[64:67], off offset:256 sc1
	v_ashrrev_i32_e32 v97, 31, v96
	v_lshlrev_b64 v[98:99], 11, v[112:113]
	v_mul_f32_e32 v64, v69, v69
	v_mul_f32_e32 v65, v71, v71
	v_fmac_f32_e32 v64, v68, v68
	v_fmac_f32_e32 v65, v70, v70
	v_add_f32_e32 v64, v64, v65
	v_mul_f32_e32 v65, v75, v75
	v_mul_f32_e32 v66, v73, v73
	v_fmac_f32_e32 v65, v74, v74
	v_fmac_f32_e32 v66, v72, v72
	v_add_f32_e32 v65, v65, v66
	v_add_f32_e32 v64, v64, v65
	v_add_f32_e32 v64, v76, v64
	ds_bpermute_b32 v65, v152, v64
	v_lshl_add_u64 v[98:99], v[176:177], 0, v[98:99]
	s_waitcnt vmcnt(4)
	v_pk_add_f32 v[62:63], v[62:63], v[94:95]
	v_pk_add_f32 v[60:61], v[60:61], v[92:93]
	v_pk_add_f32 v[90:91], v[58:59], v[90:91]
	s_waitcnt lgkmcnt(0)
	v_add_f32_e32 v100, v64, v65
	v_lshlrev_b64 v[64:65], 12, v[96:97]
	v_lshl_add_u64 v[68:69], v[178:179], 0, v[64:65]
	global_load_dwordx4 v[72:75], v[68:69], off offset:16
	global_load_dwordx4 v[76:79], v[68:69], off
	global_load_dwordx4 v[64:67], v[68:69], off offset:528
	s_nop 0
	global_load_dwordx4 v[68:71], v[68:69], off offset:512
	v_cvt_pk_bf16_f32 v56, v60, v61
	v_cvt_pk_bf16_f32 v57, v62, v63
	v_cvt_pk_bf16_f32 v58, v88, v89
	v_cvt_pk_bf16_f32 v59, v90, v91
	global_store_dwordx4 v[98:99], v[56:59], off sc1
	s_waitcnt vmcnt(7)
	v_pk_add_f32 v[54:55], v[54:55], v[86:87]
	v_pk_add_f32 v[52:53], v[52:53], v[84:85]
	v_mul_f32_e32 v56, v61, v61
	v_mul_f32_e32 v57, v63, v63
	v_fmac_f32_e32 v56, v60, v60
	v_fmac_f32_e32 v57, v62, v62
	v_add_f32_e32 v56, v56, v57
	v_mul_f32_e32 v57, v89, v89
	v_mul_f32_e32 v58, v91, v91
	v_fmac_f32_e32 v57, v88, v88
	v_fmac_f32_e32 v58, v90, v90
	v_add_f32_e32 v57, v57, v58
	v_pk_add_f32 v[58:59], v[48:49], v[80:81]
	v_cvt_pk_bf16_f32 v48, v52, v53
	v_cvt_pk_bf16_f32 v49, v54, v55
	v_add_f32_e32 v60, v56, v57
	v_pk_add_f32 v[56:57], v[50:51], v[82:83]
	v_cvt_pk_bf16_f32 v50, v58, v59
	v_add_u32_e32 v80, 0xa0, v166
	v_cvt_pk_bf16_f32 v51, v56, v57
	global_store_dwordx4 v[98:99], v[48:51], off offset:256 sc1
	v_ashrrev_i32_e32 v81, 31, v80
	v_lshlrev_b64 v[84:85], 11, v[96:97]
	v_mul_f32_e32 v48, v53, v53
	v_mul_f32_e32 v49, v55, v55
	v_fmac_f32_e32 v48, v52, v52
	v_fmac_f32_e32 v49, v54, v54
	v_add_f32_e32 v48, v48, v49
	v_mul_f32_e32 v49, v59, v59
	v_mul_f32_e32 v50, v57, v57
	v_fmac_f32_e32 v49, v58, v58
	v_fmac_f32_e32 v50, v56, v56
	v_add_f32_e32 v49, v49, v50
	v_add_f32_e32 v48, v48, v49
	v_add_f32_e32 v48, v60, v48
	ds_bpermute_b32 v49, v152, v48
	v_lshl_add_u64 v[84:85], v[176:177], 0, v[84:85]
	ds_bpermute_b32 v101, v180, v100
	s_waitcnt lgkmcnt(1)
; __device__ __forceinline__ unsigned cvt_pk_bf16(float lo, float hi) { unsigned r; asm volatile("v_cvt_pk_bf16_f32 %0, %1, %2" : "=v"(r) : "v"(lo), "v"(hi)); return r; }
; template <bool RD32>
; __device__ __forceinline__ void res_rows(const float* __restrict__ xold32, const bf16_t* __restrict__ xoldb, bf16_t* __restrict__ xb, float* __restrict__ ssq, const f32x4 (&acc)[2][2][4][2], int row0, int col0, int slot) {
;     ...
;     for (int bj = 0; bj < 2; ++bj) ld((size_t)row0 * D + col0 + bj * HALF, xo[0][bj][0], xo[0][bj][1]);
; #pragma unroll
;     for (int idx = 0; idx < 8; ++idx) {
;         const int ai = idx >> 2, m = idx & 3; const int r = row0 + ai * HALF + m * 16; const size_t off = (size_t)r * D + col0;
;         if (idx < 7) { const int ai2 = (idx + 1) >> 2, m2 = (idx + 1) & 3; const size_t off2 = (size_t)(row0 + ai2 * HALF + m2 * 16) * D + col0;
; #pragma unroll
;             for (int bj = 0; bj < 2; ++bj) ld(off2 + bj * HALF, xo[(idx + 1) & 1][bj][0], xo[(idx + 1) & 1][bj][1]); }
;         float ss = 0.f;
; #pragma unroll
;         for (int bj = 0; bj < 2; ++bj) { const f32x4 x0 = xo[idx & 1][bj][0] + acc[ai][bj][m][0], x1 = xo[idx & 1][bj][1] + acc[ai][bj][m][1];
;             u32x4 w; w.x = cvt_pk_bf16(x0[0], x0[1]); w.y = cvt_pk_bf16(x0[2], x0[3]); w.z = cvt_pk_bf16(x1[0], x1[1]); w.w = cvt_pk_bf16(x1[2], x1[3]);
;             *(u32x4*)(xb + off + bj * HALF) = w;
;             ss += ((x0[0] * x0[0] + x0[1] * x0[1]) + (x0[2] * x0[2] + x0[3] * x0[3])) + ((x1[0] * x1[0] + x1[1] * x1[1]) + (x1[2] * x1[2] + x1[3] * x1[3])); }
;         ss += __shfl_xor(ss, 16); ss += __shfl_xor(ss, 32);
;         ssv[idx] = ss;
;     }
;     const int fq = slot >> 6;
; #pragma unroll
;     for (int j = 0; j < 2; ++j) { const float v = fq == 0 ? ssv[j] : fq == 1 ? ssv[2 + j] : fq == 2 ? ssv[4 + j] : ssv[6 + j]; const int idx = 2 * fq + j;
;         ssq[(size_t)(row0 + (idx >> 2) * HALF + (idx & 3) * 16) * 16 + (slot & 15)] = v; }
	v_add_f32_e32 v82, v48, v49
	v_lshlrev_b64 v[48:49], 12, v[80:81]
	v_lshl_add_u64 v[60:61], v[178:179], 0, v[48:49]
	global_load_dwordx4 v[48:51], v[60:61], off offset:16
	global_load_dwordx4 v[52:55], v[60:61], off
	global_load_dwordx4 v[56:59], v[60:61], off offset:528
	s_nop 0
	global_load_dwordx4 v[60:63], v[60:61], off offset:512
	ds_bpermute_b32 v83, v180, v82
	s_waitcnt vmcnt(9)
	v_pk_add_f32 v[72:73], v[40:41], v[72:73]
	s_waitcnt vmcnt(8)
	v_pk_add_f32 v[46:47], v[46:47], v[78:79]
	v_pk_add_f32 v[44:45], v[44:45], v[76:77]
	v_pk_add_f32 v[74:75], v[42:43], v[74:75]
	v_cvt_pk_bf16_f32 v40, v44, v45
	v_cvt_pk_bf16_f32 v41, v46, v47
	v_cvt_pk_bf16_f32 v42, v72, v73
	s_waitcnt vmcnt(6)
	v_pk_add_f32 v[38:39], v[38:39], v[70:71]
	v_cvt_pk_bf16_f32 v43, v74, v75
	global_store_dwordx4 v[84:85], v[40:43], off sc1
	v_pk_add_f32 v[36:37], v[36:37], v[68:69]
	v_lshlrev_b64 v[68:69], 11, v[80:81]
	v_mul_f32_e32 v40, v45, v45
	v_mul_f32_e32 v41, v47, v47
	v_fmac_f32_e32 v40, v44, v44
	v_fmac_f32_e32 v41, v46, v46
	v_add_f32_e32 v40, v40, v41
	v_mul_f32_e32 v41, v73, v73
	v_mul_f32_e32 v42, v75, v75
	v_fmac_f32_e32 v41, v72, v72
	v_fmac_f32_e32 v42, v74, v74
	v_add_f32_e32 v41, v41, v42
	v_pk_add_f32 v[42:43], v[32:33], v[64:65]
	v_cvt_pk_bf16_f32 v32, v36, v37
	v_cvt_pk_bf16_f32 v33, v38, v39
	v_add_f32_e32 v44, v40, v41
	v_pk_add_f32 v[40:41], v[34:35], v[66:67]
	v_cvt_pk_bf16_f32 v34, v42, v43
	v_lshl_add_u64 v[68:69], v[176:177], 0, v[68:69]
	v_cvt_pk_bf16_f32 v35, v40, v41
	global_store_dwordx4 v[84:85], v[32:35], off offset:256 sc1
	s_waitcnt vmcnt(5)
	v_pk_add_f32 v[48:49], v[24:25], v[48:49]
	v_mul_f32_e32 v32, v37, v37
	v_mul_f32_e32 v33, v39, v39
	v_fmac_f32_e32 v32, v36, v36
	v_fmac_f32_e32 v33, v38, v38
	v_add_f32_e32 v32, v32, v33
	v_mul_f32_e32 v33, v43, v43
	v_mul_f32_e32 v34, v41, v41
	v_fmac_f32_e32 v33, v42, v42
	v_fmac_f32_e32 v34, v40, v40
	v_add_f32_e32 v33, v33, v34
	v_add_f32_e32 v32, v32, v33
	v_add_f32_e32 v32, v44, v32
	ds_bpermute_b32 v33, v152, v32
	v_add_u32_e32 v44, 0xb0, v166
	v_ashrrev_i32_e32 v45, 31, v44
	s_waitcnt vmcnt(4)
	v_pk_add_f32 v[30:31], v[30:31], v[54:55]
	v_pk_add_f32 v[28:29], v[28:29], v[52:53]
	s_waitcnt lgkmcnt(0)
	v_add_f32_e32 v46, v32, v33
	v_lshlrev_b64 v[32:33], 12, v[44:45]
	v_lshl_add_u64 v[64:65], v[178:179], 0, v[32:33]
	global_load_dwordx4 v[36:39], v[64:65], off offset:16
	global_load_dwordx4 v[40:43], v[64:65], off
	global_load_dwordx4 v[32:35], v[64:65], off offset:528
	s_nop 0
	global_load_dwordx4 v[64:67], v[64:65], off offset:512
	v_cvt_pk_bf16_f32 v24, v28, v29
	v_cvt_pk_bf16_f32 v25, v30, v31
	v_pk_add_f32 v[50:51], v[26:27], v[50:51]
	v_cvt_pk_bf16_f32 v26, v48, v49
	s_waitcnt vmcnt(6)
	v_pk_add_f32 v[22:23], v[22:23], v[62:63]
	v_cvt_pk_bf16_f32 v27, v50, v51
	global_store_dwordx4 v[68:69], v[24:27], off sc1
	v_pk_add_f32 v[20:21], v[20:21], v[60:61]
	ds_bpermute_b32 v47, v180, v46
	v_mul_f32_e32 v24, v29, v29
	v_mul_f32_e32 v25, v31, v31
	v_fmac_f32_e32 v24, v28, v28
	v_fmac_f32_e32 v25, v30, v30
	v_add_f32_e32 v24, v24, v25
	v_mul_f32_e32 v25, v49, v49
	v_mul_f32_e32 v26, v51, v51
	v_fmac_f32_e32 v25, v48, v48
	v_fmac_f32_e32 v26, v50, v50
	v_add_f32_e32 v25, v25, v26
	v_pk_add_f32 v[26:27], v[16:17], v[56:57]
	v_cvt_pk_bf16_f32 v16, v20, v21
	v_cvt_pk_bf16_f32 v17, v22, v23
	v_add_f32_e32 v28, v24, v25
	v_pk_add_f32 v[24:25], v[18:19], v[58:59]
	v_cvt_pk_bf16_f32 v18, v26, v27
	s_waitcnt vmcnt(3)
	v_pk_add_f32 v[14:15], v[14:15], v[42:43]
	v_cvt_pk_bf16_f32 v19, v24, v25
	global_store_dwordx4 v[68:69], v[16:19], off offset:256 sc1
	v_pk_add_f32 v[12:13], v[12:13], v[40:41]
	s_waitcnt vmcnt(2)
	v_pk_add_f32 v[6:7], v[6:7], v[66:67]
	v_mul_f32_e32 v16, v21, v21
	v_mul_f32_e32 v17, v23, v23
	v_fmac_f32_e32 v16, v20, v20
	v_fmac_f32_e32 v17, v22, v22
	v_add_f32_e32 v16, v16, v17
	v_mul_f32_e32 v17, v27, v27
	v_mul_f32_e32 v18, v25, v25
	v_fmac_f32_e32 v17, v26, v26
	v_fmac_f32_e32 v18, v24, v24
	v_add_f32_e32 v17, v17, v18
	v_lshlrev_b64 v[18:19], 11, v[44:45]
	v_lshl_add_u64 v[18:19], v[176:177], 0, v[18:19]
	v_pk_add_f32 v[22:23], v[8:9], v[36:37]
	v_cvt_pk_bf16_f32 v8, v12, v13
	v_cvt_pk_bf16_f32 v9, v14, v15
	v_pk_add_f32 v[20:21], v[10:11], v[38:39]
	v_cvt_pk_bf16_f32 v10, v22, v23
	v_pk_add_f32 v[4:5], v[4:5], v[64:65]
	v_cvt_pk_bf16_f32 v11, v20, v21
	global_store_dwordx4 v[18:19], v[8:11], off sc1
	v_add_f32_e32 v16, v16, v17
	v_add_f32_e32 v16, v28, v16
	v_mul_f32_e32 v8, v13, v13
	v_mul_f32_e32 v9, v15, v15
	v_fmac_f32_e32 v8, v12, v12
	v_fmac_f32_e32 v9, v14, v14
	v_add_f32_e32 v8, v8, v9
	v_mul_f32_e32 v9, v23, v23
	v_mul_f32_e32 v10, v21, v21
	v_fmac_f32_e32 v9, v22, v22
	v_fmac_f32_e32 v10, v20, v20
	v_add_f32_e32 v9, v9, v10
	v_pk_add_f32 v[10:11], v[0:1], v[32:33]
	v_cvt_pk_bf16_f32 v0, v4, v5
	v_cvt_pk_bf16_f32 v1, v6, v7
	v_add_f32_e32 v12, v8, v9
	v_pk_add_f32 v[8:9], v[2:3], v[34:35]
	v_cvt_pk_bf16_f32 v2, v10, v11
	ds_bpermute_b32 v17, v152, v16
	v_cvt_pk_bf16_f32 v3, v8, v9
	global_store_dwordx4 v[18:19], v[0:3], off offset:256 sc1
	s_waitcnt lgkmcnt(0)
	v_add_f32_e32 v16, v16, v17
	v_mul_f32_e32 v0, v5, v5
	v_mul_f32_e32 v1, v7, v7
	v_fmac_f32_e32 v0, v4, v4
	v_fmac_f32_e32 v1, v6, v6
	v_add_f32_e32 v0, v0, v1
	v_mul_f32_e32 v1, v11, v11
	v_mul_f32_e32 v2, v9, v9
	v_fmac_f32_e32 v1, v10, v10
	v_fmac_f32_e32 v2, v8, v8
	v_add_f32_e32 v1, v1, v2
	v_add_f32_e32 v0, v0, v1
	v_add_f32_e32 v0, v12, v0
	ds_bpermute_b32 v1, v152, v0
	ds_bpermute_b32 v17, v180, v16
	v_and_b32_e32 v2, 0xffffff80, v222
	v_add_u32_e32 v128, v166, v2
	v_and_b32_e32 v2, 15, v223
	s_waitcnt lgkmcnt(1)
	v_add_f32_e32 v0, v0, v1
	ds_bpermute_b32 v1, v180, v0
	v_lshlrev_b32_e32 v152, 2, v2
	v_lshl_add_u64 v[130:131], s[18:19], 0, v[152:153]
	s_and_saveexec_b64 s[4:5], vcc
	s_xor_b64 s[24:25], exec, s[4:5]
	s_cbranch_execz .LBB0_448
	v_ashrrev_i32_e32 v2, 6, v222
	v_cmp_lt_i32_e32 vcc, 1, v2
	s_mov_b64 s[36:37], 0
	s_and_saveexec_b64 s[4:5], vcc
	s_xor_b64 s[38:39], exec, s[4:5]
	s_cbranch_execnz .LBB0_461
	s_or_saveexec_b64 s[38:39], s[38:39]
	v_cmp_ne_u32_e32 vcc, 1, v2
	s_xor_b64 exec, exec, s[38:39]
	s_cbranch_execnz .LBB0_464

; __device__ __forceinline__ unsigned cvt_pk_bf16(float lo, float hi) { unsigned r; asm volatile("v_cvt_pk_bf16_f32 %0, %1, %2" : "=v"(r) : "v"(lo), "v"(hi)); return r; }
;     __device__ __forceinline__ void operator()(const f32x4 (&acc)[2][2][4][2], const Unit& u, int wr, int wc, int fr, int fq) const {
;     ...
;                 const int r = row0 + ai * HALF + m * 16; const float rs = rsv[ai][m];
;                 bf16_t* rowp = H + (size_t)r * FF + u.pn * BM + wc * 32 + 8 * fq;
; #pragma unroll
;                 for (int bj = 0; bj < 2; ++bj) { f32x4 v0 = acc[ai][bj][m][0] * rs, v1 = acc[ai][bj][m][1] * rs;
; #pragma unroll
;                     for (int j = 0; j < 4; ++j) { const float a = fmaxf(v0[j], 0.f), b = fmaxf(v1[j], 0.f); v0[j] = a * a; v1[j] = b * b; }
;                     u32x4 w; w.x = cvt_pk_bf16(v0[0], v0[1]); w.y = cvt_pk_bf16(v0[2], v0[3]); w.z = cvt_pk_bf16(v1[0], v1[1]); w.w = cvt_pk_bf16(v1[2], v1[3]);
;                     *(u32x4*)(rowp + bj * HALF) = w; }
.LBB0_543:
	s_lshl_b32 s14, s65, 8
	s_ashr_i32 s15, s14, 31
	v_lshlrev_b64 v[134:135], 13, v[184:185]
	v_pk_mul_f32 v[120:121], v[120:121], v[190:191] op_sel_hi:[1,0]
	v_lshl_add_u64 v[134:135], s[60:61], 0, v[134:135]
	s_lshl_b64 s[46:47], s[14:15], 1
	v_pk_mul_f32 v[124:125], v[124:125], v[190:191] op_sel_hi:[1,0]
	v_pk_mul_f32 v[122:123], v[122:123], v[190:191] op_sel_hi:[1,0]
	v_max_f32_e32 v120, 0, v120
	v_lshl_add_u64 v[134:135], v[134:135], 0, s[46:47]
	v_pk_mul_f32 v[126:127], v[126:127], v[190:191] op_sel_hi:[1,0]
	v_mul_f32_e32 v129, v120, v120
	v_max_f32_e32 v120, 0, v125
	v_max_f32_e32 v121, 0, v121
	v_max_f32_e32 v122, 0, v122
	v_lshl_add_u64 v[134:135], v[134:135], 0, s[76:77]
	v_max_f32_e32 v124, 0, v124
	v_mul_f32_e32 v120, v120, v120
	v_mul_f32_e32 v125, v121, v121
	v_max_f32_e32 v121, 0, v126
	v_mul_f32_e32 v126, v122, v122
	v_max_f32_e32 v122, 0, v127
	v_max_f32_e32 v123, 0, v123
	v_pk_mul_f32 v[112:113], v[112:113], v[190:191] op_sel_hi:[1,0]
	v_lshl_add_u64 v[134:135], v[134:135], 0, v[152:153]
	v_mul_f32_e32 v124, v124, v124
	v_mul_f32_e32 v121, v121, v121
	v_mul_f32_e32 v122, v122, v122
	v_mul_f32_e32 v123, v123, v123
	v_cvt_pk_bf16_f32 v120, v124, v120
	v_pk_mul_f32 v[118:119], v[118:119], v[190:191] op_sel_hi:[1,0]
	v_pk_mul_f32 v[116:117], v[116:117], v[190:191] op_sel_hi:[1,0]
	v_pk_mul_f32 v[114:115], v[114:115], v[190:191] op_sel_hi:[1,0]
	v_max_f32_e32 v112, 0, v112
	v_max_f32_e32 v113, 0, v113
	v_cvt_pk_bf16_f32 v121, v121, v122
	v_cvt_pk_bf16_f32 v122, v129, v125
	v_cvt_pk_bf16_f32 v123, v126, v123
	global_store_dwordx4 v[134:135], v[120:123], off sc1
	v_max_f32_e32 v114, 0, v114
	v_max_f32_e32 v116, 0, v116
	v_mul_f32_e32 v120, v112, v112
	v_max_f32_e32 v112, 0, v117
	v_mul_f32_e32 v117, v113, v113
	v_max_f32_e32 v113, 0, v118
	v_mul_f32_e32 v112, v112, v112
	v_mul_f32_e32 v113, v113, v113
	v_mul_f32_e32 v118, v114, v114
	v_max_f32_e32 v114, 0, v119
	v_max_f32_e32 v115, 0, v115
	v_mul_f32_e32 v116, v116, v116
	v_mul_f32_e32 v114, v114, v114
	v_mul_f32_e32 v115, v115, v115
	v_cvt_pk_bf16_f32 v112, v116, v112
	v_cvt_pk_bf16_f32 v113, v113, v114
	v_cvt_pk_bf16_f32 v114, v120, v117
	v_cvt_pk_bf16_f32 v115, v118, v115
	global_store_dwordx4 v[134:135], v[112:115], off offset:256 sc1
	v_pk_mul_f32 v[104:105], v[104:105], v[188:189] op_sel_hi:[1,0]
	v_pk_mul_f32 v[108:109], v[108:109], v[188:189] op_sel_hi:[1,0]
	v_lshlrev_b64 v[112:113], 13, v[182:183]
	v_lshl_add_u64 v[112:113], s[60:61], 0, v[112:113]
	v_pk_mul_f32 v[106:107], v[106:107], v[188:189] op_sel_hi:[1,0]
	v_max_f32_e32 v104, 0, v104
	v_lshl_add_u64 v[112:113], v[112:113], 0, s[46:47]
	v_pk_mul_f32 v[110:111], v[110:111], v[188:189] op_sel_hi:[1,0]
	v_mul_f32_e32 v114, v104, v104
	v_max_f32_e32 v104, 0, v109
	v_max_f32_e32 v105, 0, v105
	v_max_f32_e32 v106, 0, v106
	v_lshl_add_u64 v[112:113], v[112:113], 0, s[76:77]
	v_max_f32_e32 v108, 0, v108
	v_mul_f32_e32 v104, v104, v104
	v_mul_f32_e32 v109, v105, v105
	v_max_f32_e32 v105, 0, v110
	v_mul_f32_e32 v110, v106, v106
	v_max_f32_e32 v106, 0, v111
	v_max_f32_e32 v107, 0, v107
	v_pk_mul_f32 v[96:97], v[96:97], v[188:189] op_sel_hi:[1,0]
	v_lshl_add_u64 v[112:113], v[112:113], 0, v[152:153]
	v_mul_f32_e32 v108, v108, v108
	v_mul_f32_e32 v105, v105, v105
	v_mul_f32_e32 v106, v106, v106
	v_mul_f32_e32 v107, v107, v107
	v_cvt_pk_bf16_f32 v104, v108, v104
	v_pk_mul_f32 v[102:103], v[102:103], v[188:189] op_sel_hi:[1,0]
	v_pk_mul_f32 v[100:101], v[100:101], v[188:189] op_sel_hi:[1,0]
	v_pk_mul_f32 v[98:99], v[98:99], v[188:189] op_sel_hi:[1,0]
	v_max_f32_e32 v96, 0, v96
	v_max_f32_e32 v97, 0, v97
	v_cvt_pk_bf16_f32 v105, v105, v106
	v_cvt_pk_bf16_f32 v106, v114, v109
	v_cvt_pk_bf16_f32 v107, v110, v107
	global_store_dwordx4 v[112:113], v[104:107], off sc1
	v_max_f32_e32 v98, 0, v98
	v_max_f32_e32 v100, 0, v100
	v_mul_f32_e32 v104, v96, v96
	v_max_f32_e32 v96, 0, v101
	v_mul_f32_e32 v101, v97, v97
	v_max_f32_e32 v97, 0, v102
	v_mul_f32_e32 v96, v96, v96
	v_mul_f32_e32 v97, v97, v97
	v_mul_f32_e32 v102, v98, v98
	v_max_f32_e32 v98, 0, v103
	v_max_f32_e32 v99, 0, v99
	v_mul_f32_e32 v100, v100, v100
	v_mul_f32_e32 v98, v98, v98
	v_mul_f32_e32 v99, v99, v99
	v_cvt_pk_bf16_f32 v96, v100, v96
	v_cvt_pk_bf16_f32 v97, v97, v98
	v_cvt_pk_bf16_f32 v98, v104, v101
	v_cvt_pk_bf16_f32 v99, v102, v99
	global_store_dwordx4 v[112:113], v[96:99], off offset:256 sc1
	v_pk_mul_f32 v[88:89], v[88:89], v[146:147] op_sel_hi:[1,0]
	v_pk_mul_f32 v[92:93], v[92:93], v[146:147] op_sel_hi:[1,0]
	v_lshlrev_b64 v[96:97], 13, v[180:181]
	v_lshl_add_u64 v[96:97], s[60:61], 0, v[96:97]
	v_pk_mul_f32 v[90:91], v[90:91], v[146:147] op_sel_hi:[1,0]
	v_max_f32_e32 v88, 0, v88
	v_lshl_add_u64 v[96:97], v[96:97], 0, s[46:47]
	v_pk_mul_f32 v[94:95], v[94:95], v[146:147] op_sel_hi:[1,0]
	v_mul_f32_e32 v98, v88, v88
	v_max_f32_e32 v88, 0, v93
	v_max_f32_e32 v89, 0, v89
	v_max_f32_e32 v90, 0, v90
	v_lshl_add_u64 v[96:97], v[96:97], 0, s[76:77]
	v_max_f32_e32 v92, 0, v92
	v_mul_f32_e32 v88, v88, v88
	v_mul_f32_e32 v93, v89, v89
	v_max_f32_e32 v89, 0, v94
	v_mul_f32_e32 v94, v90, v90
	v_max_f32_e32 v90, 0, v95
	v_max_f32_e32 v91, 0, v91
	v_pk_mul_f32 v[80:81], v[80:81], v[146:147] op_sel_hi:[1,0]
	v_lshl_add_u64 v[96:97], v[96:97], 0, v[152:153]
	v_mul_f32_e32 v92, v92, v92
	v_mul_f32_e32 v89, v89, v89
	v_mul_f32_e32 v90, v90, v90
	v_mul_f32_e32 v91, v91, v91
	v_cvt_pk_bf16_f32 v88, v92, v88
	v_pk_mul_f32 v[86:87], v[86:87], v[146:147] op_sel_hi:[1,0]
	v_pk_mul_f32 v[84:85], v[84:85], v[146:147] op_sel_hi:[1,0]
	v_pk_mul_f32 v[82:83], v[82:83], v[146:147] op_sel_hi:[1,0]
	v_max_f32_e32 v80, 0, v80
	v_max_f32_e32 v81, 0, v81
	v_cvt_pk_bf16_f32 v89, v89, v90
; __device__ __forceinline__ unsigned cvt_pk_bf16(float lo, float hi) { unsigned r; asm volatile("v_cvt_pk_bf16_f32 %0, %1, %2" : "=v"(r) : "v"(lo), "v"(hi)); return r; }
;     __device__ __forceinline__ void operator()(const f32x4 (&acc)[2][2][4][2], const Unit& u, int wr, int wc, int fr, int fq) const {
;     ...
;                 const int r = row0 + ai * HALF + m * 16; const float rs = rsv[ai][m];
;                 bf16_t* rowp = H + (size_t)r * FF + u.pn * BM + wc * 32 + 8 * fq;
; #pragma unroll
;                 for (int bj = 0; bj < 2; ++bj) { f32x4 v0 = acc[ai][bj][m][0] * rs, v1 = acc[ai][bj][m][1] * rs;
; #pragma unroll
;                     for (int j = 0; j < 4; ++j) { const float a = fmaxf(v0[j], 0.f), b = fmaxf(v1[j], 0.f); v0[j] = a * a; v1[j] = b * b; }
;                     u32x4 w; w.x = cvt_pk_bf16(v0[0], v0[1]); w.y = cvt_pk_bf16(v0[2], v0[3]); w.z = cvt_pk_bf16(v1[0], v1[1]); w.w = cvt_pk_bf16(v1[2], v1[3]);
;                     *(u32x4*)(rowp + bj * HALF) = w; }
	v_cvt_pk_bf16_f32 v90, v98, v93
	v_cvt_pk_bf16_f32 v91, v94, v91
	global_store_dwordx4 v[96:97], v[88:91], off sc1
	v_max_f32_e32 v82, 0, v82
	v_max_f32_e32 v84, 0, v84
	v_mul_f32_e32 v88, v80, v80
	v_max_f32_e32 v80, 0, v85
	v_mul_f32_e32 v85, v81, v81
	v_max_f32_e32 v81, 0, v86
	v_mul_f32_e32 v80, v80, v80
	v_mul_f32_e32 v81, v81, v81
	v_mul_f32_e32 v86, v82, v82
	v_max_f32_e32 v82, 0, v87
	v_max_f32_e32 v83, 0, v83
	v_mul_f32_e32 v84, v84, v84
	v_mul_f32_e32 v82, v82, v82
	v_mul_f32_e32 v83, v83, v83
	v_cvt_pk_bf16_f32 v80, v84, v80
	v_cvt_pk_bf16_f32 v81, v81, v82
	v_cvt_pk_bf16_f32 v82, v88, v85
	v_cvt_pk_bf16_f32 v83, v86, v83
	global_store_dwordx4 v[96:97], v[80:83], off offset:256 sc1
	v_pk_mul_f32 v[72:73], v[72:73], v[144:145] op_sel_hi:[1,0]
	v_pk_mul_f32 v[76:77], v[76:77], v[144:145] op_sel_hi:[1,0]
	v_lshlrev_b64 v[80:81], 13, v[178:179]
	v_lshl_add_u64 v[80:81], s[60:61], 0, v[80:81]
	v_pk_mul_f32 v[74:75], v[74:75], v[144:145] op_sel_hi:[1,0]
	v_max_f32_e32 v72, 0, v72
	v_lshl_add_u64 v[80:81], v[80:81], 0, s[46:47]
	v_pk_mul_f32 v[78:79], v[78:79], v[144:145] op_sel_hi:[1,0]
	v_mul_f32_e32 v82, v72, v72
	v_max_f32_e32 v72, 0, v77
	v_max_f32_e32 v73, 0, v73
	v_max_f32_e32 v74, 0, v74
	v_lshl_add_u64 v[80:81], v[80:81], 0, s[76:77]
	v_max_f32_e32 v76, 0, v76
	v_mul_f32_e32 v72, v72, v72
	v_mul_f32_e32 v77, v73, v73
	v_max_f32_e32 v73, 0, v78
	v_mul_f32_e32 v78, v74, v74
	v_max_f32_e32 v74, 0, v79
	v_max_f32_e32 v75, 0, v75
	v_pk_mul_f32 v[64:65], v[64:65], v[144:145] op_sel_hi:[1,0]
	v_lshl_add_u64 v[80:81], v[80:81], 0, v[152:153]
	v_mul_f32_e32 v76, v76, v76
	v_mul_f32_e32 v73, v73, v73
	v_mul_f32_e32 v74, v74, v74
	v_mul_f32_e32 v75, v75, v75
	v_cvt_pk_bf16_f32 v72, v76, v72
	v_pk_mul_f32 v[70:71], v[70:71], v[144:145] op_sel_hi:[1,0]
	v_pk_mul_f32 v[68:69], v[68:69], v[144:145] op_sel_hi:[1,0]
	v_pk_mul_f32 v[66:67], v[66:67], v[144:145] op_sel_hi:[1,0]
	v_max_f32_e32 v64, 0, v64
	v_max_f32_e32 v65, 0, v65
	v_cvt_pk_bf16_f32 v73, v73, v74
	v_cvt_pk_bf16_f32 v74, v82, v77
	v_cvt_pk_bf16_f32 v75, v78, v75
	global_store_dwordx4 v[80:81], v[72:75], off sc1
	v_max_f32_e32 v66, 0, v66
	v_max_f32_e32 v68, 0, v68
	v_mul_f32_e32 v72, v64, v64
	v_max_f32_e32 v64, 0, v69
	v_mul_f32_e32 v69, v65, v65
	v_max_f32_e32 v65, 0, v70
	v_mul_f32_e32 v64, v64, v64
	v_mul_f32_e32 v65, v65, v65
	v_mul_f32_e32 v70, v66, v66
	v_max_f32_e32 v66, 0, v71
	v_max_f32_e32 v67, 0, v67
	v_mul_f32_e32 v68, v68, v68
	v_mul_f32_e32 v66, v66, v66
	v_mul_f32_e32 v67, v67, v67
	v_cvt_pk_bf16_f32 v64, v68, v64
	v_cvt_pk_bf16_f32 v65, v65, v66
	v_cvt_pk_bf16_f32 v66, v72, v69
	v_cvt_pk_bf16_f32 v67, v70, v67
	global_store_dwordx4 v[80:81], v[64:67], off offset:256 sc1
	v_pk_mul_f32 v[56:57], v[56:57], v[138:139] op_sel_hi:[1,0]
	v_pk_mul_f32 v[60:61], v[60:61], v[138:139] op_sel_hi:[1,0]
	v_lshlrev_b64 v[64:65], 13, v[132:133]
	v_lshl_add_u64 v[64:65], s[60:61], 0, v[64:65]
	v_pk_mul_f32 v[58:59], v[58:59], v[138:139] op_sel_hi:[1,0]
	v_max_f32_e32 v56, 0, v56
	v_lshl_add_u64 v[64:65], v[64:65], 0, s[46:47]
	v_pk_mul_f32 v[62:63], v[62:63], v[138:139] op_sel_hi:[1,0]
	v_mul_f32_e32 v66, v56, v56
	v_max_f32_e32 v56, 0, v61
	v_max_f32_e32 v57, 0, v57
	v_max_f32_e32 v58, 0, v58
	v_lshl_add_u64 v[64:65], v[64:65], 0, s[76:77]
	v_max_f32_e32 v60, 0, v60
	v_mul_f32_e32 v56, v56, v56
	v_mul_f32_e32 v61, v57, v57
	v_max_f32_e32 v57, 0, v62
	v_mul_f32_e32 v62, v58, v58
	v_max_f32_e32 v58, 0, v63
	v_max_f32_e32 v59, 0, v59
	v_pk_mul_f32 v[48:49], v[48:49], v[138:139] op_sel_hi:[1,0]
	v_lshl_add_u64 v[64:65], v[64:65], 0, v[152:153]
	v_mul_f32_e32 v60, v60, v60
	v_mul_f32_e32 v57, v57, v57
	v_mul_f32_e32 v58, v58, v58
	v_mul_f32_e32 v59, v59, v59
	v_cvt_pk_bf16_f32 v56, v60, v56
	v_pk_mul_f32 v[54:55], v[54:55], v[138:139] op_sel_hi:[1,0]
	v_pk_mul_f32 v[52:53], v[52:53], v[138:139] op_sel_hi:[1,0]
	v_pk_mul_f32 v[50:51], v[50:51], v[138:139] op_sel_hi:[1,0]
	v_max_f32_e32 v48, 0, v48
	v_max_f32_e32 v49, 0, v49
	v_cvt_pk_bf16_f32 v57, v57, v58
	v_cvt_pk_bf16_f32 v58, v66, v61
	v_cvt_pk_bf16_f32 v59, v62, v59
	global_store_dwordx4 v[64:65], v[56:59], off sc1
	v_max_f32_e32 v50, 0, v50
	v_max_f32_e32 v52, 0, v52
	v_mul_f32_e32 v56, v48, v48
	v_max_f32_e32 v48, 0, v53
	v_mul_f32_e32 v53, v49, v49
	v_max_f32_e32 v49, 0, v54
	v_mul_f32_e32 v48, v48, v48
	v_mul_f32_e32 v49, v49, v49
	v_mul_f32_e32 v54, v50, v50
	v_max_f32_e32 v50, 0, v55
	v_max_f32_e32 v51, 0, v51
	v_mul_f32_e32 v52, v52, v52
	v_mul_f32_e32 v50, v50, v50
	v_mul_f32_e32 v51, v51, v51
	v_cvt_pk_bf16_f32 v48, v52, v48
	v_cvt_pk_bf16_f32 v49, v49, v50
	v_ashrrev_i32_e32 v177, 31, v176
	v_cvt_pk_bf16_f32 v50, v56, v53
	v_cvt_pk_bf16_f32 v51, v54, v51
	global_store_dwordx4 v[64:65], v[48:51], off offset:256 sc1
	v_pk_mul_f32 v[40:41], v[40:41], v[136:137] op_sel_hi:[1,0]
	v_pk_mul_f32 v[44:45], v[44:45], v[136:137] op_sel_hi:[1,0]
	v_lshlrev_b64 v[48:49], 13, v[176:177]
	v_lshl_add_u64 v[48:49], s[60:61], 0, v[48:49]
	v_lshl_add_u64 v[48:49], v[48:49], 0, s[46:47]
	v_lshl_add_u64 v[48:49], v[48:49], 0, s[76:77]
	v_pk_mul_f32 v[42:43], v[42:43], v[136:137] op_sel_hi:[1,0]
	v_max_f32_e32 v40, 0, v40
	v_lshl_add_u64 v[48:49], v[48:49], 0, v[152:153]
	s_mov_b64 s[14:15], 0x20000
	v_pk_mul_f32 v[46:47], v[46:47], v[136:137] op_sel_hi:[1,0]
	v_max_f32_e32 v44, 0, v44
	v_mul_f32_e32 v52, v40, v40
	v_max_f32_e32 v40, 0, v45
	v_max_f32_e32 v41, 0, v41
	v_max_f32_e32 v42, 0, v42
	v_lshl_add_u64 v[50:51], v[48:49], 0, s[14:15]
; __device__ __forceinline__ unsigned cvt_pk_bf16(float lo, float hi) { unsigned r; asm volatile("v_cvt_pk_bf16_f32 %0, %1, %2" : "=v"(r) : "v"(lo), "v"(hi)); return r; }
; #define PG8_BAR __builtin_amdgcn_s_barrier()
; template <class Epi, class Sched, bool ALIGN_EPI = false, bool SP2 = false>
; __device__ __forceinline__ void gemm_phase(LAS unsigned char* lds, const Gemm g, const Sched& S, const Epi& E) {
;     ...
;         if (!has_next) break;
; #pragma unroll
;         for (int a = 0; a < 2; ++a)
; #pragma unroll
;             for (int b = 0; b < 2; ++b)
; #pragma unroll
;                 for (int m = 0; m < 4; ++m)
; #pragma unroll
;                     for (int n = 0; n < 2; ++n) acc[a][b][m][n] = (f32x4){0.f, 0.f, 0.f, 0.f};
;         cur = nxt; cA = nA; cB = nB; ++ui;
;         if constexpr (ALIGN_EPI) { if (wr == 1) PG8_BAR; }
;     __device__ __forceinline__ void operator()(const f32x4 (&acc)[2][2][4][2], const Unit& u, int wr, int wc, int fr, int fq) const {
;     ...
;                 const int r = row0 + ai * HALF + m * 16; const float rs = rsv[ai][m];
;                 bf16_t* rowp = H + (size_t)r * FF + u.pn * BM + wc * 32 + 8 * fq;
; #pragma unroll
;                 for (int bj = 0; bj < 2; ++bj) { f32x4 v0 = acc[ai][bj][m][0] * rs, v1 = acc[ai][bj][m][1] * rs;
; #pragma unroll
;                     for (int j = 0; j < 4; ++j) { const float a = fmaxf(v0[j], 0.f), b = fmaxf(v1[j], 0.f); v0[j] = a * a; v1[j] = b * b; }
;                     u32x4 w; w.x = cvt_pk_bf16(v0[0], v0[1]); w.y = cvt_pk_bf16(v0[2], v0[3]); w.z = cvt_pk_bf16(v1[0], v1[1]); w.w = cvt_pk_bf16(v1[2], v1[3]);
;                     *(u32x4*)(rowp + bj * HALF) = w; }
	v_mul_f32_e32 v44, v44, v44
	v_mul_f32_e32 v40, v40, v40
	v_mul_f32_e32 v45, v41, v41
	v_max_f32_e32 v41, 0, v46
	v_mul_f32_e32 v46, v42, v42
	v_max_f32_e32 v42, 0, v47
	s_mov_b32 s14, 0x20000
	v_mul_f32_e32 v41, v41, v41
	v_max_f32_e32 v43, 0, v43
	v_mul_f32_e32 v42, v42, v42
	v_cvt_pk_bf16_f32 v40, v44, v40
	v_add_co_u32_e32 v44, vcc, s14, v48
	v_pk_mul_f32 v[34:35], v[34:35], v[136:137] op_sel_hi:[1,0]
	v_pk_mul_f32 v[32:33], v[32:33], v[136:137] op_sel_hi:[1,0]
	v_mul_f32_e32 v43, v43, v43
	v_cvt_pk_bf16_f32 v41, v41, v42
	v_cvt_pk_bf16_f32 v42, v52, v45
	v_addc_co_u32_e32 v45, vcc, 0, v49, vcc
	v_pk_mul_f32 v[38:39], v[38:39], v[136:137] op_sel_hi:[1,0]
	v_pk_mul_f32 v[36:37], v[36:37], v[136:137] op_sel_hi:[1,0]
	v_max_f32_e32 v32, 0, v32
	v_max_f32_e32 v33, 0, v33
	v_max_f32_e32 v34, 0, v34
	v_cvt_pk_bf16_f32 v43, v46, v43
	global_store_dwordx4 v[44:45], v[40:43], off sc1
	v_max_f32_e32 v36, 0, v36
	v_max_f32_e32 v35, 0, v35
	v_mul_f32_e32 v40, v32, v32
	v_max_f32_e32 v32, 0, v37
	v_mul_f32_e32 v37, v33, v33
	v_max_f32_e32 v33, 0, v38
	v_mul_f32_e32 v38, v34, v34
	v_max_f32_e32 v34, 0, v39
	v_mul_f32_e32 v32, v32, v32
	v_mul_f32_e32 v33, v33, v33
	v_mul_f32_e32 v34, v34, v34
	v_pk_mul_f32 v[24:25], v[24:25], v[130:131] op_sel_hi:[1,0]
	v_mul_f32_e32 v36, v36, v36
	v_mul_f32_e32 v35, v35, v35
	v_cvt_pk_bf16_f32 v32, v36, v32
	v_cvt_pk_bf16_f32 v33, v33, v34
	v_cvt_pk_bf16_f32 v34, v40, v37
	v_pk_mul_f32 v[28:29], v[28:29], v[130:131] op_sel_hi:[1,0]
	v_pk_mul_f32 v[26:27], v[26:27], v[130:131] op_sel_hi:[1,0]
	v_max_f32_e32 v24, 0, v24
	v_cvt_pk_bf16_f32 v35, v38, v35
	global_store_dwordx4 v[50:51], v[32:35], off offset:256 sc1
	s_mov_b64 s[14:15], 0x40000
	v_pk_mul_f32 v[30:31], v[30:31], v[130:131] op_sel_hi:[1,0]
	v_max_f32_e32 v28, 0, v28
	v_mul_f32_e32 v34, v24, v24
	v_max_f32_e32 v24, 0, v29
	v_max_f32_e32 v25, 0, v25
	v_max_f32_e32 v26, 0, v26
	v_lshl_add_u64 v[32:33], v[48:49], 0, s[14:15]
	v_mul_f32_e32 v28, v28, v28
	v_mul_f32_e32 v24, v24, v24
	v_mul_f32_e32 v29, v25, v25
	v_max_f32_e32 v25, 0, v30
	v_mul_f32_e32 v30, v26, v26
	v_max_f32_e32 v26, 0, v31
	s_mov_b32 s14, 0x40000
	v_mul_f32_e32 v25, v25, v25
	v_max_f32_e32 v27, 0, v27
	v_mul_f32_e32 v26, v26, v26
	v_cvt_pk_bf16_f32 v24, v28, v24
	v_add_co_u32_e32 v28, vcc, s14, v48
	v_pk_mul_f32 v[18:19], v[18:19], v[130:131] op_sel_hi:[1,0]
	v_pk_mul_f32 v[16:17], v[16:17], v[130:131] op_sel_hi:[1,0]
	v_mul_f32_e32 v27, v27, v27
	v_cvt_pk_bf16_f32 v25, v25, v26
	v_cvt_pk_bf16_f32 v26, v34, v29
	v_addc_co_u32_e32 v29, vcc, 0, v49, vcc
	v_pk_mul_f32 v[22:23], v[22:23], v[130:131] op_sel_hi:[1,0]
	v_pk_mul_f32 v[20:21], v[20:21], v[130:131] op_sel_hi:[1,0]
	v_max_f32_e32 v16, 0, v16
	v_max_f32_e32 v17, 0, v17
	v_max_f32_e32 v18, 0, v18
	v_cvt_pk_bf16_f32 v27, v30, v27
	global_store_dwordx4 v[28:29], v[24:27], off sc1
	v_max_f32_e32 v20, 0, v20
	v_max_f32_e32 v19, 0, v19
	v_mul_f32_e32 v24, v16, v16
	v_max_f32_e32 v16, 0, v21
	v_mul_f32_e32 v21, v17, v17
	v_max_f32_e32 v17, 0, v22
	v_mul_f32_e32 v22, v18, v18
	v_max_f32_e32 v18, 0, v23
	v_mul_f32_e32 v16, v16, v16
	v_mul_f32_e32 v17, v17, v17
	v_mul_f32_e32 v18, v18, v18
	v_pk_mul_f32 v[8:9], v[8:9], v[128:129] op_sel_hi:[1,0]
	v_mul_f32_e32 v20, v20, v20
	v_mul_f32_e32 v19, v19, v19
	v_cvt_pk_bf16_f32 v16, v20, v16
	v_cvt_pk_bf16_f32 v17, v17, v18
	v_cvt_pk_bf16_f32 v18, v24, v21
	v_pk_mul_f32 v[12:13], v[12:13], v[128:129] op_sel_hi:[1,0]
	v_pk_mul_f32 v[10:11], v[10:11], v[128:129] op_sel_hi:[1,0]
	v_max_f32_e32 v8, 0, v8
	v_cvt_pk_bf16_f32 v19, v22, v19
	global_store_dwordx4 v[32:33], v[16:19], off offset:256 sc1
	s_mov_b64 s[14:15], 0x60000
	v_pk_mul_f32 v[14:15], v[14:15], v[128:129] op_sel_hi:[1,0]
	v_max_f32_e32 v12, 0, v12
	v_mul_f32_e32 v18, v8, v8
	v_max_f32_e32 v8, 0, v13
	v_max_f32_e32 v9, 0, v9
	v_max_f32_e32 v10, 0, v10
	v_lshl_add_u64 v[16:17], v[48:49], 0, s[14:15]
	v_mul_f32_e32 v12, v12, v12
	v_mul_f32_e32 v8, v8, v8
	v_mul_f32_e32 v13, v9, v9
	v_max_f32_e32 v9, 0, v14
	v_mul_f32_e32 v14, v10, v10
	v_max_f32_e32 v10, 0, v15
	s_mov_b32 s14, 0x60000
	v_mul_f32_e32 v9, v9, v9
	v_max_f32_e32 v11, 0, v11
	v_mul_f32_e32 v10, v10, v10
	v_cvt_pk_bf16_f32 v8, v12, v8
	v_add_co_u32_e32 v12, vcc, s14, v48
	v_pk_mul_f32 v[2:3], v[2:3], v[128:129] op_sel_hi:[1,0]
	v_pk_mul_f32 v[0:1], v[0:1], v[128:129] op_sel_hi:[1,0]
	v_mul_f32_e32 v11, v11, v11
	v_cvt_pk_bf16_f32 v9, v9, v10
	v_cvt_pk_bf16_f32 v10, v18, v13
	v_addc_co_u32_e32 v13, vcc, 0, v49, vcc
	v_pk_mul_f32 v[6:7], v[6:7], v[128:129] op_sel_hi:[1,0]
	v_pk_mul_f32 v[4:5], v[4:5], v[128:129] op_sel_hi:[1,0]
	v_max_f32_e32 v0, 0, v0
	v_max_f32_e32 v1, 0, v1
	v_max_f32_e32 v2, 0, v2
	v_cvt_pk_bf16_f32 v11, v14, v11
	global_store_dwordx4 v[12:13], v[8:11], off sc1
	v_max_f32_e32 v3, 0, v3
	v_max_f32_e32 v4, 0, v4
	v_mul_f32_e32 v8, v0, v0
	v_max_f32_e32 v0, 0, v5
	v_mul_f32_e32 v5, v1, v1
	v_max_f32_e32 v1, 0, v6
	v_mul_f32_e32 v6, v2, v2
	v_max_f32_e32 v2, 0, v7
	v_mul_f32_e32 v0, v0, v0
	v_mul_f32_e32 v1, v1, v1
	v_mul_f32_e32 v2, v2, v2
	v_mul_f32_e32 v3, v3, v3
	s_andn2_b64 vcc, exec, s[44:45]
	s_mov_b64 s[44:45], -1
	v_mul_f32_e32 v4, v4, v4
	v_cvt_pk_bf16_f32 v0, v4, v0
	v_cvt_pk_bf16_f32 v1, v1, v2
	v_cvt_pk_bf16_f32 v2, v8, v5
	v_cvt_pk_bf16_f32 v3, v6, v3
	global_store_dwordx4 v[16:17], v[0:3], off offset:256 sc1
	s_cbranch_vccnz .LBB0_526
	s_andn2_b64 vcc, exec, s[26:27]
	s_cbranch_vccnz .LBB0_525
	s_barrier
	s_branch .LBB0_525

; __device__ __forceinline__ unsigned cvt_pk_bf16(float lo, float hi) { unsigned r; asm volatile("v_cvt_pk_bf16_f32 %0, %1, %2" : "=v"(r) : "v"(lo), "v"(hi)); return r; }
; __device__ __forceinline__ float bflo(unsigned w) { return __uint_as_float(w << 16); }
; __device__ __forceinline__ float bfhi(unsigned w) { return __uint_as_float(w & 0xffff0000u); }
; template <bool RD32>
; __device__ __forceinline__ void res_rows(const float* __restrict__ xold32, const bf16_t* __restrict__ xoldb, bf16_t* __restrict__ xb, float* __restrict__ ssq, const f32x4 (&acc)[2][2][4][2], int row0, int col0, int slot) {
;     f32x4 xo[2][2][2];
;     float ssv[8];
;     auto ld = [&](size_t o, f32x4& a, f32x4& b) { if (RD32) { a = *(const f32x4*)(xold32 + o); b = *(const f32x4*)(xold32 + o + 4); }
;         else { const u32x4 w = *(const u32x4*)(xoldb + o); a = (f32x4){bflo(w.x), bfhi(w.x), bflo(w.y), bfhi(w.y)}; b = (f32x4){bflo(w.z), bfhi(w.z), bflo(w.w), bfhi(w.w)}; } };
; #pragma unroll
;     for (int bj = 0; bj < 2; ++bj) ld((size_t)row0 * D + col0 + bj * HALF, xo[0][bj][0], xo[0][bj][1]);
; #pragma unroll
;     for (int idx = 0; idx < 8; ++idx) {
;         const int ai = idx >> 2, m = idx & 3; const int r = row0 + ai * HALF + m * 16; const size_t off = (size_t)r * D + col0;
;         if (idx < 7) { const int ai2 = (idx + 1) >> 2, m2 = (idx + 1) & 3; const size_t off2 = (size_t)(row0 + ai2 * HALF + m2 * 16) * D + col0;
; #pragma unroll
;             for (int bj = 0; bj < 2; ++bj) ld(off2 + bj * HALF, xo[(idx + 1) & 1][bj][0], xo[(idx + 1) & 1][bj][1]); }
;         float ss = 0.f;
; #pragma unroll
;         for (int bj = 0; bj < 2; ++bj) { const f32x4 x0 = xo[idx & 1][bj][0] + acc[ai][bj][m][0], x1 = xo[idx & 1][bj][1] + acc[ai][bj][m][1];
;             u32x4 w; w.x = cvt_pk_bf16(x0[0], x0[1]); w.y = cvt_pk_bf16(x0[2], x0[3]); w.z = cvt_pk_bf16(x1[0], x1[1]); w.w = cvt_pk_bf16(x1[2], x1[3]);
;             *(u32x4*)(xb + off + bj * HALF) = w;
;             ss += ((x0[0] * x0[0] + x0[1] * x0[1]) + (x0[2] * x0[2] + x0[3] * x0[3])) + ((x1[0] * x1[0] + x1[1] * x1[1]) + (x1[2] * x1[2] + x1[3] * x1[3])); }
;         ss += __shfl_xor(ss, 16); ss += __shfl_xor(ss, 32);
;         ssv[idx] = ss;
;     }
.LBB0_615:
	v_lshl_add_u32 v164, s51, 8, v174
	v_lshl_or_b32 v128, s50, 8, v176
	v_ashrrev_i32_e32 v165, 31, v164
	v_ashrrev_i32_e32 v129, 31, v128
	v_lshlrev_b64 v[166:167], 11, v[164:165]
	v_lshl_add_u64 v[130:131], s[58:59], 0, v[166:167]
	v_lshlrev_b64 v[128:129], 1, v[128:129]
	v_lshl_add_u64 v[130:131], v[130:131], 0, v[128:129]
	global_load_dwordx4 v[136:139], v[130:131], off
	global_load_dwordx4 v[140:143], v[130:131], off offset:256
	v_or_b32_e32 v130, 16, v164
	v_ashrrev_i32_e32 v131, 31, v130
	v_lshl_add_u64 v[168:169], s[58:59], 0, v[128:129]
	v_lshlrev_b64 v[128:129], 11, v[130:131]
	v_lshl_add_u64 v[170:171], v[168:169], 0, v[128:129]
	global_load_dwordx4 v[128:131], v[170:171], off
	global_load_dwordx4 v[132:135], v[170:171], off offset:256
	v_and_b32_e32 v172, 64, v209
	v_xor_b32_e32 v173, 16, v209
	v_add_u32_e32 v194, 64, v172
	v_or_b32_e32 v172, 32, v164
	v_or_b32_e32 v182, 48, v164
	v_cmp_lt_i32_e32 vcc, v173, v194
	v_ashrrev_i32_e32 v183, 31, v182
	v_lshlrev_b64 v[182:183], 11, v[182:183]
	v_cndmask_b32_e32 v180, v209, v173, vcc
	v_ashrrev_i32_e32 v173, 31, v172
	v_lshlrev_b64 v[172:173], 11, v[172:173]
	v_lshl_add_u64 v[166:167], v[168:169], 0, v[166:167]
	v_lshl_add_u64 v[172:173], v[168:169], 0, v[172:173]
	v_lshl_add_u64 v[168:169], v[168:169], 0, v[182:183]
	v_lshlrev_b32_e32 v180, 2, v180
	s_mov_b32 s14, 0x40000
	v_xor_b32_e32 v181, 32, v209
	s_lshl_b32 s29, s50, 2
	v_or_b32_e32 v179, s29, v177
	s_waitcnt vmcnt(0)
	v_lshlrev_b32_e32 v182, 16, v136
	v_and_b32_e32 v183, 0xffff0000, v136
	v_lshlrev_b32_e32 v136, 16, v137
	v_and_b32_e32 v137, 0xffff0000, v137
	v_lshlrev_b32_e32 v184, 16, v138
	v_and_b32_e32 v185, 0xffff0000, v138
	v_lshlrev_b32_e32 v138, 16, v139
	v_and_b32_e32 v139, 0xffff0000, v139
	v_lshlrev_b32_e32 v188, 16, v142
	v_and_b32_e32 v189, 0xffff0000, v142
	v_lshlrev_b32_e32 v142, 16, v143
	v_and_b32_e32 v143, 0xffff0000, v143
	v_lshlrev_b32_e32 v186, 16, v140
	v_and_b32_e32 v187, 0xffff0000, v140
	v_lshlrev_b32_e32 v140, 16, v141
	v_and_b32_e32 v141, 0xffff0000, v141
	v_pk_add_f32 v[126:127], v[126:127], v[136:137]
	v_pk_add_f32 v[124:125], v[124:125], v[182:183]
	v_pk_add_f32 v[136:137], v[122:123], v[138:139]
	v_pk_add_f32 v[138:139], v[120:121], v[184:185]
	v_pk_add_f32 v[142:143], v[110:111], v[142:143]
	v_pk_add_f32 v[184:185], v[108:109], v[188:189]
	v_cvt_pk_bf16_f32 v108, v124, v125
	v_cvt_pk_bf16_f32 v109, v126, v127
	v_cvt_pk_bf16_f32 v110, v138, v139
	v_cvt_pk_bf16_f32 v111, v136, v137
	v_pk_add_f32 v[140:141], v[118:119], v[140:141]
	v_pk_add_f32 v[182:183], v[116:117], v[186:187]
	global_store_dwordx4 v[166:167], v[108:111], off sc1
	v_lshlrev_b32_e32 v190, 16, v128
	v_and_b32_e32 v191, 0xffff0000, v128
	v_cvt_pk_bf16_f32 v108, v182, v183
	v_cvt_pk_bf16_f32 v109, v140, v141
	v_cvt_pk_bf16_f32 v110, v184, v185
	v_cvt_pk_bf16_f32 v111, v142, v143
	global_load_dwordx4 v[116:119], v[172:173], off
	global_load_dwordx4 v[120:123], v[172:173], off offset:256
	v_lshlrev_b32_e32 v128, 16, v129
	v_and_b32_e32 v129, 0xffff0000, v129
	v_lshlrev_b32_e32 v186, 16, v130
	v_and_b32_e32 v187, 0xffff0000, v130
	v_lshlrev_b32_e32 v130, 16, v131
	v_and_b32_e32 v131, 0xffff0000, v131
	v_lshlrev_b32_e32 v188, 16, v132
	v_and_b32_e32 v189, 0xffff0000, v132
	v_lshlrev_b32_e32 v192, 16, v134
	v_and_b32_e32 v193, 0xffff0000, v134
	v_lshlrev_b32_e32 v134, 16, v135
	v_and_b32_e32 v135, 0xffff0000, v135
	v_lshlrev_b32_e32 v132, 16, v133
	v_and_b32_e32 v133, 0xffff0000, v133
	v_pk_add_f32 v[114:115], v[114:115], v[128:129]
	v_pk_add_f32 v[112:113], v[112:113], v[190:191]
	v_pk_add_f32 v[128:129], v[106:107], v[130:131]
	v_pk_add_f32 v[130:131], v[104:105], v[186:187]
	v_pk_add_f32 v[186:187], v[100:101], v[188:189]
	v_pk_add_f32 v[134:135], v[98:99], v[134:135]
	v_pk_add_f32 v[188:189], v[96:97], v[192:193]
	global_store_dwordx4 v[166:167], v[108:111], off offset:256 sc1
	v_cvt_pk_bf16_f32 v96, v112, v113
	v_cvt_pk_bf16_f32 v97, v114, v115
	v_cvt_pk_bf16_f32 v98, v130, v131
	v_cvt_pk_bf16_f32 v99, v128, v129
	v_pk_add_f32 v[132:133], v[102:103], v[132:133]
	global_store_dwordx4 v[170:171], v[96:99], off sc1
	v_mul_f32_e32 v125, v125, v125
	v_mul_f32_e32 v127, v127, v127
	v_cvt_pk_bf16_f32 v96, v186, v187
	v_cvt_pk_bf16_f32 v97, v132, v133
	v_cvt_pk_bf16_f32 v98, v188, v189
	v_cvt_pk_bf16_f32 v99, v134, v135
	global_load_dwordx4 v[100:103], v[168:169], off
	global_load_dwordx4 v[104:107], v[168:169], off offset:256
	v_mul_f32_e32 v139, v139, v139
	v_mul_f32_e32 v137, v137, v137
	v_mul_f32_e32 v183, v183, v183
	v_mul_f32_e32 v141, v141, v141
	v_mul_f32_e32 v185, v185, v185
	v_mul_f32_e32 v143, v143, v143
	v_fmac_f32_e32 v125, v124, v124
	v_fmac_f32_e32 v127, v126, v126
	v_fmac_f32_e32 v139, v138, v138
	v_fmac_f32_e32 v137, v136, v136
	v_fmac_f32_e32 v183, v182, v182
	v_fmac_f32_e32 v141, v140, v140
	v_fmac_f32_e32 v185, v184, v184
	v_fmac_f32_e32 v143, v142, v142
	v_add_f32_e32 v108, v125, v127
	v_add_f32_e32 v109, v139, v137
	v_add_f32_e32 v110, v183, v141
	v_add_f32_e32 v111, v185, v143
	v_add_f32_e32 v108, v108, v109
	v_add_f32_e32 v109, v110, v111
	v_mul_f32_e32 v190, v113, v113
	v_mul_f32_e32 v191, v115, v115
	v_mul_f32_e32 v192, v131, v131
	v_mul_f32_e32 v193, v129, v129
	v_add_f32_e32 v108, v108, v109
	v_fmac_f32_e32 v190, v112, v112
	v_fmac_f32_e32 v191, v114, v114
	v_fmac_f32_e32 v192, v130, v130
	v_fmac_f32_e32 v193, v128, v128
	ds_bpermute_b32 v109, v180, v108
	v_add_f32_e32 v112, v190, v191
	v_add_f32_e32 v110, v192, v193
	v_add_f32_e32 v127, v112, v110
	v_mul_f32_e32 v195, v187, v187
	v_mul_f32_e32 v196, v133, v133
	v_mul_f32_e32 v197, v189, v189
	v_fmac_f32_e32 v195, v186, v186
	v_fmac_f32_e32 v196, v132, v132
	v_fmac_f32_e32 v197, v188, v188
	v_add_f32_e32 v126, v195, v196
	global_store_dwordx4 v[170:171], v[96:99], off offset:256 sc1
	s_waitcnt vmcnt(6)
; __device__ __forceinline__ unsigned cvt_pk_bf16(float lo, float hi) { unsigned r; asm volatile("v_cvt_pk_bf16_f32 %0, %1, %2" : "=v"(r) : "v"(lo), "v"(hi)); return r; }
; template <bool RD32>
; __device__ __forceinline__ void res_rows(const float* __restrict__ xold32, const bf16_t* __restrict__ xoldb, bf16_t* __restrict__ xb, float* __restrict__ ssq, const f32x4 (&acc)[2][2][4][2], int row0, int col0, int slot) {
;     ...
;     for (int bj = 0; bj < 2; ++bj) ld((size_t)row0 * D + col0 + bj * HALF, xo[0][bj][0], xo[0][bj][1]);
; #pragma unroll
;     for (int idx = 0; idx < 8; ++idx) {
;         const int ai = idx >> 2, m = idx & 3; const int r = row0 + ai * HALF + m * 16; const size_t off = (size_t)r * D + col0;
;         if (idx < 7) { const int ai2 = (idx + 1) >> 2, m2 = (idx + 1) & 3; const size_t off2 = (size_t)(row0 + ai2 * HALF + m2 * 16) * D + col0;
; #pragma unroll
;             for (int bj = 0; bj < 2; ++bj) ld(off2 + bj * HALF, xo[(idx + 1) & 1][bj][0], xo[(idx + 1) & 1][bj][1]); }
;         float ss = 0.f;
; #pragma unroll
;         for (int bj = 0; bj < 2; ++bj) { const f32x4 x0 = xo[idx & 1][bj][0] + acc[ai][bj][m][0], x1 = xo[idx & 1][bj][1] + acc[ai][bj][m][1];
;             u32x4 w; w.x = cvt_pk_bf16(x0[0], x0[1]); w.y = cvt_pk_bf16(x0[2], x0[3]); w.z = cvt_pk_bf16(x1[0], x1[1]); w.w = cvt_pk_bf16(x1[2], x1[3]);
;             *(u32x4*)(xb + off + bj * HALF) = w;
;             ss += ((x0[0] * x0[0] + x0[1] * x0[1]) + (x0[2] * x0[2] + x0[3] * x0[3])) + ((x1[0] * x1[0] + x1[1] * x1[1]) + (x1[2] * x1[2] + x1[3] * x1[3])); }
;         ss += __shfl_xor(ss, 16); ss += __shfl_xor(ss, 32);
;         ssv[idx] = ss;
;     }
	v_lshlrev_b32_e32 v110, 16, v118
	v_and_b32_e32 v111, 0xffff0000, v118
	v_lshlrev_b32_e32 v112, 16, v119
	v_and_b32_e32 v113, 0xffff0000, v119
	s_waitcnt vmcnt(5)
	v_lshlrev_b32_e32 v118, 16, v122
	v_and_b32_e32 v119, 0xffff0000, v122
	v_pk_add_f32 v[118:119], v[80:81], v[118:119]
	v_mul_f32_e32 v80, v135, v135
	v_fmac_f32_e32 v80, v134, v134
	s_waitcnt lgkmcnt(0)
	v_add_f32_e32 v96, v108, v109
	v_lshlrev_b32_e32 v98, 16, v116
	v_and_b32_e32 v99, 0xffff0000, v116
	v_lshlrev_b32_e32 v108, 16, v117
	v_and_b32_e32 v109, 0xffff0000, v117
	v_lshlrev_b32_e32 v114, 16, v120
	v_and_b32_e32 v115, 0xffff0000, v120
	v_lshlrev_b32_e32 v116, 16, v121
	v_and_b32_e32 v117, 0xffff0000, v121
	v_lshlrev_b32_e32 v120, 16, v123
	v_and_b32_e32 v121, 0xffff0000, v123
	v_add_f32_e32 v80, v197, v80
	v_pk_add_f32 v[120:121], v[82:83], v[120:121]
	v_add_co_u32_e32 v82, vcc, s14, v166
	v_add_f32_e32 v80, v126, v80
	s_mov_b64 s[14:15], 0x40000
	v_pk_add_f32 v[122:123], v[94:95], v[108:109]
	v_pk_add_f32 v[98:99], v[92:93], v[98:99]
	v_pk_add_f32 v[90:91], v[90:91], v[112:113]
	v_pk_add_f32 v[88:89], v[88:89], v[110:111]
	v_cvt_pk_bf16_f32 v92, v98, v99
	v_cvt_pk_bf16_f32 v93, v122, v123
	v_pk_add_f32 v[124:125], v[84:85], v[114:115]
	v_cvt_pk_bf16_f32 v94, v88, v89
	v_cvt_pk_bf16_f32 v95, v90, v91
	v_addc_co_u32_e32 v83, vcc, 0, v167, vcc
	v_add_f32_e32 v84, v127, v80
	v_lshl_add_u64 v[80:81], v[166:167], 0, s[14:15]
	global_store_dwordx4 v[172:173], v[92:95], off sc1
	v_pk_add_f32 v[116:117], v[86:87], v[116:117]
	v_mul_f32_e32 v97, v99, v99
	v_cvt_pk_bf16_f32 v92, v124, v125
	v_cvt_pk_bf16_f32 v93, v116, v117
	v_cvt_pk_bf16_f32 v94, v118, v119
	v_cvt_pk_bf16_f32 v95, v120, v121
	global_load_dwordx4 v[108:111], v[82:83], off
	global_load_dwordx4 v[112:115], v[80:81], off offset:256
	s_waitcnt vmcnt(4)
	v_lshlrev_b32_e32 v132, 16, v106
	v_and_b32_e32 v133, 0xffff0000, v106
	v_fmac_f32_e32 v97, v98, v98
	v_mul_f32_e32 v98, v123, v123
	v_fmac_f32_e32 v98, v122, v122
	v_mul_f32_e32 v89, v89, v89
	v_pk_add_f32 v[122:123], v[64:65], v[132:133]
	v_mul_f32_e32 v64, v91, v91
	v_cmp_lt_i32_e32 vcc, v181, v194
	v_lshlrev_b32_e32 v106, 16, v107
	v_and_b32_e32 v107, 0xffff0000, v107
	s_mov_b32 s14, 0x48000
	v_fmac_f32_e32 v89, v88, v88
	v_fmac_f32_e32 v64, v90, v90
	v_cndmask_b32_e32 v85, v209, v181, vcc
	v_lshlrev_b32_e32 v126, 16, v100
	v_and_b32_e32 v127, 0xffff0000, v100
	v_lshlrev_b32_e32 v100, 16, v101
	v_and_b32_e32 v101, 0xffff0000, v101
	v_lshlrev_b32_e32 v128, 16, v102
	v_and_b32_e32 v129, 0xffff0000, v102
	v_lshlrev_b32_e32 v102, 16, v103
	v_and_b32_e32 v103, 0xffff0000, v103
	v_add_f32_e32 v97, v97, v98
	v_pk_add_f32 v[106:107], v[66:67], v[106:107]
	v_add_co_u32_e32 v66, vcc, s14, v166
	v_add_f32_e32 v64, v89, v64
	s_mov_b64 s[14:15], 0x48000
	v_lshlrev_b32_e32 v130, 16, v104
	v_and_b32_e32 v131, 0xffff0000, v104
	v_lshlrev_b32_e32 v104, 16, v105
	v_and_b32_e32 v105, 0xffff0000, v105
	global_store_dwordx4 v[172:173], v[92:95], off offset:256 sc1
	v_pk_add_f32 v[98:99], v[74:75], v[102:103]
	v_addc_co_u32_e32 v67, vcc, 0, v167, vcc
	v_pk_add_f32 v[92:93], v[78:79], v[100:101]
	v_pk_add_f32 v[94:95], v[76:77], v[126:127]
	v_pk_add_f32 v[100:101], v[72:73], v[128:129]
	v_cvt_pk_bf16_f32 v72, v94, v95
	v_cvt_pk_bf16_f32 v73, v92, v93
	v_add_f32_e32 v88, v97, v64
	v_cvt_pk_bf16_f32 v74, v100, v101
	v_cvt_pk_bf16_f32 v75, v98, v99
	v_lshl_add_u64 v[64:65], v[166:167], 0, s[14:15]
	global_store_dwordx4 v[168:169], v[72:75], off sc1
	v_pk_add_f32 v[102:103], v[70:71], v[104:105]
	v_pk_add_f32 v[104:105], v[68:69], v[130:131]
	v_mul_f32_e32 v89, v125, v125
	v_cvt_pk_bf16_f32 v68, v104, v105
	v_cvt_pk_bf16_f32 v69, v102, v103
	v_cvt_pk_bf16_f32 v70, v122, v123
	v_cvt_pk_bf16_f32 v71, v106, v107
	global_load_dwordx4 v[72:75], v[66:67], off
	global_load_dwordx4 v[76:79], v[64:65], off offset:256
	v_mul_f32_e32 v90, v117, v117
	v_fmac_f32_e32 v89, v124, v124
	v_fmac_f32_e32 v90, v116, v116
	v_add_f32_e32 v89, v89, v90
	v_mul_f32_e32 v90, v119, v119
	v_mul_f32_e32 v91, v121, v121
	v_mul_f32_e32 v95, v95, v95
	v_mul_f32_e32 v93, v93, v93
	v_fmac_f32_e32 v90, v118, v118
	v_fmac_f32_e32 v91, v120, v120
	v_fmac_f32_e32 v95, v94, v94
	v_fmac_f32_e32 v93, v92, v92
	v_add_f32_e32 v90, v90, v91
	v_add_f32_e32 v92, v95, v93
	v_mul_f32_e32 v93, v101, v101
	v_mul_f32_e32 v94, v99, v99
	v_add_f32_e32 v89, v89, v90
	v_fmac_f32_e32 v93, v100, v100
	v_fmac_f32_e32 v94, v98, v98
	global_store_dwordx4 v[168:169], v[68:71], off offset:256 sc1
	s_mov_b32 s14, 0x50000
	v_add_f32_e32 v97, v88, v89
	v_mul_f32_e32 v68, v105, v105
	s_waitcnt vmcnt(5)
	v_lshlrev_b32_e32 v118, 16, v114
	v_and_b32_e32 v119, 0xffff0000, v114
	v_lshlrev_b32_e32 v114, 16, v115
	v_and_b32_e32 v115, 0xffff0000, v115
	v_mul_f32_e32 v69, v103, v103
	v_lshlrev_b32_e32 v88, 16, v108
	v_and_b32_e32 v89, 0xffff0000, v108
	v_lshlrev_b32_e32 v90, 16, v109
	v_and_b32_e32 v91, 0xffff0000, v109
	v_lshlrev_b32_e32 v108, 16, v110
	v_and_b32_e32 v109, 0xffff0000, v110
	v_lshlrev_b32_e32 v110, 16, v111
	v_and_b32_e32 v111, 0xffff0000, v111
	v_add_f32_e32 v93, v93, v94
	v_fmac_f32_e32 v68, v104, v104
	v_fmac_f32_e32 v69, v102, v102
	v_pk_add_f32 v[94:95], v[50:51], v[114:115]
	v_add_co_u32_e32 v50, vcc, s14, v166
	v_lshlrev_b32_e32 v116, 16, v112
	v_and_b32_e32 v117, 0xffff0000, v112
	v_lshlrev_b32_e32 v112, 16, v113
	v_and_b32_e32 v113, 0xffff0000, v113
	v_add_f32_e32 v124, v68, v69
	v_pk_add_f32 v[62:63], v[62:63], v[90:91]
	v_pk_add_f32 v[60:61], v[60:61], v[88:89]
	v_pk_add_f32 v[58:59], v[58:59], v[110:111]
	v_pk_add_f32 v[56:57], v[56:57], v[108:109]
	v_cvt_pk_bf16_f32 v68, v60, v61
	v_cvt_pk_bf16_f32 v69, v62, v63
	v_addc_co_u32_e32 v51, vcc, 0, v167, vcc
	v_cvt_pk_bf16_f32 v70, v56, v57
	v_cvt_pk_bf16_f32 v71, v58, v59
	v_add_f32_e32 v121, v92, v93
	global_store_dwordx4 v[82:83], v[68:71], off sc1
	v_pk_add_f32 v[82:83], v[54:55], v[112:113]
	v_pk_add_f32 v[92:93], v[52:53], v[116:117]
	v_pk_add_f32 v[98:99], v[48:49], v[118:119]
	v_cvt_pk_bf16_f32 v52, v92, v93
	v_cvt_pk_bf16_f32 v53, v82, v83
	s_mov_b64 s[14:15], 0x50000
	v_cvt_pk_bf16_f32 v54, v98, v99
	v_cvt_pk_bf16_f32 v55, v94, v95
	global_load_dwordx4 v[68:71], v[50:51], off
	v_lshl_add_u64 v[48:49], v[166:167], 0, s[14:15]
	global_load_dwordx4 v[88:91], v[48:49], off offset:256
	s_mov_b32 s14, 0x58000
	v_mul_f32_e32 v108, v107, v107
	v_fmac_f32_e32 v108, v106, v106
	global_store_dwordx4 v[80:81], v[52:55], off offset:256 sc1
	v_mul_f32_e32 v123, v123, v123
	v_fmac_f32_e32 v123, v122, v122
	ds_bpermute_b32 v86, v180, v84
	ds_bpermute_b32 v120, v180, v97
	s_waitcnt vmcnt(6)
; __device__ __forceinline__ unsigned cvt_pk_bf16(float lo, float hi) { unsigned r; asm volatile("v_cvt_pk_bf16_f32 %0, %1, %2" : "=v"(r) : "v"(lo), "v"(hi)); return r; }
; template <bool RD32>
; __device__ __forceinline__ void res_rows(const float* __restrict__ xold32, const bf16_t* __restrict__ xoldb, bf16_t* __restrict__ xb, float* __restrict__ ssq, const f32x4 (&acc)[2][2][4][2], int row0, int col0, int slot) {
;     ...
;     for (int bj = 0; bj < 2; ++bj) ld((size_t)row0 * D + col0 + bj * HALF, xo[0][bj][0], xo[0][bj][1]);
; #pragma unroll
;     for (int idx = 0; idx < 8; ++idx) {
;         const int ai = idx >> 2, m = idx & 3; const int r = row0 + ai * HALF + m * 16; const size_t off = (size_t)r * D + col0;
;         if (idx < 7) { const int ai2 = (idx + 1) >> 2, m2 = (idx + 1) & 3; const size_t off2 = (size_t)(row0 + ai2 * HALF + m2 * 16) * D + col0;
; #pragma unroll
;             for (int bj = 0; bj < 2; ++bj) ld(off2 + bj * HALF, xo[(idx + 1) & 1][bj][0], xo[(idx + 1) & 1][bj][1]); }
;         float ss = 0.f;
; #pragma unroll
;         for (int bj = 0; bj < 2; ++bj) { const f32x4 x0 = xo[idx & 1][bj][0] + acc[ai][bj][m][0], x1 = xo[idx & 1][bj][1] + acc[ai][bj][m][1];
;             u32x4 w; w.x = cvt_pk_bf16(x0[0], x0[1]); w.y = cvt_pk_bf16(x0[2], x0[3]); w.z = cvt_pk_bf16(x1[0], x1[1]); w.w = cvt_pk_bf16(x1[2], x1[3]);
;             *(u32x4*)(xb + off + bj * HALF) = w;
;             ss += ((x0[0] * x0[0] + x0[1] * x0[1]) + (x0[2] * x0[2] + x0[3] * x0[3])) + ((x1[0] * x1[0] + x1[1] * x1[1]) + (x1[2] * x1[2] + x1[3] * x1[3])); }
;         ss += __shfl_xor(ss, 16); ss += __shfl_xor(ss, 32);
;         ssv[idx] = ss;
;     }
	v_lshlrev_b32_e32 v100, 16, v72
	s_waitcnt vmcnt(5)
	v_lshlrev_b32_e32 v104, 16, v76
	v_and_b32_e32 v105, 0xffff0000, v76
	v_and_b32_e32 v101, 0xffff0000, v72
	v_lshlrev_b32_e32 v72, 16, v73
	v_and_b32_e32 v73, 0xffff0000, v73
	v_lshlrev_b32_e32 v102, 16, v74
	v_and_b32_e32 v103, 0xffff0000, v74
	v_lshlrev_b32_e32 v74, 16, v75
	v_and_b32_e32 v75, 0xffff0000, v75
	v_pk_add_f32 v[36:37], v[36:37], v[104:105]
	v_add_co_u32_e32 v104, vcc, s14, v166
	v_lshlrev_b32_e32 v76, 16, v77
	v_and_b32_e32 v77, 0xffff0000, v77
	v_lshlrev_b32_e32 v106, 16, v78
	v_and_b32_e32 v107, 0xffff0000, v78
	v_lshlrev_b32_e32 v78, 16, v79
	v_and_b32_e32 v79, 0xffff0000, v79
	v_pk_add_f32 v[46:47], v[46:47], v[72:73]
	v_pk_add_f32 v[80:81], v[44:45], v[100:101]
	v_pk_add_f32 v[100:101], v[42:43], v[74:75]
	v_pk_add_f32 v[102:103], v[40:41], v[102:103]
	v_cvt_pk_bf16_f32 v40, v80, v81
	v_cvt_pk_bf16_f32 v41, v46, v47
	v_addc_co_u32_e32 v105, vcc, 0, v167, vcc
	v_cvt_pk_bf16_f32 v42, v102, v103
	v_cvt_pk_bf16_f32 v43, v100, v101
	global_store_dwordx4 v[66:67], v[40:43], off sc1
	v_pk_add_f32 v[66:67], v[38:39], v[76:77]
	v_pk_add_f32 v[76:77], v[34:35], v[78:79]
	v_pk_add_f32 v[78:79], v[32:33], v[106:107]
	v_cvt_pk_bf16_f32 v42, v36, v37
	v_cvt_pk_bf16_f32 v43, v66, v67
	v_add_f32_e32 v32, v123, v108
	v_cvt_pk_bf16_f32 v44, v78, v79
	v_cvt_pk_bf16_f32 v45, v76, v77
	global_load_dwordx4 v[52:55], v[104:105], off
	v_add_f32_e32 v32, v124, v32
	s_mov_b64 s[14:15], 0x58000
	v_add_f32_e32 v34, v121, v32
	v_lshl_add_u64 v[32:33], v[166:167], 0, s[14:15]
	global_load_dwordx4 v[72:75], v[32:33], off offset:256
	v_mul_f32_e32 v38, v61, v61
	v_mul_f32_e32 v39, v63, v63
	v_mul_f32_e32 v81, v81, v81
	v_mul_f32_e32 v47, v47, v47
	v_fmac_f32_e32 v38, v60, v60
	v_fmac_f32_e32 v39, v62, v62
	v_fmac_f32_e32 v81, v80, v80
	v_fmac_f32_e32 v47, v46, v46
	v_add_f32_e32 v38, v38, v39
	v_mul_f32_e32 v39, v57, v57
	v_mul_f32_e32 v40, v59, v59
	v_add_f32_e32 v46, v81, v47
	v_mul_f32_e32 v47, v103, v103
	v_mul_f32_e32 v80, v101, v101
	v_mul_f32_e32 v37, v37, v37
	v_fmac_f32_e32 v39, v56, v56
	v_fmac_f32_e32 v40, v58, v58
	v_fmac_f32_e32 v47, v102, v102
	v_fmac_f32_e32 v80, v100, v100
	v_fmac_f32_e32 v37, v36, v36
	v_mul_f32_e32 v36, v67, v67
	v_add_f32_e32 v47, v47, v80
	v_fmac_f32_e32 v36, v66, v66
	global_store_dwordx4 v[64:65], v[42:45], off offset:256 sc1
	v_add_f32_e32 v46, v46, v47
	s_waitcnt vmcnt(6)
	v_lshlrev_b32_e32 v56, 16, v68
	v_and_b32_e32 v57, 0xffff0000, v68
	v_lshlrev_b32_e32 v58, 16, v69
	v_and_b32_e32 v59, 0xffff0000, v69
	v_lshlrev_b32_e32 v60, 16, v70
	v_and_b32_e32 v61, 0xffff0000, v70
	v_lshlrev_b32_e32 v62, 16, v71
	v_and_b32_e32 v63, 0xffff0000, v71
	v_pk_add_f32 v[30:31], v[30:31], v[58:59]
	v_pk_add_f32 v[28:29], v[28:29], v[56:57]
	v_pk_add_f32 v[58:59], v[24:25], v[60:61]
	v_cvt_pk_bf16_f32 v24, v28, v29
	v_cvt_pk_bf16_f32 v25, v30, v31
	v_add_f32_e32 v36, v37, v36
	v_mul_f32_e32 v37, v79, v79
	v_mul_f32_e32 v47, v77, v77
	v_pk_add_f32 v[56:57], v[26:27], v[62:63]
	v_cvt_pk_bf16_f32 v26, v58, v59
	v_fmac_f32_e32 v37, v78, v78
	v_cvt_pk_bf16_f32 v27, v56, v57
	global_store_dwordx4 v[50:51], v[24:27], off sc1
	v_fmac_f32_e32 v47, v76, v76
	v_add_f32_e32 v37, v37, v47
	v_mul_f32_e32 v24, v29, v29
	v_mul_f32_e32 v25, v31, v31
	v_fmac_f32_e32 v24, v28, v28
	v_fmac_f32_e32 v25, v30, v30
	v_add_f32_e32 v24, v24, v25
	v_mul_f32_e32 v25, v59, v59
	v_mul_f32_e32 v26, v57, v57
	v_add_f32_e32 v39, v39, v40
	v_mul_f32_e32 v40, v83, v83
	s_waitcnt vmcnt(6)
	v_lshlrev_b32_e32 v68, 16, v88
	v_and_b32_e32 v69, 0xffff0000, v88
	v_add_f32_e32 v36, v36, v37
	v_fmac_f32_e32 v25, v58, v58
	v_fmac_f32_e32 v26, v56, v56
	v_fmac_f32_e32 v40, v82, v82
	v_lshlrev_b32_e32 v70, 16, v89
	v_and_b32_e32 v71, 0xffff0000, v89
	v_lshlrev_b32_e32 v82, 16, v90
	v_add_f32_e32 v36, v46, v36
	v_and_b32_e32 v83, 0xffff0000, v90
	v_lshlrev_b32_e32 v46, 16, v91
	v_and_b32_e32 v47, 0xffff0000, v91
	v_add_f32_e32 v25, v25, v26
	v_pk_add_f32 v[20:21], v[20:21], v[68:69]
	v_add_f32_e32 v26, v24, v25
	v_pk_add_f32 v[22:23], v[22:23], v[70:71]
	v_pk_add_f32 v[24:25], v[18:19], v[46:47]
	v_pk_add_f32 v[18:19], v[16:17], v[82:83]
	v_mul_f32_e32 v17, v21, v21
	v_cvt_pk_bf16_f32 v16, v20, v21
	v_fmac_f32_e32 v17, v20, v20
	v_mul_f32_e32 v20, v23, v23
	v_fmac_f32_e32 v20, v22, v22
	v_add_f32_e32 v17, v17, v20
	v_mul_f32_e32 v20, v19, v19
	v_mul_f32_e32 v21, v25, v25
	v_fmac_f32_e32 v20, v18, v18
	v_fmac_f32_e32 v21, v24, v24
	v_add_f32_e32 v20, v20, v21
	v_add_f32_e32 v17, v17, v20
	v_add_f32_e32 v20, v26, v17
	ds_bpermute_b32 v21, v180, v20
	s_waitcnt vmcnt(3)
; __device__ __forceinline__ unsigned cvt_pk_bf16(float lo, float hi) { unsigned r; asm volatile("v_cvt_pk_bf16_f32 %0, %1, %2" : "=v"(r) : "v"(lo), "v"(hi)); return r; }
; template <bool RD32>
; __device__ __forceinline__ void res_rows(const float* __restrict__ xold32, const bf16_t* __restrict__ xoldb, bf16_t* __restrict__ xb, float* __restrict__ ssq, const f32x4 (&acc)[2][2][4][2], int row0, int col0, int slot) {
;     ...
;     for (int bj = 0; bj < 2; ++bj) ld((size_t)row0 * D + col0 + bj * HALF, xo[0][bj][0], xo[0][bj][1]);
; #pragma unroll
;     for (int idx = 0; idx < 8; ++idx) {
;         const int ai = idx >> 2, m = idx & 3; const int r = row0 + ai * HALF + m * 16; const size_t off = (size_t)r * D + col0;
;         if (idx < 7) { const int ai2 = (idx + 1) >> 2, m2 = (idx + 1) & 3; const size_t off2 = (size_t)(row0 + ai2 * HALF + m2 * 16) * D + col0;
; #pragma unroll
;             for (int bj = 0; bj < 2; ++bj) ld(off2 + bj * HALF, xo[(idx + 1) & 1][bj][0], xo[(idx + 1) & 1][bj][1]); }
;         float ss = 0.f;
; #pragma unroll
;         for (int bj = 0; bj < 2; ++bj) { const f32x4 x0 = xo[idx & 1][bj][0] + acc[ai][bj][m][0], x1 = xo[idx & 1][bj][1] + acc[ai][bj][m][1];
;             u32x4 w; w.x = cvt_pk_bf16(x0[0], x0[1]); w.y = cvt_pk_bf16(x0[2], x0[3]); w.z = cvt_pk_bf16(x1[0], x1[1]); w.w = cvt_pk_bf16(x1[2], x1[3]);
;             *(u32x4*)(xb + off + bj * HALF) = w;
;             ss += ((x0[0] * x0[0] + x0[1] * x0[1]) + (x0[2] * x0[2] + x0[3] * x0[3])) + ((x1[0] * x1[0] + x1[1] * x1[1]) + (x1[2] * x1[2] + x1[3] * x1[3])); }
;         ss += __shfl_xor(ss, 16); ss += __shfl_xor(ss, 32);
;         ssv[idx] = ss;
;     }
;     const int fq = slot >> 6;
; #pragma unroll
;     for (int j = 0; j < 2; ++j) { const float v = fq == 0 ? ssv[j] : fq == 1 ? ssv[2 + j] : fq == 2 ? ssv[4 + j] : ssv[6 + j]; const int idx = 2 * fq + j;
;         ssq[(size_t)(row0 + (idx >> 2) * HALF + (idx & 3) * 16) * 16 + (slot & 15)] = v; }
	v_lshlrev_b32_e32 v42, 16, v52
	v_and_b32_e32 v43, 0xffff0000, v52
	v_lshlrev_b32_e32 v44, 16, v53
	v_and_b32_e32 v45, 0xffff0000, v53
	v_lshlrev_b32_e32 v52, 16, v54
	v_and_b32_e32 v53, 0xffff0000, v54
	v_lshlrev_b32_e32 v54, 16, v55
	v_and_b32_e32 v55, 0xffff0000, v55
	v_cvt_pk_bf16_f32 v17, v22, v23
	v_cvt_pk_bf16_f32 v18, v18, v19
	v_cvt_pk_bf16_f32 v19, v24, v25
	global_store_dwordx4 v[48:49], v[16:19], off offset:256 sc1
	v_pk_add_f32 v[14:15], v[14:15], v[44:45]
	v_pk_add_f32 v[12:13], v[12:13], v[42:43]
	s_waitcnt lgkmcnt(0)
	v_add_f32_e32 v16, v20, v21
	v_pk_add_f32 v[20:21], v[8:9], v[52:53]
	v_cvt_pk_bf16_f32 v8, v12, v13
	v_cvt_pk_bf16_f32 v9, v14, v15
	v_pk_add_f32 v[18:19], v[10:11], v[54:55]
	v_cvt_pk_bf16_f32 v10, v20, v21
	s_waitcnt vmcnt(3)
	v_lshlrev_b32_e32 v64, 16, v72
	v_cvt_pk_bf16_f32 v11, v18, v19
	global_store_dwordx4 v[104:105], v[8:11], off sc1
	v_and_b32_e32 v65, 0xffff0000, v72
	v_lshlrev_b32_e32 v66, 16, v73
	v_mul_f32_e32 v8, v13, v13
	v_mul_f32_e32 v9, v15, v15
	v_fmac_f32_e32 v8, v12, v12
	v_fmac_f32_e32 v9, v14, v14
	v_add_f32_e32 v8, v8, v9
	v_mul_f32_e32 v9, v21, v21
	v_mul_f32_e32 v10, v19, v19
	v_fmac_f32_e32 v9, v20, v20
	v_fmac_f32_e32 v10, v18, v18
	v_and_b32_e32 v67, 0xffff0000, v73
	v_lshlrev_b32_e32 v72, 16, v74
	v_and_b32_e32 v73, 0xffff0000, v74
	v_lshlrev_b32_e32 v74, 16, v75
	v_and_b32_e32 v75, 0xffff0000, v75
	v_add_f32_e32 v9, v9, v10
	v_pk_add_f32 v[4:5], v[4:5], v[64:65]
	v_add_f32_e32 v10, v8, v9
	v_pk_add_f32 v[6:7], v[6:7], v[66:67]
	v_pk_add_f32 v[8:9], v[2:3], v[74:75]
	v_pk_add_f32 v[2:3], v[0:1], v[72:73]
	v_mul_f32_e32 v1, v5, v5
	v_add_f32_e32 v38, v38, v39
	v_mul_f32_e32 v39, v93, v93
	v_cvt_pk_bf16_f32 v0, v4, v5
	v_fmac_f32_e32 v1, v4, v4
	v_mul_f32_e32 v4, v7, v7
	v_fmac_f32_e32 v39, v92, v92
	v_fmac_f32_e32 v4, v6, v6
	v_add_f32_e32 v39, v39, v40
	v_mul_f32_e32 v40, v99, v99
	v_mul_f32_e32 v41, v95, v95
	v_add_f32_e32 v1, v1, v4
	v_mul_f32_e32 v4, v3, v3
	v_mul_f32_e32 v5, v9, v9
	v_fmac_f32_e32 v40, v98, v98
	v_fmac_f32_e32 v41, v94, v94
	v_fmac_f32_e32 v4, v2, v2
	v_fmac_f32_e32 v5, v8, v8
	v_add_f32_e32 v40, v40, v41
	v_add_f32_e32 v4, v4, v5
	v_add_f32_e32 v39, v39, v40
	v_add_f32_e32 v1, v1, v4
	v_add_f32_e32 v40, v38, v39
	v_add_f32_e32 v4, v10, v1
	ds_bpermute_b32 v35, v180, v34
	ds_bpermute_b32 v41, v180, v40
	ds_bpermute_b32 v37, v180, v36
	ds_bpermute_b32 v5, v180, v4
	v_cvt_pk_bf16_f32 v1, v6, v7
	v_cvt_pk_bf16_f32 v2, v2, v3
	v_lshlrev_b32_e32 v87, 2, v85
	v_add_f32_e32 v84, v84, v86
	v_add_f32_e32 v38, v97, v120
	s_waitcnt lgkmcnt(3)
	v_add_f32_e32 v34, v34, v35
	s_waitcnt lgkmcnt(2)
	v_add_f32_e32 v40, v40, v41
	s_waitcnt lgkmcnt(1)
	v_add_f32_e32 v36, v36, v37
	v_cvt_pk_bf16_f32 v3, v8, v9
	global_store_dwordx4 v[32:33], v[0:3], off offset:256 sc1
	ds_bpermute_b32 v85, v87, v96
	ds_bpermute_b32 v86, v87, v84
	s_waitcnt lgkmcnt(2)
	v_add_f32_e32 v2, v4, v5
	ds_bpermute_b32 v39, v87, v38
	ds_bpermute_b32 v35, v87, v34
	ds_bpermute_b32 v41, v87, v40
	ds_bpermute_b32 v37, v87, v36
	ds_bpermute_b32 v17, v87, v16
	ds_bpermute_b32 v3, v87, v2
	s_and_b32 s14, s29, 12
	s_or_b32 s14, s14, s11
	s_lshl_b32 s14, s14, 2
	v_bitop3_b32 v0, s29, v216, v177 bitop3:0xc8
	s_add_u32 s46, s18, s14
	v_cmp_lt_u32_e32 vcc, 63, v179
	v_add_u32_e32 v0, v164, v0
	s_addc_u32 s47, s19, 0
	s_and_saveexec_b64 s[14:15], vcc
	s_xor_b64 s[48:49], exec, s[14:15]
	s_cbranch_execz .LBB0_626
	v_ashrrev_i32_e32 v4, 6, v179
	v_cmp_lt_i32_e32 vcc, 1, v4
	s_mov_b64 s[42:43], 0
	s_and_saveexec_b64 s[14:15], vcc
	s_xor_b64 s[50:51], exec, s[14:15]
	s_cbranch_execnz .LBB0_631
	s_or_saveexec_b64 s[50:51], s[50:51]
	v_cmp_ne_u32_e32 vcc, 1, v4
	s_xor_b64 exec, exec, s[50:51]
	s_cbranch_execnz .LBB0_634
